# P4c plus LDS-DMA loads in GEMM K-loops use SGPR base + 32-bit lane offset (saddr form) where the address temp is single-use
# baseline (speedup 1.0000x reference)
; #define PG8_STAGE(bufoff, gbase, voff) do { _Pragma("unroll") for (int _i = 0; _i < 2; ++_i) \
;         __builtin_amdgcn_global_load_lds((const unsigned*)((const char*)(gbase) + (voff)[_i]), (PG8_LAS unsigned*)(lds + (bufoff) + ldsw + _i * 8192), 16, 0, 0); } while (0)
; #define PG8_LDA(dst, b, h) do { _Pragma("unroll") for (int m = 0; m < 4; ++m) _Pragma("unroll") for (int k = 0; k < 2; ++k) dst[m][k] = *(const PG8_LAS bf16x8*)(lds + PG8_SA(b, h) + aoff + m * 2048 + k * 1024); } while (0)
; #define PG8_LDB(dst, b, h) do { _Pragma("unroll") for (int n = 0; n < 2; ++n) _Pragma("unroll") for (int k = 0; k < 2; ++k) dst[n][k] = *(const PG8_LAS bf16x8*)(lds + PG8_SB(b, h) + boff + n * 2048 + k * 1024); } while (0)
; #define PG8_MMA(ai, bj, At, Bt) do { __builtin_amdgcn_s_setprio(1); _Pragma("unroll") for (int m = 0; m < 4; ++m) _Pragma("unroll") for (int n = 0; n < 2; ++n) _Pragma("unroll") for (int k = 0; k < 2; ++k) \
;         acc[ai][bj][m][n] = __builtin_amdgcn_mfma_f32_16x16x32_bf16(Bt[n][k], At[m][k], acc[ai][bj][m][n], 0, 0, 0); __builtin_amdgcn_s_setprio(0); } while (0)
; #define PG8_WAIT_V(n) asm volatile("s_waitcnt vmcnt(" #n ")" ::: "memory")
; #define PG8_WAIT_L(n) asm volatile("s_waitcnt lgkmcnt(" #n ")" ::: "memory")
; #define PG8_BAR __builtin_amdgcn_s_barrier()
; #define PG8_SCHED __builtin_amdgcn_sched_barrier(0)
; template <class Epi, class Sched, bool ALIGN_EPI = false, bool SP2 = false>
; __device__ __forceinline__ void gemm_phase(PG8_LAS unsigned char* lds, const Gemm g, const Sched& S, const Epi& E, int wave_s_) {
;     ...
;             PG8_LDB(B0, 0, 0); PG8_LDB(B1, 0, 1); PG8_SCHED; PG8_LDA(At, 0, 0); PG8_STAGE(PG8_SA(1, 1), a1 + hstep, voffA);
;             PG8_WAIT_V(8); PG8_WAIT_L(0); PG8_BAR; PG8_MMA(0, 0, At, B0); PG8_MMA(0, 1, At, B1); PG8_BAR; PG8_SCHED;
;             PG8_LDA(At, 0, 1); PG8_STAGE(PG8_SB(0, 0), b2, voffB); PG8_STAGE(PG8_SB(0, 1), b2 + hstep, voffB); PG8_STAGE(PG8_SA(0, 0), a2, voffA);
;             PG8_WAIT_V(8); PG8_WAIT_L(0); PG8_BAR; PG8_MMA(1, 0, At, B0); PG8_MMA(1, 1, At, B1); PG8_BAR; PG8_SCHED;
.LBB0_207:
	s_add_u32 s24, s22, 0xfffc0080
	s_addc_u32 s25, s23, -1
	s_add_i32 s50, 0, 0x10000
	s_cmp_eq_u32 s49, 12
	s_cselect_b32 s27, s9, s25
	s_cselect_b32 s26, s8, s24
	s_cselect_b32 s25, s19, s48
	s_cselect_b32 s24, s18, s17
	s_add_i32 s52, 0, 0x14000
	v_add_u32_e32 v152, s50, v138
	v_add_u32_e32 v168, s52, v138
	ds_read_b128 v[140:143], v152
	ds_read_b128 v[144:147], v152 offset:1024
	ds_read_b128 v[148:151], v152 offset:2048
	ds_read_b128 v[152:155], v152 offset:3072
	ds_read_b128 v[156:159], v168
	ds_read_b128 v[160:163], v168 offset:1024
	ds_read_b128 v[164:167], v168 offset:2048
	ds_read_b128 v[168:171], v168 offset:3072
	s_add_i32 m0, s35, 0xc000
	ds_read_b128 v[172:175], v139
	ds_read_b128 v[176:179], v139 offset:1024
	ds_read_b128 v[180:183], v139 offset:2048
	ds_read_b128 v[184:187], v139 offset:3072
	ds_read_b128 v[188:191], v139 offset:4096
	ds_read_b128 v[192:195], v139 offset:5120
	ds_read_b128 v[206:209], v139 offset:6144
	ds_read_b128 v[210:213], v139 offset:7168
	global_load_lds_dwordx4 v136, s[22:23]
	s_add_i32 m0, s35, 0xe000
	s_nop 0
	global_load_lds_dwordx4 v134, s[22:23]
	s_waitcnt vmcnt(8)
	s_waitcnt lgkmcnt(0)
	s_barrier
	s_setprio 1
	s_waitcnt lgkmcnt(0)
	v_mfma_f32_16x16x32_bf16 v[124:127], v[140:143], v[172:175], v[124:127]
	v_mfma_f32_16x16x32_bf16 v[116:119], v[148:151], v[172:175], v[116:119]
	v_mfma_f32_16x16x32_bf16 v[108:111], v[140:143], v[180:183], v[108:111]
	v_mfma_f32_16x16x32_bf16 v[100:103], v[148:151], v[180:183], v[100:103]
	v_mfma_f32_16x16x32_bf16 v[92:95], v[140:143], v[188:191], v[92:95]
	v_mfma_f32_16x16x32_bf16 v[84:87], v[148:151], v[188:191], v[84:87]
	v_mfma_f32_16x16x32_bf16 v[76:79], v[140:143], v[206:209], v[76:79]
	v_mfma_f32_16x16x32_bf16 v[68:71], v[148:151], v[206:209], v[68:71]
	v_mfma_f32_16x16x32_bf16 v[124:127], v[144:147], v[176:179], v[124:127]
	v_mfma_f32_16x16x32_bf16 v[116:119], v[152:155], v[176:179], v[116:119]
	v_mfma_f32_16x16x32_bf16 v[108:111], v[144:147], v[184:187], v[108:111]
	v_mfma_f32_16x16x32_bf16 v[100:103], v[152:155], v[184:187], v[100:103]
	v_mfma_f32_16x16x32_bf16 v[92:95], v[144:147], v[192:195], v[92:95]
	v_mfma_f32_16x16x32_bf16 v[84:87], v[152:155], v[192:195], v[84:87]
	v_mfma_f32_16x16x32_bf16 v[76:79], v[144:147], v[210:213], v[76:79]
	v_mfma_f32_16x16x32_bf16 v[68:71], v[152:155], v[210:213], v[68:71]
	s_setprio 0
	s_setprio 1
	v_mfma_f32_16x16x32_bf16 v[120:123], v[156:159], v[172:175], v[120:123]
	v_mfma_f32_16x16x32_bf16 v[112:115], v[164:167], v[172:175], v[112:115]
	v_mfma_f32_16x16x32_bf16 v[104:107], v[156:159], v[180:183], v[104:107]
	v_mfma_f32_16x16x32_bf16 v[96:99], v[164:167], v[180:183], v[96:99]
	v_mfma_f32_16x16x32_bf16 v[88:91], v[156:159], v[188:191], v[88:91]
	v_mfma_f32_16x16x32_bf16 v[80:83], v[164:167], v[188:191], v[80:83]
	v_mfma_f32_16x16x32_bf16 v[72:75], v[156:159], v[206:209], v[72:75]
	v_mfma_f32_16x16x32_bf16 v[64:67], v[164:167], v[206:209], v[64:67]
	v_mfma_f32_16x16x32_bf16 v[120:123], v[160:163], v[176:179], v[120:123]
	v_mfma_f32_16x16x32_bf16 v[112:115], v[168:171], v[176:179], v[112:115]
	v_mfma_f32_16x16x32_bf16 v[104:107], v[160:163], v[184:187], v[104:107]
	v_mfma_f32_16x16x32_bf16 v[96:99], v[168:171], v[184:187], v[96:99]
	v_mfma_f32_16x16x32_bf16 v[88:91], v[160:163], v[192:195], v[88:91]
	v_mfma_f32_16x16x32_bf16 v[80:83], v[168:171], v[192:195], v[80:83]
	v_mfma_f32_16x16x32_bf16 v[72:75], v[160:163], v[210:213], v[72:75]
	v_mfma_f32_16x16x32_bf16 v[64:67], v[168:171], v[210:213], v[64:67]
	s_setprio 0
	s_barrier
	s_add_i32 s50, s50, s34
	v_lshl_add_u64 v[214:215], s[24:25], 0, v[196:197]
	s_mov_b32 m0, s50
	ds_read_b128 v[172:175], v139 offset:16384
	ds_read_b128 v[176:179], v139 offset:17408
	ds_read_b128 v[180:183], v139 offset:18432
	ds_read_b128 v[184:187], v139 offset:19456
	ds_read_b128 v[188:191], v139 offset:20480
	ds_read_b128 v[192:195], v139 offset:21504
	ds_read_b128 v[206:209], v139 offset:22528
	ds_read_b128 v[210:213], v139 offset:23552
	global_load_lds_dwordx4 v[214:215], off
	s_add_i32 m0, s50, 0x2000
	s_add_u32 s50, s24, 0x40000
	v_lshl_add_u64 v[216:217], s[24:25], 0, v[132:133]
	s_addc_u32 s51, s25, 0
	s_add_i32 s52, s52, s34
	global_load_lds_dwordx4 v[216:217], off
	s_mov_b32 m0, s52
	v_lshl_add_u64 v[220:221], s[26:27], 0, v[130:131]
	global_load_lds_dwordx4 v196, s[50:51]
	s_add_i32 m0, s52, 0x2000
	s_nop 0
	global_load_lds_dwordx4 v132, s[50:51]
	v_lshl_add_u64 v[218:219], s[26:27], 0, v[128:129]
	s_mov_b32 m0, s35
	s_nop 0
	global_load_lds_dwordx4 v[218:219], off
	s_mov_b32 m0, s36
	s_nop 0
	global_load_lds_dwordx4 v[220:221], off
	s_waitcnt vmcnt(8)
	s_waitcnt lgkmcnt(0)
	s_barrier
; #define PG8_STAGE(bufoff, gbase, voff) do { _Pragma("unroll") for (int _i = 0; _i < 2; ++_i) \
;         __builtin_amdgcn_global_load_lds((const unsigned*)((const char*)(gbase) + (voff)[_i]), (PG8_LAS unsigned*)(lds + (bufoff) + ldsw + _i * 8192), 16, 0, 0); } while (0)
; #define PG8_LDA(dst, b, h) do { _Pragma("unroll") for (int m = 0; m < 4; ++m) _Pragma("unroll") for (int k = 0; k < 2; ++k) dst[m][k] = *(const PG8_LAS bf16x8*)(lds + PG8_SA(b, h) + aoff + m * 2048 + k * 1024); } while (0)
; #define PG8_LDB(dst, b, h) do { _Pragma("unroll") for (int n = 0; n < 2; ++n) _Pragma("unroll") for (int k = 0; k < 2; ++k) dst[n][k] = *(const PG8_LAS bf16x8*)(lds + PG8_SB(b, h) + boff + n * 2048 + k * 1024); } while (0)
; #define PG8_MMA(ai, bj, At, Bt) do { __builtin_amdgcn_s_setprio(1); _Pragma("unroll") for (int m = 0; m < 4; ++m) _Pragma("unroll") for (int n = 0; n < 2; ++n) _Pragma("unroll") for (int k = 0; k < 2; ++k) \
;         acc[ai][bj][m][n] = __builtin_amdgcn_mfma_f32_16x16x32_bf16(Bt[n][k], At[m][k], acc[ai][bj][m][n], 0, 0, 0); __builtin_amdgcn_s_setprio(0); } while (0)
; #define PG8_WAIT_V(n) asm volatile("s_waitcnt vmcnt(" #n ")" ::: "memory")
; #define PG8_WAIT_L(n) asm volatile("s_waitcnt lgkmcnt(" #n ")" ::: "memory")
; #define PG8_BAR __builtin_amdgcn_s_barrier()
; #define PG8_SCHED __builtin_amdgcn_sched_barrier(0)
; template <class Epi, class Sched, bool ALIGN_EPI = false, bool SP2 = false>
; __device__ __forceinline__ void gemm_phase(PG8_LAS unsigned char* lds, const Gemm g, const Sched& S, const Epi& E, int wave_s_) {
;     ...
;             PG8_WAIT_V(8); PG8_WAIT_L(0); PG8_BAR; PG8_MMA(1, 0, At, B0); PG8_MMA(1, 1, At, B1); PG8_BAR; PG8_SCHED;
;             PG8_LDB(B0, 1, 0); PG8_LDB(B1, 1, 1); PG8_SCHED; PG8_LDA(At, 1, 0); PG8_STAGE(PG8_SA(0, 1), a2 + hstep, voffA);
;             PG8_WAIT_V(8); PG8_WAIT_L(0); PG8_BAR; PG8_MMA(0, 0, At, B0); PG8_MMA(0, 1, At, B1); PG8_BAR; PG8_SCHED;
	s_setprio 1
	s_waitcnt lgkmcnt(0)
	v_mfma_f32_16x16x32_bf16 v[60:63], v[140:143], v[172:175], v[60:63]
	v_mfma_f32_16x16x32_bf16 v[52:55], v[148:151], v[172:175], v[52:55]
	v_mfma_f32_16x16x32_bf16 v[44:47], v[140:143], v[180:183], v[44:47]
	v_mfma_f32_16x16x32_bf16 v[36:39], v[148:151], v[180:183], v[36:39]
	v_mfma_f32_16x16x32_bf16 v[28:31], v[140:143], v[188:191], v[28:31]
	v_mfma_f32_16x16x32_bf16 v[20:23], v[148:151], v[188:191], v[20:23]
	v_mfma_f32_16x16x32_bf16 v[12:15], v[140:143], v[206:209], v[12:15]
	v_mfma_f32_16x16x32_bf16 v[4:7], v[148:151], v[206:209], v[4:7]
	v_mfma_f32_16x16x32_bf16 v[60:63], v[144:147], v[176:179], v[60:63]
	v_mfma_f32_16x16x32_bf16 v[52:55], v[152:155], v[176:179], v[52:55]
	v_mfma_f32_16x16x32_bf16 v[44:47], v[144:147], v[184:187], v[44:47]
	v_mfma_f32_16x16x32_bf16 v[36:39], v[152:155], v[184:187], v[36:39]
	v_mfma_f32_16x16x32_bf16 v[28:31], v[144:147], v[192:195], v[28:31]
	v_mfma_f32_16x16x32_bf16 v[20:23], v[152:155], v[192:195], v[20:23]
	v_mfma_f32_16x16x32_bf16 v[12:15], v[144:147], v[210:213], v[12:15]
	v_mfma_f32_16x16x32_bf16 v[4:7], v[152:155], v[210:213], v[4:7]
	s_setprio 0
	s_setprio 1
	v_mfma_f32_16x16x32_bf16 v[56:59], v[156:159], v[172:175], v[56:59]
	v_mfma_f32_16x16x32_bf16 v[48:51], v[164:167], v[172:175], v[48:51]
	v_mfma_f32_16x16x32_bf16 v[40:43], v[156:159], v[180:183], v[40:43]
	v_mfma_f32_16x16x32_bf16 v[32:35], v[164:167], v[180:183], v[32:35]
	v_mfma_f32_16x16x32_bf16 v[24:27], v[156:159], v[188:191], v[24:27]
	v_mfma_f32_16x16x32_bf16 v[16:19], v[164:167], v[188:191], v[16:19]
	v_mfma_f32_16x16x32_bf16 v[8:11], v[156:159], v[206:209], v[8:11]
	v_mfma_f32_16x16x32_bf16 v[0:3], v[164:167], v[206:209], v[0:3]
	v_mfma_f32_16x16x32_bf16 v[56:59], v[160:163], v[176:179], v[56:59]
	v_mfma_f32_16x16x32_bf16 v[48:51], v[168:171], v[176:179], v[48:51]
	v_mfma_f32_16x16x32_bf16 v[40:43], v[160:163], v[184:187], v[40:43]
	v_mfma_f32_16x16x32_bf16 v[32:35], v[168:171], v[184:187], v[32:35]
	v_mfma_f32_16x16x32_bf16 v[24:27], v[160:163], v[192:195], v[24:27]
	v_mfma_f32_16x16x32_bf16 v[16:19], v[168:171], v[192:195], v[16:19]
	v_mfma_f32_16x16x32_bf16 v[8:11], v[160:163], v[210:213], v[8:11]
	v_mfma_f32_16x16x32_bf16 v[0:3], v[168:171], v[210:213], v[0:3]
	s_setprio 0
	s_barrier
	s_add_i32 s50, 0, 0x18000
	s_add_i32 s51, 0, 0x1c000
	v_add_u32_e32 v152, s50, v138
	v_add_u32_e32 v168, s51, v138
	ds_read_b128 v[140:143], v152
	ds_read_b128 v[144:147], v152 offset:1024
	ds_read_b128 v[148:151], v152 offset:2048
	ds_read_b128 v[152:155], v152 offset:3072
	ds_read_b128 v[156:159], v168
	ds_read_b128 v[160:163], v168 offset:1024
	ds_read_b128 v[164:167], v168 offset:2048
	ds_read_b128 v[168:171], v168 offset:3072
	s_add_u32 s26, s26, 0x40000
	s_addc_u32 s27, s27, 0
	s_mov_b32 m0, s37
	ds_read_b128 v[172:175], v139 offset:32768
	ds_read_b128 v[176:179], v139 offset:33792
	ds_read_b128 v[180:183], v139 offset:34816
	ds_read_b128 v[184:187], v139 offset:35840
	ds_read_b128 v[188:191], v139 offset:36864
	ds_read_b128 v[192:195], v139 offset:37888
	ds_read_b128 v[206:209], v139 offset:38912
	ds_read_b128 v[210:213], v139 offset:39936
	global_load_lds_dwordx4 v128, s[26:27]
	s_mov_b32 m0, s38
	s_nop 0
	global_load_lds_dwordx4 v130, s[26:27]
	s_waitcnt vmcnt(8)
	s_waitcnt lgkmcnt(0)
	s_barrier
	s_setprio 1
	s_waitcnt lgkmcnt(0)
	v_mfma_f32_16x16x32_bf16 v[124:127], v[140:143], v[172:175], v[124:127]
	v_mfma_f32_16x16x32_bf16 v[116:119], v[148:151], v[172:175], v[116:119]
	v_mfma_f32_16x16x32_bf16 v[108:111], v[140:143], v[180:183], v[108:111]
	v_mfma_f32_16x16x32_bf16 v[100:103], v[148:151], v[180:183], v[100:103]
	v_mfma_f32_16x16x32_bf16 v[92:95], v[140:143], v[188:191], v[92:95]
	v_mfma_f32_16x16x32_bf16 v[84:87], v[148:151], v[188:191], v[84:87]
	v_mfma_f32_16x16x32_bf16 v[76:79], v[140:143], v[206:209], v[76:79]
	v_mfma_f32_16x16x32_bf16 v[68:71], v[148:151], v[206:209], v[68:71]
	v_mfma_f32_16x16x32_bf16 v[124:127], v[144:147], v[176:179], v[124:127]
	v_mfma_f32_16x16x32_bf16 v[116:119], v[152:155], v[176:179], v[116:119]
	v_mfma_f32_16x16x32_bf16 v[108:111], v[144:147], v[184:187], v[108:111]
	v_mfma_f32_16x16x32_bf16 v[100:103], v[152:155], v[184:187], v[100:103]
	v_mfma_f32_16x16x32_bf16 v[92:95], v[144:147], v[192:195], v[92:95]
	v_mfma_f32_16x16x32_bf16 v[84:87], v[152:155], v[192:195], v[84:87]
	v_mfma_f32_16x16x32_bf16 v[76:79], v[144:147], v[210:213], v[76:79]
	v_mfma_f32_16x16x32_bf16 v[68:71], v[152:155], v[210:213], v[68:71]
	s_setprio 0
	s_setprio 1
	v_mfma_f32_16x16x32_bf16 v[120:123], v[156:159], v[172:175], v[120:123]
	v_mfma_f32_16x16x32_bf16 v[112:115], v[164:167], v[172:175], v[112:115]
	v_mfma_f32_16x16x32_bf16 v[104:107], v[156:159], v[180:183], v[104:107]
	v_mfma_f32_16x16x32_bf16 v[96:99], v[164:167], v[180:183], v[96:99]
	v_mfma_f32_16x16x32_bf16 v[88:91], v[156:159], v[188:191], v[88:91]
	v_mfma_f32_16x16x32_bf16 v[80:83], v[164:167], v[188:191], v[80:83]
	v_mfma_f32_16x16x32_bf16 v[72:75], v[156:159], v[206:209], v[72:75]
	v_mfma_f32_16x16x32_bf16 v[64:67], v[164:167], v[206:209], v[64:67]
	v_mfma_f32_16x16x32_bf16 v[120:123], v[160:163], v[176:179], v[120:123]
	v_mfma_f32_16x16x32_bf16 v[112:115], v[168:171], v[176:179], v[112:115]
	v_mfma_f32_16x16x32_bf16 v[104:107], v[160:163], v[184:187], v[104:107]
	v_mfma_f32_16x16x32_bf16 v[96:99], v[168:171], v[184:187], v[96:99]
	v_mfma_f32_16x16x32_bf16 v[88:91], v[160:163], v[192:195], v[88:91]
	v_mfma_f32_16x16x32_bf16 v[80:83], v[168:171], v[192:195], v[80:83]
	v_mfma_f32_16x16x32_bf16 v[72:75], v[160:163], v[210:213], v[72:75]
	v_mfma_f32_16x16x32_bf16 v[64:67], v[168:171], v[210:213], v[64:67]
	s_setprio 0
	s_barrier
; #define PG8_STAGE(bufoff, gbase, voff) do { _Pragma("unroll") for (int _i = 0; _i < 2; ++_i) \
;         __builtin_amdgcn_global_load_lds((const unsigned*)((const char*)(gbase) + (voff)[_i]), (PG8_LAS unsigned*)(lds + (bufoff) + ldsw + _i * 8192), 16, 0, 0); } while (0)
; #define PG8_LDA(dst, b, h) do { _Pragma("unroll") for (int m = 0; m < 4; ++m) _Pragma("unroll") for (int k = 0; k < 2; ++k) dst[m][k] = *(const PG8_LAS bf16x8*)(lds + PG8_SA(b, h) + aoff + m * 2048 + k * 1024); } while (0)
; #define PG8_MMA(ai, bj, At, Bt) do { __builtin_amdgcn_s_setprio(1); _Pragma("unroll") for (int m = 0; m < 4; ++m) _Pragma("unroll") for (int n = 0; n < 2; ++n) _Pragma("unroll") for (int k = 0; k < 2; ++k) \
;         acc[ai][bj][m][n] = __builtin_amdgcn_mfma_f32_16x16x32_bf16(Bt[n][k], At[m][k], acc[ai][bj][m][n], 0, 0, 0); __builtin_amdgcn_s_setprio(0); } while (0)
; #define PG8_WAIT_V(n) asm volatile("s_waitcnt vmcnt(" #n ")" ::: "memory")
; #define PG8_WAIT_L(n) asm volatile("s_waitcnt lgkmcnt(" #n ")" ::: "memory")
; #define PG8_BAR __builtin_amdgcn_s_barrier()
; #define PG8_SCHED __builtin_amdgcn_sched_barrier(0)
; template <class Epi, class Sched, bool ALIGN_EPI = false, bool SP2 = false>
; __device__ __forceinline__ void gemm_phase(PG8_LAS unsigned char* lds, const Gemm g, const Sched& S, const Epi& E, int wave_s_) {
;     ...
;             PG8_WAIT_V(8); PG8_WAIT_L(0); PG8_BAR; PG8_MMA(0, 0, At, B0); PG8_MMA(0, 1, At, B1); PG8_BAR; PG8_SCHED;
;             PG8_LDA(At, 1, 1); PG8_STAGE(PG8_SB(1, 0), b3, voffB); PG8_STAGE(PG8_SB(1, 1), b3 + hstep, voffB); PG8_STAGE(PG8_SA(1, 0), a3, voffA);
;             PG8_WAIT_V(8); PG8_WAIT_L(0); PG8_BAR; PG8_MMA(1, 0, At, B0); PG8_MMA(1, 1, At, B1); PG8_BAR; PG8_SCHED;
	s_add_i32 s26, s50, s34
	v_lshl_add_u64 v[214:215], v[214:215], 0, s[76:77]
	s_mov_b32 m0, s26
	ds_read_b128 v[172:175], v139 offset:49152
	ds_read_b128 v[176:179], v139 offset:50176
	ds_read_b128 v[180:183], v139 offset:51200
	ds_read_b128 v[184:187], v139 offset:52224
	ds_read_b128 v[188:191], v139 offset:53248
	ds_read_b128 v[192:195], v139 offset:54272
	ds_read_b128 v[206:209], v139 offset:55296
	ds_read_b128 v[210:213], v139 offset:56320
	global_load_lds_dwordx4 v[214:215], off
	s_add_i32 m0, s26, 0x2000
	s_add_u32 s24, s24, 0x40080
	v_lshl_add_u64 v[214:215], v[216:217], 0, s[76:77]
	s_addc_u32 s25, s25, 0
	s_add_i32 s26, s51, s34
	global_load_lds_dwordx4 v[214:215], off
	s_mov_b32 m0, s26
	s_nop 0
	global_load_lds_dwordx4 v196, s[24:25]
	s_add_i32 m0, s26, 0x2000
	s_nop 0
	global_load_lds_dwordx4 v132, s[24:25]
	v_lshl_add_u64 v[214:215], v[218:219], 0, s[76:77]
	s_mov_b32 m0, s41
	s_nop 0
	global_load_lds_dwordx4 v[214:215], off
	v_lshl_add_u64 v[214:215], v[220:221], 0, s[76:77]
	s_mov_b32 m0, s42
	s_nop 0
	global_load_lds_dwordx4 v[214:215], off
	s_waitcnt vmcnt(8)
	s_waitcnt lgkmcnt(0)
	s_barrier
	s_setprio 1
	s_waitcnt lgkmcnt(0)
	v_mfma_f32_16x16x32_bf16 v[60:63], v[140:143], v[172:175], v[60:63]
	v_mfma_f32_16x16x32_bf16 v[52:55], v[148:151], v[172:175], v[52:55]
	v_mfma_f32_16x16x32_bf16 v[44:47], v[140:143], v[180:183], v[44:47]
	v_mfma_f32_16x16x32_bf16 v[36:39], v[148:151], v[180:183], v[36:39]
	v_mfma_f32_16x16x32_bf16 v[28:31], v[140:143], v[188:191], v[28:31]
	v_mfma_f32_16x16x32_bf16 v[20:23], v[148:151], v[188:191], v[20:23]
	v_mfma_f32_16x16x32_bf16 v[12:15], v[140:143], v[206:209], v[12:15]
	v_mfma_f32_16x16x32_bf16 v[4:7], v[148:151], v[206:209], v[4:7]
	v_mfma_f32_16x16x32_bf16 v[60:63], v[144:147], v[176:179], v[60:63]
	v_mfma_f32_16x16x32_bf16 v[52:55], v[152:155], v[176:179], v[52:55]
	v_mfma_f32_16x16x32_bf16 v[44:47], v[144:147], v[184:187], v[44:47]
	v_mfma_f32_16x16x32_bf16 v[36:39], v[152:155], v[184:187], v[36:39]
	v_mfma_f32_16x16x32_bf16 v[28:31], v[144:147], v[192:195], v[28:31]
	v_mfma_f32_16x16x32_bf16 v[20:23], v[152:155], v[192:195], v[20:23]
	v_mfma_f32_16x16x32_bf16 v[12:15], v[144:147], v[210:213], v[12:15]
	v_mfma_f32_16x16x32_bf16 v[4:7], v[152:155], v[210:213], v[4:7]
	s_setprio 0
	s_setprio 1
	v_mfma_f32_16x16x32_bf16 v[56:59], v[156:159], v[172:175], v[56:59]
	v_mfma_f32_16x16x32_bf16 v[48:51], v[164:167], v[172:175], v[48:51]
	v_mfma_f32_16x16x32_bf16 v[40:43], v[156:159], v[180:183], v[40:43]
	v_mfma_f32_16x16x32_bf16 v[32:35], v[164:167], v[180:183], v[32:35]
	v_mfma_f32_16x16x32_bf16 v[24:27], v[156:159], v[188:191], v[24:27]
	v_mfma_f32_16x16x32_bf16 v[16:19], v[164:167], v[188:191], v[16:19]
	v_mfma_f32_16x16x32_bf16 v[8:11], v[156:159], v[206:209], v[8:11]
	v_mfma_f32_16x16x32_bf16 v[0:3], v[164:167], v[206:209], v[0:3]
	v_mfma_f32_16x16x32_bf16 v[56:59], v[160:163], v[176:179], v[56:59]
	v_mfma_f32_16x16x32_bf16 v[48:51], v[168:171], v[176:179], v[48:51]
	v_mfma_f32_16x16x32_bf16 v[40:43], v[160:163], v[184:187], v[40:43]
	v_mfma_f32_16x16x32_bf16 v[32:35], v[168:171], v[184:187], v[32:35]
	v_mfma_f32_16x16x32_bf16 v[24:27], v[160:163], v[192:195], v[24:27]
	v_mfma_f32_16x16x32_bf16 v[16:19], v[168:171], v[192:195], v[16:19]
	v_mfma_f32_16x16x32_bf16 v[8:11], v[160:163], v[210:213], v[8:11]
	v_mfma_f32_16x16x32_bf16 v[0:3], v[168:171], v[210:213], v[0:3]
	s_setprio 0
	s_barrier
	s_add_i32 s49, s49, 2
	s_add_u32 s17, s17, 0x100
	s_addc_u32 s48, s48, 0
	s_add_u32 s22, s22, 0x100
	s_addc_u32 s23, s23, 0
	s_cmp_gt_u32 s49, 13
	s_cbranch_scc0 .LBB0_207
	s_and_b64 vcc, exec, s[14:15]
	s_cbranch_vccz .LBB0_210
	s_barrier

; #define PG8_STAGE(bufoff, gbase, voff) do { _Pragma("unroll") for (int _i = 0; _i < 2; ++_i) \
;         __builtin_amdgcn_global_load_lds((const unsigned*)((const char*)(gbase) + (voff)[_i]), (PG8_LAS unsigned*)(lds + (bufoff) + ldsw + _i * 8192), 16, 0, 0); } while (0)
; #define PG8_LDA(dst, b, h) do { _Pragma("unroll") for (int m = 0; m < 4; ++m) _Pragma("unroll") for (int k = 0; k < 2; ++k) dst[m][k] = *(const PG8_LAS bf16x8*)(lds + PG8_SA(b, h) + aoff + m * 2048 + k * 1024); } while (0)
; #define PG8_LDB(dst, b, h) do { _Pragma("unroll") for (int n = 0; n < 2; ++n) _Pragma("unroll") for (int k = 0; k < 2; ++k) dst[n][k] = *(const PG8_LAS bf16x8*)(lds + PG8_SB(b, h) + boff + n * 2048 + k * 1024); } while (0)
; #define PG8_MMA(ai, bj, At, Bt) do { __builtin_amdgcn_s_setprio(1); _Pragma("unroll") for (int m = 0; m < 4; ++m) _Pragma("unroll") for (int n = 0; n < 2; ++n) _Pragma("unroll") for (int k = 0; k < 2; ++k) \
;         acc[ai][bj][m][n] = __builtin_amdgcn_mfma_f32_16x16x32_bf16(Bt[n][k], At[m][k], acc[ai][bj][m][n], 0, 0, 0); __builtin_amdgcn_s_setprio(0); } while (0)
; #define PG8_WAIT_V(n) asm volatile("s_waitcnt vmcnt(" #n ")" ::: "memory")
; #define PG8_WAIT_L(n) asm volatile("s_waitcnt lgkmcnt(" #n ")" ::: "memory")
; #define PG8_BAR __builtin_amdgcn_s_barrier()
; #define PG8_SCHED __builtin_amdgcn_sched_barrier(0)
; template <class Epi, class Sched, bool ALIGN_EPI = false, bool SP2 = false>
; __device__ __forceinline__ void gemm_phase(PG8_LAS unsigned char* lds, const Gemm g, const Sched& S, const Epi& E, int wave_s_) {
;     ...
;             PG8_LDB(B0, 0, 0); PG8_LDB(B1, 0, 1); PG8_SCHED; PG8_LDA(At, 0, 0); PG8_STAGE(PG8_SA(1, 1), a1 + hstep, voffA);
;             PG8_WAIT_V(8); PG8_WAIT_L(0); PG8_BAR; PG8_MMA(0, 0, At, B0); PG8_MMA(0, 1, At, B1); PG8_BAR; PG8_SCHED;
;             PG8_LDA(At, 0, 1); PG8_STAGE(PG8_SB(0, 0), b2, voffB); PG8_STAGE(PG8_SB(0, 1), b2 + hstep, voffB); PG8_STAGE(PG8_SA(0, 0), a2, voffA);
;             PG8_WAIT_V(8); PG8_WAIT_L(0); PG8_BAR; PG8_MMA(1, 0, At, B0); PG8_MMA(1, 1, At, B1); PG8_BAR; PG8_SCHED;
.LBB0_298:
	s_add_i32 s63, s34, 2
	s_add_u32 s12, s10, 0x100
	s_addc_u32 s13, s11, 0
	s_add_i32 s64, 0, 0x10000
	s_cmp_eq_u32 s60, s34
	s_cselect_b32 s37, s27, s13
	s_cselect_b32 s36, s26, s12
	s_cselect_b32 s35, s29, s62
	s_cselect_b32 s34, s28, s61
	s_add_i32 s65, 0, 0x14000
	v_add_u32_e32 v80, s64, v226
	v_add_u32_e32 v100, s65, v226
	ds_read_b128 v[64:67], v80
	ds_read_b128 v[68:71], v80 offset:1024
	ds_read_b128 v[76:79], v80 offset:2048
	ds_read_b128 v[80:83], v80 offset:3072
	ds_read_b128 v[88:91], v100
	ds_read_b128 v[92:95], v100 offset:1024
	ds_read_b128 v[96:99], v100 offset:2048
	ds_read_b128 v[100:103], v100 offset:3072
	v_lshl_add_u64 v[208:209], s[10:11], 0, v[206:207]
	s_add_i32 m0, s42, 0xc000
	ds_read_b128 v[160:163], v227
	ds_read_b128 v[164:167], v227 offset:1024
	ds_read_b128 v[168:171], v227 offset:2048
	ds_read_b128 v[172:175], v227 offset:3072
	ds_read_b128 v[176:179], v227 offset:4096
	ds_read_b128 v[180:183], v227 offset:5120
	ds_read_b128 v[184:187], v227 offset:6144
	ds_read_b128 v[188:191], v227 offset:7168
	global_load_lds_dwordx4 v[208:209], off
	v_lshl_add_u64 v[208:209], s[10:11], 0, v[194:195]
	s_add_i32 m0, s42, 0xe000
	s_nop 0
	global_load_lds_dwordx4 v[208:209], off
	s_waitcnt vmcnt(8)
	s_waitcnt lgkmcnt(0)
	s_barrier
	s_setprio 1
	s_waitcnt lgkmcnt(0)
	v_mfma_f32_16x16x32_bf16 v[156:159], v[64:67], v[160:163], v[156:159]
	v_mfma_f32_16x16x32_bf16 v[152:155], v[76:79], v[160:163], v[152:155]
	v_mfma_f32_16x16x32_bf16 v[144:147], v[64:67], v[168:171], v[144:147]
	v_mfma_f32_16x16x32_bf16 v[136:139], v[76:79], v[168:171], v[136:139]
	v_mfma_f32_16x16x32_bf16 v[124:127], v[64:67], v[176:179], v[124:127]
	v_mfma_f32_16x16x32_bf16 v[120:123], v[76:79], v[176:179], v[120:123]
	v_mfma_f32_16x16x32_bf16 v[112:115], v[64:67], v[184:187], v[112:115]
	v_mfma_f32_16x16x32_bf16 v[104:107], v[76:79], v[184:187], v[104:107]
	v_mfma_f32_16x16x32_bf16 v[156:159], v[68:71], v[164:167], v[156:159]
	v_mfma_f32_16x16x32_bf16 v[152:155], v[80:83], v[164:167], v[152:155]
	v_mfma_f32_16x16x32_bf16 v[144:147], v[68:71], v[172:175], v[144:147]
	v_mfma_f32_16x16x32_bf16 v[136:139], v[80:83], v[172:175], v[136:139]
	v_mfma_f32_16x16x32_bf16 v[124:127], v[68:71], v[180:183], v[124:127]
	v_mfma_f32_16x16x32_bf16 v[120:123], v[80:83], v[180:183], v[120:123]
	v_mfma_f32_16x16x32_bf16 v[112:115], v[68:71], v[188:191], v[112:115]
	v_mfma_f32_16x16x32_bf16 v[104:107], v[80:83], v[188:191], v[104:107]
	s_setprio 0
	s_setprio 1
	v_mfma_f32_16x16x32_bf16 v[148:151], v[88:91], v[160:163], v[148:151]
	v_mfma_f32_16x16x32_bf16 v[140:143], v[96:99], v[160:163], v[140:143]
	v_mfma_f32_16x16x32_bf16 v[132:135], v[88:91], v[168:171], v[132:135]
	v_mfma_f32_16x16x32_bf16 v[128:131], v[96:99], v[168:171], v[128:131]
	v_mfma_f32_16x16x32_bf16 v[116:119], v[88:91], v[176:179], v[116:119]
	v_mfma_f32_16x16x32_bf16 v[108:111], v[96:99], v[176:179], v[108:111]
	v_mfma_f32_16x16x32_bf16 v[84:87], v[88:91], v[184:187], v[84:87]
	v_mfma_f32_16x16x32_bf16 v[72:75], v[96:99], v[184:187], v[72:75]
	v_mfma_f32_16x16x32_bf16 v[148:151], v[92:95], v[164:167], v[148:151]
	v_mfma_f32_16x16x32_bf16 v[140:143], v[100:103], v[164:167], v[140:143]
	v_mfma_f32_16x16x32_bf16 v[132:135], v[92:95], v[172:175], v[132:135]
	v_mfma_f32_16x16x32_bf16 v[128:131], v[100:103], v[172:175], v[128:131]
	v_mfma_f32_16x16x32_bf16 v[116:119], v[92:95], v[180:183], v[116:119]
	v_mfma_f32_16x16x32_bf16 v[108:111], v[100:103], v[180:183], v[108:111]
	v_mfma_f32_16x16x32_bf16 v[84:87], v[92:95], v[188:191], v[84:87]
	v_mfma_f32_16x16x32_bf16 v[72:75], v[100:103], v[188:191], v[72:75]
	s_setprio 0
	s_barrier
	s_add_i32 s10, s64, s41
	v_lshl_add_u64 v[208:209], s[34:35], 0, v[196:197]
	s_mov_b32 m0, s10
	ds_read_b128 v[160:163], v227 offset:16384
	ds_read_b128 v[164:167], v227 offset:17408
	ds_read_b128 v[168:171], v227 offset:18432
	ds_read_b128 v[172:175], v227 offset:19456
	ds_read_b128 v[176:179], v227 offset:20480
	ds_read_b128 v[180:183], v227 offset:21504
	ds_read_b128 v[184:187], v227 offset:22528
	ds_read_b128 v[188:191], v227 offset:23552
	global_load_lds_dwordx4 v[208:209], off
	s_add_i32 m0, s10, 0x2000
	s_add_u32 s10, s34, 0xb0000
	v_lshl_add_u64 v[210:211], s[34:35], 0, v[192:193]
	s_addc_u32 s11, s35, 0
	s_add_i32 s64, s65, s41
	global_load_lds_dwordx4 v[210:211], off
	s_mov_b32 m0, s64
	v_lshl_add_u64 v[214:215], s[36:37], 0, v[192:193]
	global_load_lds_dwordx4 v196, s[10:11]
	s_add_i32 m0, s64, 0x2000
	s_nop 0
	global_load_lds_dwordx4 v192, s[10:11]
	v_lshl_add_u64 v[212:213], s[36:37], 0, v[196:197]
	s_mov_b32 m0, s42
	s_nop 0
	global_load_lds_dwordx4 v[212:213], off
	s_mov_b32 m0, s43
	s_nop 0
	global_load_lds_dwordx4 v[214:215], off
	s_waitcnt vmcnt(8)
	s_waitcnt lgkmcnt(0)
	s_barrier
; #define PG8_STAGE(bufoff, gbase, voff) do { _Pragma("unroll") for (int _i = 0; _i < 2; ++_i) \
;         __builtin_amdgcn_global_load_lds((const unsigned*)((const char*)(gbase) + (voff)[_i]), (PG8_LAS unsigned*)(lds + (bufoff) + ldsw + _i * 8192), 16, 0, 0); } while (0)
; #define PG8_LDA(dst, b, h) do { _Pragma("unroll") for (int m = 0; m < 4; ++m) _Pragma("unroll") for (int k = 0; k < 2; ++k) dst[m][k] = *(const PG8_LAS bf16x8*)(lds + PG8_SA(b, h) + aoff + m * 2048 + k * 1024); } while (0)
; #define PG8_LDB(dst, b, h) do { _Pragma("unroll") for (int n = 0; n < 2; ++n) _Pragma("unroll") for (int k = 0; k < 2; ++k) dst[n][k] = *(const PG8_LAS bf16x8*)(lds + PG8_SB(b, h) + boff + n * 2048 + k * 1024); } while (0)
; #define PG8_MMA(ai, bj, At, Bt) do { __builtin_amdgcn_s_setprio(1); _Pragma("unroll") for (int m = 0; m < 4; ++m) _Pragma("unroll") for (int n = 0; n < 2; ++n) _Pragma("unroll") for (int k = 0; k < 2; ++k) \
;         acc[ai][bj][m][n] = __builtin_amdgcn_mfma_f32_16x16x32_bf16(Bt[n][k], At[m][k], acc[ai][bj][m][n], 0, 0, 0); __builtin_amdgcn_s_setprio(0); } while (0)
; #define PG8_WAIT_V(n) asm volatile("s_waitcnt vmcnt(" #n ")" ::: "memory")
; #define PG8_WAIT_L(n) asm volatile("s_waitcnt lgkmcnt(" #n ")" ::: "memory")
; #define PG8_BAR __builtin_amdgcn_s_barrier()
; #define PG8_SCHED __builtin_amdgcn_sched_barrier(0)
; template <class Epi, class Sched, bool ALIGN_EPI = false, bool SP2 = false>
; __device__ __forceinline__ void gemm_phase(PG8_LAS unsigned char* lds, const Gemm g, const Sched& S, const Epi& E, int wave_s_) {
;     ...
;             PG8_WAIT_V(8); PG8_WAIT_L(0); PG8_BAR; PG8_MMA(1, 0, At, B0); PG8_MMA(1, 1, At, B1); PG8_BAR; PG8_SCHED;
;             PG8_LDB(B0, 1, 0); PG8_LDB(B1, 1, 1); PG8_SCHED; PG8_LDA(At, 1, 0); PG8_STAGE(PG8_SA(0, 1), a2 + hstep, voffA);
;             PG8_WAIT_V(8); PG8_WAIT_L(0); PG8_BAR; PG8_MMA(0, 0, At, B0); PG8_MMA(0, 1, At, B1); PG8_BAR; PG8_SCHED;
	s_setprio 1
	s_waitcnt lgkmcnt(0)
	v_mfma_f32_16x16x32_bf16 v[60:63], v[64:67], v[160:163], v[60:63]
	v_mfma_f32_16x16x32_bf16 v[56:59], v[76:79], v[160:163], v[56:59]
	v_mfma_f32_16x16x32_bf16 v[48:51], v[64:67], v[168:171], v[48:51]
	v_mfma_f32_16x16x32_bf16 v[40:43], v[76:79], v[168:171], v[40:43]
	v_mfma_f32_16x16x32_bf16 v[28:31], v[64:67], v[176:179], v[28:31]
	v_mfma_f32_16x16x32_bf16 v[24:27], v[76:79], v[176:179], v[24:27]
	v_mfma_f32_16x16x32_bf16 v[16:19], v[64:67], v[184:187], v[16:19]
	v_mfma_f32_16x16x32_bf16 v[8:11], v[76:79], v[184:187], v[8:11]
	v_mfma_f32_16x16x32_bf16 v[60:63], v[68:71], v[164:167], v[60:63]
	v_mfma_f32_16x16x32_bf16 v[56:59], v[80:83], v[164:167], v[56:59]
	v_mfma_f32_16x16x32_bf16 v[48:51], v[68:71], v[172:175], v[48:51]
	v_mfma_f32_16x16x32_bf16 v[40:43], v[80:83], v[172:175], v[40:43]
	v_mfma_f32_16x16x32_bf16 v[28:31], v[68:71], v[180:183], v[28:31]
	v_mfma_f32_16x16x32_bf16 v[24:27], v[80:83], v[180:183], v[24:27]
	v_mfma_f32_16x16x32_bf16 v[16:19], v[68:71], v[188:191], v[16:19]
	v_mfma_f32_16x16x32_bf16 v[8:11], v[80:83], v[188:191], v[8:11]
	s_setprio 0
	s_setprio 1
	v_mfma_f32_16x16x32_bf16 v[52:55], v[88:91], v[160:163], v[52:55]
	v_mfma_f32_16x16x32_bf16 v[44:47], v[96:99], v[160:163], v[44:47]
	v_mfma_f32_16x16x32_bf16 v[36:39], v[88:91], v[168:171], v[36:39]
	v_mfma_f32_16x16x32_bf16 v[32:35], v[96:99], v[168:171], v[32:35]
	v_mfma_f32_16x16x32_bf16 v[20:23], v[88:91], v[176:179], v[20:23]
	v_mfma_f32_16x16x32_bf16 v[12:15], v[96:99], v[176:179], v[12:15]
	v_mfma_f32_16x16x32_bf16 v[4:7], v[88:91], v[184:187], v[4:7]
	v_mfma_f32_16x16x32_bf16 v[0:3], v[96:99], v[184:187], v[0:3]
	v_mfma_f32_16x16x32_bf16 v[52:55], v[92:95], v[164:167], v[52:55]
	v_mfma_f32_16x16x32_bf16 v[44:47], v[100:103], v[164:167], v[44:47]
	v_mfma_f32_16x16x32_bf16 v[36:39], v[92:95], v[172:175], v[36:39]
	v_mfma_f32_16x16x32_bf16 v[32:35], v[100:103], v[172:175], v[32:35]
	v_mfma_f32_16x16x32_bf16 v[20:23], v[92:95], v[180:183], v[20:23]
	v_mfma_f32_16x16x32_bf16 v[12:15], v[100:103], v[180:183], v[12:15]
	v_mfma_f32_16x16x32_bf16 v[4:7], v[92:95], v[188:191], v[4:7]
	v_mfma_f32_16x16x32_bf16 v[0:3], v[100:103], v[188:191], v[0:3]
	s_setprio 0
	s_barrier
	s_add_i32 s64, 0, 0x18000
	s_add_i32 s65, 0, 0x1c000
	v_add_u32_e32 v80, s64, v226
	v_add_u32_e32 v100, s65, v226
	ds_read_b128 v[64:67], v80
	ds_read_b128 v[68:71], v80 offset:1024
	ds_read_b128 v[76:79], v80 offset:2048
	ds_read_b128 v[80:83], v80 offset:3072
	ds_read_b128 v[88:91], v100
	ds_read_b128 v[92:95], v100 offset:1024
	ds_read_b128 v[96:99], v100 offset:2048
	ds_read_b128 v[100:103], v100 offset:3072
	s_add_u32 s10, s36, 0xb0000
	s_addc_u32 s11, s37, 0
	s_mov_b32 m0, s44
	ds_read_b128 v[160:163], v227 offset:32768
	ds_read_b128 v[164:167], v227 offset:33792
	ds_read_b128 v[168:171], v227 offset:34816
	ds_read_b128 v[172:175], v227 offset:35840
	ds_read_b128 v[176:179], v227 offset:36864
	ds_read_b128 v[180:183], v227 offset:37888
	ds_read_b128 v[184:187], v227 offset:38912
	ds_read_b128 v[188:191], v227 offset:39936
	global_load_lds_dwordx4 v196, s[10:11]
	s_mov_b32 m0, s45
	s_nop 0
	global_load_lds_dwordx4 v192, s[10:11]
	s_waitcnt vmcnt(8)
	s_waitcnt lgkmcnt(0)
	s_barrier
	s_setprio 1
	s_waitcnt lgkmcnt(0)
	v_mfma_f32_16x16x32_bf16 v[156:159], v[64:67], v[160:163], v[156:159]
	v_mfma_f32_16x16x32_bf16 v[152:155], v[76:79], v[160:163], v[152:155]
	v_mfma_f32_16x16x32_bf16 v[144:147], v[64:67], v[168:171], v[144:147]
	v_mfma_f32_16x16x32_bf16 v[136:139], v[76:79], v[168:171], v[136:139]
	v_mfma_f32_16x16x32_bf16 v[124:127], v[64:67], v[176:179], v[124:127]
	v_mfma_f32_16x16x32_bf16 v[120:123], v[76:79], v[176:179], v[120:123]
	v_mfma_f32_16x16x32_bf16 v[112:115], v[64:67], v[184:187], v[112:115]
	v_mfma_f32_16x16x32_bf16 v[104:107], v[76:79], v[184:187], v[104:107]
	v_mfma_f32_16x16x32_bf16 v[156:159], v[68:71], v[164:167], v[156:159]
	v_mfma_f32_16x16x32_bf16 v[152:155], v[80:83], v[164:167], v[152:155]
	v_mfma_f32_16x16x32_bf16 v[144:147], v[68:71], v[172:175], v[144:147]
	v_mfma_f32_16x16x32_bf16 v[136:139], v[80:83], v[172:175], v[136:139]
	v_mfma_f32_16x16x32_bf16 v[124:127], v[68:71], v[180:183], v[124:127]
	v_mfma_f32_16x16x32_bf16 v[120:123], v[80:83], v[180:183], v[120:123]
	v_mfma_f32_16x16x32_bf16 v[112:115], v[68:71], v[188:191], v[112:115]
	v_mfma_f32_16x16x32_bf16 v[104:107], v[80:83], v[188:191], v[104:107]
	s_setprio 0
	s_setprio 1
	v_mfma_f32_16x16x32_bf16 v[148:151], v[88:91], v[160:163], v[148:151]
	v_mfma_f32_16x16x32_bf16 v[140:143], v[96:99], v[160:163], v[140:143]
	v_mfma_f32_16x16x32_bf16 v[132:135], v[88:91], v[168:171], v[132:135]
	v_mfma_f32_16x16x32_bf16 v[128:131], v[96:99], v[168:171], v[128:131]
	v_mfma_f32_16x16x32_bf16 v[116:119], v[88:91], v[176:179], v[116:119]
	v_mfma_f32_16x16x32_bf16 v[108:111], v[96:99], v[176:179], v[108:111]
	v_mfma_f32_16x16x32_bf16 v[84:87], v[88:91], v[184:187], v[84:87]
	v_mfma_f32_16x16x32_bf16 v[72:75], v[96:99], v[184:187], v[72:75]
	v_mfma_f32_16x16x32_bf16 v[148:151], v[92:95], v[164:167], v[148:151]
	v_mfma_f32_16x16x32_bf16 v[140:143], v[100:103], v[164:167], v[140:143]
	v_mfma_f32_16x16x32_bf16 v[132:135], v[92:95], v[172:175], v[132:135]
	v_mfma_f32_16x16x32_bf16 v[128:131], v[100:103], v[172:175], v[128:131]
	v_mfma_f32_16x16x32_bf16 v[116:119], v[92:95], v[180:183], v[116:119]
	v_mfma_f32_16x16x32_bf16 v[108:111], v[100:103], v[180:183], v[108:111]
	v_mfma_f32_16x16x32_bf16 v[84:87], v[92:95], v[188:191], v[84:87]
	v_mfma_f32_16x16x32_bf16 v[72:75], v[100:103], v[188:191], v[72:75]
	s_setprio 0
	s_barrier
; #define PG8_STAGE(bufoff, gbase, voff) do { _Pragma("unroll") for (int _i = 0; _i < 2; ++_i) \
;         __builtin_amdgcn_global_load_lds((const unsigned*)((const char*)(gbase) + (voff)[_i]), (PG8_LAS unsigned*)(lds + (bufoff) + ldsw + _i * 8192), 16, 0, 0); } while (0)
; #define PG8_LDA(dst, b, h) do { _Pragma("unroll") for (int m = 0; m < 4; ++m) _Pragma("unroll") for (int k = 0; k < 2; ++k) dst[m][k] = *(const PG8_LAS bf16x8*)(lds + PG8_SA(b, h) + aoff + m * 2048 + k * 1024); } while (0)
; #define PG8_MMA(ai, bj, At, Bt) do { __builtin_amdgcn_s_setprio(1); _Pragma("unroll") for (int m = 0; m < 4; ++m) _Pragma("unroll") for (int n = 0; n < 2; ++n) _Pragma("unroll") for (int k = 0; k < 2; ++k) \
;         acc[ai][bj][m][n] = __builtin_amdgcn_mfma_f32_16x16x32_bf16(Bt[n][k], At[m][k], acc[ai][bj][m][n], 0, 0, 0); __builtin_amdgcn_s_setprio(0); } while (0)
; #define PG8_WAIT_V(n) asm volatile("s_waitcnt vmcnt(" #n ")" ::: "memory")
; #define PG8_WAIT_L(n) asm volatile("s_waitcnt lgkmcnt(" #n ")" ::: "memory")
; #define PG8_BAR __builtin_amdgcn_s_barrier()
; #define PG8_SCHED __builtin_amdgcn_sched_barrier(0)
; template <class Epi, class Sched, bool ALIGN_EPI = false, bool SP2 = false>
; __device__ __forceinline__ void gemm_phase(PG8_LAS unsigned char* lds, const Gemm g, const Sched& S, const Epi& E, int wave_s_) {
;     ...
;             PG8_WAIT_V(8); PG8_WAIT_L(0); PG8_BAR; PG8_MMA(0, 0, At, B0); PG8_MMA(0, 1, At, B1); PG8_BAR; PG8_SCHED;
;             PG8_LDA(At, 1, 1); PG8_STAGE(PG8_SB(1, 0), b3, voffB); PG8_STAGE(PG8_SB(1, 1), b3 + hstep, voffB); PG8_STAGE(PG8_SA(1, 0), a3, voffA);
;             PG8_WAIT_V(8); PG8_WAIT_L(0); PG8_BAR; PG8_MMA(1, 0, At, B0); PG8_MMA(1, 1, At, B1); PG8_BAR; PG8_SCHED;
	s_add_i32 s10, s64, s41
	v_lshl_add_u64 v[208:209], v[208:209], 0, s[76:77]
	s_mov_b32 m0, s10
	ds_read_b128 v[160:163], v227 offset:49152
	ds_read_b128 v[164:167], v227 offset:50176
	ds_read_b128 v[168:171], v227 offset:51200
	ds_read_b128 v[172:175], v227 offset:52224
	ds_read_b128 v[176:179], v227 offset:53248
	ds_read_b128 v[180:183], v227 offset:54272
	ds_read_b128 v[184:187], v227 offset:55296
	ds_read_b128 v[188:191], v227 offset:56320
	global_load_lds_dwordx4 v[208:209], off
	s_add_i32 m0, s10, 0x2000
	s_add_u32 s10, s34, 0xb0080
	v_lshl_add_u64 v[208:209], v[210:211], 0, s[76:77]
	s_addc_u32 s11, s35, 0
	s_add_i32 s34, s65, s41
	global_load_lds_dwordx4 v[208:209], off
	s_mov_b32 m0, s34
	s_nop 0
	global_load_lds_dwordx4 v196, s[10:11]
	s_add_i32 m0, s34, 0x2000
	s_nop 0
	global_load_lds_dwordx4 v192, s[10:11]
	v_lshl_add_u64 v[208:209], v[212:213], 0, s[76:77]
	s_mov_b32 m0, s48
	s_nop 0
	global_load_lds_dwordx4 v[208:209], off
	v_lshl_add_u64 v[208:209], v[214:215], 0, s[76:77]
	s_mov_b32 m0, s49
	s_nop 0
	global_load_lds_dwordx4 v[208:209], off
	s_waitcnt vmcnt(8)
	s_waitcnt lgkmcnt(0)
	s_barrier
	s_setprio 1
	s_waitcnt lgkmcnt(0)
	v_mfma_f32_16x16x32_bf16 v[60:63], v[64:67], v[160:163], v[60:63]
	v_mfma_f32_16x16x32_bf16 v[56:59], v[76:79], v[160:163], v[56:59]
	v_mfma_f32_16x16x32_bf16 v[48:51], v[64:67], v[168:171], v[48:51]
	v_mfma_f32_16x16x32_bf16 v[40:43], v[76:79], v[168:171], v[40:43]
	v_mfma_f32_16x16x32_bf16 v[28:31], v[64:67], v[176:179], v[28:31]
	v_mfma_f32_16x16x32_bf16 v[24:27], v[76:79], v[176:179], v[24:27]
	v_mfma_f32_16x16x32_bf16 v[16:19], v[64:67], v[184:187], v[16:19]
	v_mfma_f32_16x16x32_bf16 v[8:11], v[76:79], v[184:187], v[8:11]
	v_mfma_f32_16x16x32_bf16 v[60:63], v[68:71], v[164:167], v[60:63]
	v_mfma_f32_16x16x32_bf16 v[56:59], v[80:83], v[164:167], v[56:59]
	v_mfma_f32_16x16x32_bf16 v[48:51], v[68:71], v[172:175], v[48:51]
	v_mfma_f32_16x16x32_bf16 v[40:43], v[80:83], v[172:175], v[40:43]
	v_mfma_f32_16x16x32_bf16 v[28:31], v[68:71], v[180:183], v[28:31]
	v_mfma_f32_16x16x32_bf16 v[24:27], v[80:83], v[180:183], v[24:27]
	v_mfma_f32_16x16x32_bf16 v[16:19], v[68:71], v[188:191], v[16:19]
	v_mfma_f32_16x16x32_bf16 v[8:11], v[80:83], v[188:191], v[8:11]
	s_setprio 0
	s_setprio 1
	v_mfma_f32_16x16x32_bf16 v[52:55], v[88:91], v[160:163], v[52:55]
	v_mfma_f32_16x16x32_bf16 v[44:47], v[96:99], v[160:163], v[44:47]
	v_mfma_f32_16x16x32_bf16 v[36:39], v[88:91], v[168:171], v[36:39]
	v_mfma_f32_16x16x32_bf16 v[32:35], v[96:99], v[168:171], v[32:35]
	v_mfma_f32_16x16x32_bf16 v[20:23], v[88:91], v[176:179], v[20:23]
	v_mfma_f32_16x16x32_bf16 v[12:15], v[96:99], v[176:179], v[12:15]
	v_mfma_f32_16x16x32_bf16 v[4:7], v[88:91], v[184:187], v[4:7]
	v_mfma_f32_16x16x32_bf16 v[0:3], v[96:99], v[184:187], v[0:3]
	v_mfma_f32_16x16x32_bf16 v[52:55], v[92:95], v[164:167], v[52:55]
	v_mfma_f32_16x16x32_bf16 v[44:47], v[100:103], v[164:167], v[44:47]
	v_mfma_f32_16x16x32_bf16 v[36:39], v[92:95], v[172:175], v[36:39]
	v_mfma_f32_16x16x32_bf16 v[32:35], v[100:103], v[172:175], v[32:35]
	v_mfma_f32_16x16x32_bf16 v[20:23], v[92:95], v[180:183], v[20:23]
	v_mfma_f32_16x16x32_bf16 v[12:15], v[100:103], v[180:183], v[12:15]
	v_mfma_f32_16x16x32_bf16 v[4:7], v[92:95], v[188:191], v[4:7]
	v_mfma_f32_16x16x32_bf16 v[0:3], v[100:103], v[188:191], v[0:3]
	s_setprio 0
	s_barrier
	s_add_u32 s61, s61, 0x100
	s_addc_u32 s62, s62, 0
	s_cmp_ge_u32 s63, s59
	s_mov_b64 s[10:11], s[12:13]
	s_mov_b32 s34, s63
	s_cbranch_scc0 .LBB0_298
	s_and_b64 vcc, exec, s[22:23]
	s_cbranch_vccz .LBB0_301
	s_barrier

; #define PG8_STAGE(bufoff, gbase, voff) do { _Pragma("unroll") for (int _i = 0; _i < 2; ++_i) \
;         __builtin_amdgcn_global_load_lds((const unsigned*)((const char*)(gbase) + (voff)[_i]), (PG8_LAS unsigned*)(lds + (bufoff) + ldsw + _i * 8192), 16, 0, 0); } while (0)
; #define PG8_LDA(dst, b, h) do { _Pragma("unroll") for (int m = 0; m < 4; ++m) _Pragma("unroll") for (int k = 0; k < 2; ++k) dst[m][k] = *(const PG8_LAS bf16x8*)(lds + PG8_SA(b, h) + aoff + m * 2048 + k * 1024); } while (0)
; #define PG8_LDB(dst, b, h) do { _Pragma("unroll") for (int n = 0; n < 2; ++n) _Pragma("unroll") for (int k = 0; k < 2; ++k) dst[n][k] = *(const PG8_LAS bf16x8*)(lds + PG8_SB(b, h) + boff + n * 2048 + k * 1024); } while (0)
; #define PG8_MMA(ai, bj, At, Bt) do { __builtin_amdgcn_s_setprio(1); _Pragma("unroll") for (int m = 0; m < 4; ++m) _Pragma("unroll") for (int n = 0; n < 2; ++n) _Pragma("unroll") for (int k = 0; k < 2; ++k) \
;         acc[ai][bj][m][n] = __builtin_amdgcn_mfma_f32_16x16x32_bf16(Bt[n][k], At[m][k], acc[ai][bj][m][n], 0, 0, 0); __builtin_amdgcn_s_setprio(0); } while (0)
; #define PG8_WAIT_V(n) asm volatile("s_waitcnt vmcnt(" #n ")" ::: "memory")
; #define PG8_WAIT_L(n) asm volatile("s_waitcnt lgkmcnt(" #n ")" ::: "memory")
; #define PG8_BAR __builtin_amdgcn_s_barrier()
; #define PG8_SCHED __builtin_amdgcn_sched_barrier(0)
; template <class Epi, class Sched, bool ALIGN_EPI = false, bool SP2 = false>
; __device__ __forceinline__ void gemm_phase(PG8_LAS unsigned char* lds, const Gemm g, const Sched& S, const Epi& E, int wave_s_) {
;     ...
;             PG8_LDB(B0, 0, 0); PG8_LDB(B1, 0, 1); PG8_SCHED; PG8_LDA(At, 0, 0); PG8_STAGE(PG8_SA(1, 1), a1 + hstep, voffA);
;             PG8_WAIT_V(8); PG8_WAIT_L(0); PG8_BAR; PG8_MMA(0, 0, At, B0); PG8_MMA(0, 1, At, B1); PG8_BAR; PG8_SCHED;
;             PG8_LDA(At, 0, 1); PG8_STAGE(PG8_SB(0, 0), b2, voffB); PG8_STAGE(PG8_SB(0, 1), b2 + hstep, voffB); PG8_STAGE(PG8_SA(0, 0), a2, voffA);
;             PG8_WAIT_V(8); PG8_WAIT_L(0); PG8_BAR; PG8_MMA(1, 0, At, B0); PG8_MMA(1, 1, At, B1); PG8_BAR; PG8_SCHED;
.LBB0_562:
	s_add_u32 s10, s6, 0xfffc0080
	s_addc_u32 s11, s7, -1
	s_add_i32 s16, 0, 0x10000
	s_cmp_eq_u32 s15, 12
	s_cselect_b32 s13, s61, s11
	s_cselect_b32 s12, s60, s10
	s_cselect_b32 s11, s63, s14
	s_cselect_b32 s10, s62, s9
	s_add_i32 s18, 0, 0x14000
	v_add_u32_e32 v154, s16, v152
	v_add_u32_e32 v170, s18, v152
	ds_read_b128 v[128:131], v154
	ds_read_b128 v[144:147], v154 offset:1024
	ds_read_b128 v[148:151], v154 offset:2048
	ds_read_b128 v[154:157], v154 offset:3072
	ds_read_b128 v[158:161], v170
	ds_read_b128 v[162:165], v170 offset:1024
	ds_read_b128 v[166:169], v170 offset:2048
	ds_read_b128 v[170:173], v170 offset:3072
	s_add_i32 m0, s93, 0xc000
	ds_read_b128 v[174:177], v153
	ds_read_b128 v[178:181], v153 offset:1024
	ds_read_b128 v[182:185], v153 offset:2048
	ds_read_b128 v[186:189], v153 offset:3072
	ds_read_b128 v[190:193], v153 offset:4096
	ds_read_b128 v[206:209], v153 offset:5120
	ds_read_b128 v[210:213], v153 offset:6144
	ds_read_b128 v[214:217], v153 offset:7168
	global_load_lds_dwordx4 v140, s[6:7]
	s_add_i32 m0, s93, 0xe000
	s_nop 0
	global_load_lds_dwordx4 v142, s[6:7]
	s_waitcnt vmcnt(8)
	s_waitcnt lgkmcnt(0)
	s_barrier
	s_setprio 1
	s_waitcnt lgkmcnt(0)
	v_mfma_f32_16x16x32_bf16 v[124:127], v[128:131], v[174:177], v[124:127]
	v_mfma_f32_16x16x32_bf16 v[120:123], v[148:151], v[174:177], v[120:123]
	v_mfma_f32_16x16x32_bf16 v[116:119], v[128:131], v[182:185], v[116:119]
	v_mfma_f32_16x16x32_bf16 v[112:115], v[148:151], v[182:185], v[112:115]
	v_mfma_f32_16x16x32_bf16 v[108:111], v[128:131], v[190:193], v[108:111]
	v_mfma_f32_16x16x32_bf16 v[104:107], v[148:151], v[190:193], v[104:107]
	v_mfma_f32_16x16x32_bf16 v[100:103], v[128:131], v[210:213], v[100:103]
	v_mfma_f32_16x16x32_bf16 v[96:99], v[148:151], v[210:213], v[96:99]
	v_mfma_f32_16x16x32_bf16 v[124:127], v[144:147], v[178:181], v[124:127]
	v_mfma_f32_16x16x32_bf16 v[120:123], v[154:157], v[178:181], v[120:123]
	v_mfma_f32_16x16x32_bf16 v[116:119], v[144:147], v[186:189], v[116:119]
	v_mfma_f32_16x16x32_bf16 v[112:115], v[154:157], v[186:189], v[112:115]
	v_mfma_f32_16x16x32_bf16 v[108:111], v[144:147], v[206:209], v[108:111]
	v_mfma_f32_16x16x32_bf16 v[104:107], v[154:157], v[206:209], v[104:107]
	v_mfma_f32_16x16x32_bf16 v[100:103], v[144:147], v[214:217], v[100:103]
	v_mfma_f32_16x16x32_bf16 v[96:99], v[154:157], v[214:217], v[96:99]
	s_setprio 0
	s_setprio 1
	v_mfma_f32_16x16x32_bf16 v[60:63], v[158:161], v[174:177], v[60:63]
	v_mfma_f32_16x16x32_bf16 v[56:59], v[166:169], v[174:177], v[56:59]
	v_mfma_f32_16x16x32_bf16 v[52:55], v[158:161], v[182:185], v[52:55]
	v_mfma_f32_16x16x32_bf16 v[48:51], v[166:169], v[182:185], v[48:51]
	v_mfma_f32_16x16x32_bf16 v[44:47], v[158:161], v[190:193], v[44:47]
	v_mfma_f32_16x16x32_bf16 v[40:43], v[166:169], v[190:193], v[40:43]
	v_mfma_f32_16x16x32_bf16 v[36:39], v[158:161], v[210:213], v[36:39]
	v_mfma_f32_16x16x32_bf16 v[32:35], v[166:169], v[210:213], v[32:35]
	v_mfma_f32_16x16x32_bf16 v[60:63], v[162:165], v[178:181], v[60:63]
	v_mfma_f32_16x16x32_bf16 v[56:59], v[170:173], v[178:181], v[56:59]
	v_mfma_f32_16x16x32_bf16 v[52:55], v[162:165], v[186:189], v[52:55]
	v_mfma_f32_16x16x32_bf16 v[48:51], v[170:173], v[186:189], v[48:51]
	v_mfma_f32_16x16x32_bf16 v[44:47], v[162:165], v[206:209], v[44:47]
	v_mfma_f32_16x16x32_bf16 v[40:43], v[170:173], v[206:209], v[40:43]
	v_mfma_f32_16x16x32_bf16 v[36:39], v[162:165], v[214:217], v[36:39]
	v_mfma_f32_16x16x32_bf16 v[32:35], v[170:173], v[214:217], v[32:35]
	s_setprio 0
	s_barrier
	s_add_i32 s16, s16, s92
	v_lshl_add_u64 v[194:195], s[10:11], 0, v[134:135]
	s_mov_b32 m0, s16
	ds_read_b128 v[174:177], v153 offset:16384
	ds_read_b128 v[178:181], v153 offset:17408
	ds_read_b128 v[182:185], v153 offset:18432
	ds_read_b128 v[186:189], v153 offset:19456
	ds_read_b128 v[190:193], v153 offset:20480
	ds_read_b128 v[206:209], v153 offset:21504
	ds_read_b128 v[210:213], v153 offset:22528
	ds_read_b128 v[214:217], v153 offset:23552
	global_load_lds_dwordx4 v[194:195], off
	s_add_i32 m0, s16, 0x2000
	s_add_u32 s16, s10, 0x40000
	v_lshl_add_u64 v[218:219], s[10:11], 0, v[138:139]
	s_addc_u32 s17, s11, 0
	s_add_i32 s18, s18, s92
	global_load_lds_dwordx4 v[218:219], off
	s_mov_b32 m0, s18
	v_lshl_add_u64 v[222:223], s[12:13], 0, v[136:137]
	global_load_lds_dwordx4 v134, s[16:17]
	s_add_i32 m0, s18, 0x2000
	s_nop 0
	global_load_lds_dwordx4 v138, s[16:17]
	v_lshl_add_u64 v[220:221], s[12:13], 0, v[132:133]
	s_mov_b32 m0, s93
	s_nop 0
	global_load_lds_dwordx4 v[220:221], off
	s_mov_b32 m0, s94
	s_nop 0
	global_load_lds_dwordx4 v[222:223], off
	s_waitcnt vmcnt(8)
	s_waitcnt lgkmcnt(0)
	s_barrier
; #define PG8_STAGE(bufoff, gbase, voff) do { _Pragma("unroll") for (int _i = 0; _i < 2; ++_i) \
;         __builtin_amdgcn_global_load_lds((const unsigned*)((const char*)(gbase) + (voff)[_i]), (PG8_LAS unsigned*)(lds + (bufoff) + ldsw + _i * 8192), 16, 0, 0); } while (0)
; #define PG8_LDA(dst, b, h) do { _Pragma("unroll") for (int m = 0; m < 4; ++m) _Pragma("unroll") for (int k = 0; k < 2; ++k) dst[m][k] = *(const PG8_LAS bf16x8*)(lds + PG8_SA(b, h) + aoff + m * 2048 + k * 1024); } while (0)
; #define PG8_LDB(dst, b, h) do { _Pragma("unroll") for (int n = 0; n < 2; ++n) _Pragma("unroll") for (int k = 0; k < 2; ++k) dst[n][k] = *(const PG8_LAS bf16x8*)(lds + PG8_SB(b, h) + boff + n * 2048 + k * 1024); } while (0)
; #define PG8_MMA(ai, bj, At, Bt) do { __builtin_amdgcn_s_setprio(1); _Pragma("unroll") for (int m = 0; m < 4; ++m) _Pragma("unroll") for (int n = 0; n < 2; ++n) _Pragma("unroll") for (int k = 0; k < 2; ++k) \
;         acc[ai][bj][m][n] = __builtin_amdgcn_mfma_f32_16x16x32_bf16(Bt[n][k], At[m][k], acc[ai][bj][m][n], 0, 0, 0); __builtin_amdgcn_s_setprio(0); } while (0)
; #define PG8_WAIT_V(n) asm volatile("s_waitcnt vmcnt(" #n ")" ::: "memory")
; #define PG8_WAIT_L(n) asm volatile("s_waitcnt lgkmcnt(" #n ")" ::: "memory")
; #define PG8_BAR __builtin_amdgcn_s_barrier()
; #define PG8_SCHED __builtin_amdgcn_sched_barrier(0)
; template <class Epi, class Sched, bool ALIGN_EPI = false, bool SP2 = false>
; __device__ __forceinline__ void gemm_phase(PG8_LAS unsigned char* lds, const Gemm g, const Sched& S, const Epi& E, int wave_s_) {
;     ...
;             PG8_WAIT_V(8); PG8_WAIT_L(0); PG8_BAR; PG8_MMA(1, 0, At, B0); PG8_MMA(1, 1, At, B1); PG8_BAR; PG8_SCHED;
;             PG8_LDB(B0, 1, 0); PG8_LDB(B1, 1, 1); PG8_SCHED; PG8_LDA(At, 1, 0); PG8_STAGE(PG8_SA(0, 1), a2 + hstep, voffA);
;             PG8_WAIT_V(8); PG8_WAIT_L(0); PG8_BAR; PG8_MMA(0, 0, At, B0); PG8_MMA(0, 1, At, B1); PG8_BAR; PG8_SCHED;
	s_setprio 1
	s_waitcnt lgkmcnt(0)
	v_mfma_f32_16x16x32_bf16 v[92:95], v[128:131], v[174:177], v[92:95]
	v_mfma_f32_16x16x32_bf16 v[88:91], v[148:151], v[174:177], v[88:91]
	v_mfma_f32_16x16x32_bf16 v[84:87], v[128:131], v[182:185], v[84:87]
	v_mfma_f32_16x16x32_bf16 v[80:83], v[148:151], v[182:185], v[80:83]
	v_mfma_f32_16x16x32_bf16 v[76:79], v[128:131], v[190:193], v[76:79]
	v_mfma_f32_16x16x32_bf16 v[72:75], v[148:151], v[190:193], v[72:75]
	v_mfma_f32_16x16x32_bf16 v[68:71], v[128:131], v[210:213], v[68:71]
	v_mfma_f32_16x16x32_bf16 v[64:67], v[148:151], v[210:213], v[64:67]
	v_mfma_f32_16x16x32_bf16 v[92:95], v[144:147], v[178:181], v[92:95]
	v_mfma_f32_16x16x32_bf16 v[88:91], v[154:157], v[178:181], v[88:91]
	v_mfma_f32_16x16x32_bf16 v[84:87], v[144:147], v[186:189], v[84:87]
	v_mfma_f32_16x16x32_bf16 v[80:83], v[154:157], v[186:189], v[80:83]
	v_mfma_f32_16x16x32_bf16 v[76:79], v[144:147], v[206:209], v[76:79]
	v_mfma_f32_16x16x32_bf16 v[72:75], v[154:157], v[206:209], v[72:75]
	v_mfma_f32_16x16x32_bf16 v[68:71], v[144:147], v[214:217], v[68:71]
	v_mfma_f32_16x16x32_bf16 v[64:67], v[154:157], v[214:217], v[64:67]
	s_setprio 0
	s_setprio 1
	v_mfma_f32_16x16x32_bf16 v[28:31], v[158:161], v[174:177], v[28:31]
	v_mfma_f32_16x16x32_bf16 v[24:27], v[166:169], v[174:177], v[24:27]
	v_mfma_f32_16x16x32_bf16 v[20:23], v[158:161], v[182:185], v[20:23]
	v_mfma_f32_16x16x32_bf16 v[16:19], v[166:169], v[182:185], v[16:19]
	v_mfma_f32_16x16x32_bf16 v[12:15], v[158:161], v[190:193], v[12:15]
	v_mfma_f32_16x16x32_bf16 v[8:11], v[166:169], v[190:193], v[8:11]
	v_mfma_f32_16x16x32_bf16 v[4:7], v[158:161], v[210:213], v[4:7]
	v_mfma_f32_16x16x32_bf16 v[0:3], v[166:169], v[210:213], v[0:3]
	v_mfma_f32_16x16x32_bf16 v[28:31], v[162:165], v[178:181], v[28:31]
	v_mfma_f32_16x16x32_bf16 v[24:27], v[170:173], v[178:181], v[24:27]
	v_mfma_f32_16x16x32_bf16 v[20:23], v[162:165], v[186:189], v[20:23]
	v_mfma_f32_16x16x32_bf16 v[16:19], v[170:173], v[186:189], v[16:19]
	v_mfma_f32_16x16x32_bf16 v[12:15], v[162:165], v[206:209], v[12:15]
	v_mfma_f32_16x16x32_bf16 v[8:11], v[170:173], v[206:209], v[8:11]
	v_mfma_f32_16x16x32_bf16 v[4:7], v[162:165], v[214:217], v[4:7]
	v_mfma_f32_16x16x32_bf16 v[0:3], v[170:173], v[214:217], v[0:3]
	s_setprio 0
	s_barrier
	s_add_i32 s16, 0, 0x18000
	s_add_i32 s17, 0, 0x1c000
	v_add_u32_e32 v154, s16, v152
	v_add_u32_e32 v170, s17, v152
	ds_read_b128 v[128:131], v154
	ds_read_b128 v[144:147], v154 offset:1024
	ds_read_b128 v[148:151], v154 offset:2048
	ds_read_b128 v[154:157], v154 offset:3072
	ds_read_b128 v[158:161], v170
	ds_read_b128 v[162:165], v170 offset:1024
	ds_read_b128 v[166:169], v170 offset:2048
	ds_read_b128 v[170:173], v170 offset:3072
	s_add_u32 s12, s12, 0x40000
	s_addc_u32 s13, s13, 0
	s_mov_b32 m0, s95
	ds_read_b128 v[174:177], v153 offset:32768
	ds_read_b128 v[178:181], v153 offset:33792
	ds_read_b128 v[182:185], v153 offset:34816
	ds_read_b128 v[186:189], v153 offset:35840
	ds_read_b128 v[190:193], v153 offset:36864
	ds_read_b128 v[206:209], v153 offset:37888
	ds_read_b128 v[210:213], v153 offset:38912
	ds_read_b128 v[214:217], v153 offset:39936
	global_load_lds_dwordx4 v132, s[12:13]
	s_mov_b32 m0, s96
	s_nop 0
	global_load_lds_dwordx4 v136, s[12:13]
	s_waitcnt vmcnt(8)
	s_waitcnt lgkmcnt(0)
	s_barrier
	s_setprio 1
	s_waitcnt lgkmcnt(0)
	v_mfma_f32_16x16x32_bf16 v[124:127], v[128:131], v[174:177], v[124:127]
	v_mfma_f32_16x16x32_bf16 v[120:123], v[148:151], v[174:177], v[120:123]
	v_mfma_f32_16x16x32_bf16 v[116:119], v[128:131], v[182:185], v[116:119]
	v_mfma_f32_16x16x32_bf16 v[112:115], v[148:151], v[182:185], v[112:115]
	v_mfma_f32_16x16x32_bf16 v[108:111], v[128:131], v[190:193], v[108:111]
	v_mfma_f32_16x16x32_bf16 v[104:107], v[148:151], v[190:193], v[104:107]
	v_mfma_f32_16x16x32_bf16 v[100:103], v[128:131], v[210:213], v[100:103]
	v_mfma_f32_16x16x32_bf16 v[96:99], v[148:151], v[210:213], v[96:99]
	v_mfma_f32_16x16x32_bf16 v[124:127], v[144:147], v[178:181], v[124:127]
	v_mfma_f32_16x16x32_bf16 v[120:123], v[154:157], v[178:181], v[120:123]
	v_mfma_f32_16x16x32_bf16 v[116:119], v[144:147], v[186:189], v[116:119]
	v_mfma_f32_16x16x32_bf16 v[112:115], v[154:157], v[186:189], v[112:115]
	v_mfma_f32_16x16x32_bf16 v[108:111], v[144:147], v[206:209], v[108:111]
	v_mfma_f32_16x16x32_bf16 v[104:107], v[154:157], v[206:209], v[104:107]
	v_mfma_f32_16x16x32_bf16 v[100:103], v[144:147], v[214:217], v[100:103]
	v_mfma_f32_16x16x32_bf16 v[96:99], v[154:157], v[214:217], v[96:99]
	s_setprio 0
	s_setprio 1
	v_mfma_f32_16x16x32_bf16 v[60:63], v[158:161], v[174:177], v[60:63]
	v_mfma_f32_16x16x32_bf16 v[56:59], v[166:169], v[174:177], v[56:59]
	v_mfma_f32_16x16x32_bf16 v[52:55], v[158:161], v[182:185], v[52:55]
	v_mfma_f32_16x16x32_bf16 v[48:51], v[166:169], v[182:185], v[48:51]
	v_mfma_f32_16x16x32_bf16 v[44:47], v[158:161], v[190:193], v[44:47]
	v_mfma_f32_16x16x32_bf16 v[40:43], v[166:169], v[190:193], v[40:43]
	v_mfma_f32_16x16x32_bf16 v[36:39], v[158:161], v[210:213], v[36:39]
	v_mfma_f32_16x16x32_bf16 v[32:35], v[166:169], v[210:213], v[32:35]
	v_mfma_f32_16x16x32_bf16 v[60:63], v[162:165], v[178:181], v[60:63]
	v_mfma_f32_16x16x32_bf16 v[56:59], v[170:173], v[178:181], v[56:59]
	v_mfma_f32_16x16x32_bf16 v[52:55], v[162:165], v[186:189], v[52:55]
	v_mfma_f32_16x16x32_bf16 v[48:51], v[170:173], v[186:189], v[48:51]
	v_mfma_f32_16x16x32_bf16 v[44:47], v[162:165], v[206:209], v[44:47]
	v_mfma_f32_16x16x32_bf16 v[40:43], v[170:173], v[206:209], v[40:43]
	v_mfma_f32_16x16x32_bf16 v[36:39], v[162:165], v[214:217], v[36:39]
	v_mfma_f32_16x16x32_bf16 v[32:35], v[170:173], v[214:217], v[32:35]
	s_setprio 0
	s_barrier
; #define PG8_STAGE(bufoff, gbase, voff) do { _Pragma("unroll") for (int _i = 0; _i < 2; ++_i) \
;         __builtin_amdgcn_global_load_lds((const unsigned*)((const char*)(gbase) + (voff)[_i]), (PG8_LAS unsigned*)(lds + (bufoff) + ldsw + _i * 8192), 16, 0, 0); } while (0)
; #define PG8_LDA(dst, b, h) do { _Pragma("unroll") for (int m = 0; m < 4; ++m) _Pragma("unroll") for (int k = 0; k < 2; ++k) dst[m][k] = *(const PG8_LAS bf16x8*)(lds + PG8_SA(b, h) + aoff + m * 2048 + k * 1024); } while (0)
; #define PG8_MMA(ai, bj, At, Bt) do { __builtin_amdgcn_s_setprio(1); _Pragma("unroll") for (int m = 0; m < 4; ++m) _Pragma("unroll") for (int n = 0; n < 2; ++n) _Pragma("unroll") for (int k = 0; k < 2; ++k) \
;         acc[ai][bj][m][n] = __builtin_amdgcn_mfma_f32_16x16x32_bf16(Bt[n][k], At[m][k], acc[ai][bj][m][n], 0, 0, 0); __builtin_amdgcn_s_setprio(0); } while (0)
; #define PG8_WAIT_V(n) asm volatile("s_waitcnt vmcnt(" #n ")" ::: "memory")
; #define PG8_WAIT_L(n) asm volatile("s_waitcnt lgkmcnt(" #n ")" ::: "memory")
; #define PG8_BAR __builtin_amdgcn_s_barrier()
; #define PG8_SCHED __builtin_amdgcn_sched_barrier(0)
; template <class Epi, class Sched, bool ALIGN_EPI = false, bool SP2 = false>
; __device__ __forceinline__ void gemm_phase(PG8_LAS unsigned char* lds, const Gemm g, const Sched& S, const Epi& E, int wave_s_) {
;     ...
;             PG8_WAIT_V(8); PG8_WAIT_L(0); PG8_BAR; PG8_MMA(0, 0, At, B0); PG8_MMA(0, 1, At, B1); PG8_BAR; PG8_SCHED;
;             PG8_LDA(At, 1, 1); PG8_STAGE(PG8_SB(1, 0), b3, voffB); PG8_STAGE(PG8_SB(1, 1), b3 + hstep, voffB); PG8_STAGE(PG8_SA(1, 0), a3, voffA);
;             PG8_WAIT_V(8); PG8_WAIT_L(0); PG8_BAR; PG8_MMA(1, 0, At, B0); PG8_MMA(1, 1, At, B1); PG8_BAR; PG8_SCHED;
	s_add_i32 s12, s16, s92
	v_lshl_add_u64 v[194:195], v[194:195], 0, s[76:77]
	s_mov_b32 m0, s12
	ds_read_b128 v[174:177], v153 offset:49152
	ds_read_b128 v[178:181], v153 offset:50176
	ds_read_b128 v[182:185], v153 offset:51200
	ds_read_b128 v[186:189], v153 offset:52224
	ds_read_b128 v[190:193], v153 offset:53248
	ds_read_b128 v[206:209], v153 offset:54272
	ds_read_b128 v[210:213], v153 offset:55296
	ds_read_b128 v[214:217], v153 offset:56320
	global_load_lds_dwordx4 v[194:195], off
	s_add_i32 m0, s12, 0x2000
	s_add_u32 s10, s10, 0x40080
	v_lshl_add_u64 v[194:195], v[218:219], 0, s[76:77]
	s_addc_u32 s11, s11, 0
	s_add_i32 s12, s17, s92
	global_load_lds_dwordx4 v[194:195], off
	s_mov_b32 m0, s12
	s_nop 0
	global_load_lds_dwordx4 v134, s[10:11]
	s_add_i32 m0, s12, 0x2000
	s_nop 0
	global_load_lds_dwordx4 v138, s[10:11]
	v_lshl_add_u64 v[194:195], v[220:221], 0, s[76:77]
	s_mov_b32 m0, s48
	s_nop 0
	global_load_lds_dwordx4 v[194:195], off
	v_lshl_add_u64 v[194:195], v[222:223], 0, s[76:77]
	s_mov_b32 m0, s49
	s_nop 0
	global_load_lds_dwordx4 v[194:195], off
	s_waitcnt vmcnt(8)
	s_waitcnt lgkmcnt(0)
	s_barrier
	s_setprio 1
	s_waitcnt lgkmcnt(0)
	v_mfma_f32_16x16x32_bf16 v[92:95], v[128:131], v[174:177], v[92:95]
	v_mfma_f32_16x16x32_bf16 v[88:91], v[148:151], v[174:177], v[88:91]
	v_mfma_f32_16x16x32_bf16 v[84:87], v[128:131], v[182:185], v[84:87]
	v_mfma_f32_16x16x32_bf16 v[80:83], v[148:151], v[182:185], v[80:83]
	v_mfma_f32_16x16x32_bf16 v[76:79], v[128:131], v[190:193], v[76:79]
	v_mfma_f32_16x16x32_bf16 v[72:75], v[148:151], v[190:193], v[72:75]
	v_mfma_f32_16x16x32_bf16 v[68:71], v[128:131], v[210:213], v[68:71]
	v_mfma_f32_16x16x32_bf16 v[64:67], v[148:151], v[210:213], v[64:67]
	v_mfma_f32_16x16x32_bf16 v[92:95], v[144:147], v[178:181], v[92:95]
	v_mfma_f32_16x16x32_bf16 v[88:91], v[154:157], v[178:181], v[88:91]
	v_mfma_f32_16x16x32_bf16 v[84:87], v[144:147], v[186:189], v[84:87]
	v_mfma_f32_16x16x32_bf16 v[80:83], v[154:157], v[186:189], v[80:83]
	v_mfma_f32_16x16x32_bf16 v[76:79], v[144:147], v[206:209], v[76:79]
	v_mfma_f32_16x16x32_bf16 v[72:75], v[154:157], v[206:209], v[72:75]
	v_mfma_f32_16x16x32_bf16 v[68:71], v[144:147], v[214:217], v[68:71]
	v_mfma_f32_16x16x32_bf16 v[64:67], v[154:157], v[214:217], v[64:67]
	s_setprio 0
	s_setprio 1
	v_mfma_f32_16x16x32_bf16 v[28:31], v[158:161], v[174:177], v[28:31]
	v_mfma_f32_16x16x32_bf16 v[24:27], v[166:169], v[174:177], v[24:27]
	v_mfma_f32_16x16x32_bf16 v[20:23], v[158:161], v[182:185], v[20:23]
	v_mfma_f32_16x16x32_bf16 v[16:19], v[166:169], v[182:185], v[16:19]
	v_mfma_f32_16x16x32_bf16 v[12:15], v[158:161], v[190:193], v[12:15]
	v_mfma_f32_16x16x32_bf16 v[8:11], v[166:169], v[190:193], v[8:11]
	v_mfma_f32_16x16x32_bf16 v[4:7], v[158:161], v[210:213], v[4:7]
	v_mfma_f32_16x16x32_bf16 v[0:3], v[166:169], v[210:213], v[0:3]
	v_mfma_f32_16x16x32_bf16 v[28:31], v[162:165], v[178:181], v[28:31]
	v_mfma_f32_16x16x32_bf16 v[24:27], v[170:173], v[178:181], v[24:27]
	v_mfma_f32_16x16x32_bf16 v[20:23], v[162:165], v[186:189], v[20:23]
	v_mfma_f32_16x16x32_bf16 v[16:19], v[170:173], v[186:189], v[16:19]
	v_mfma_f32_16x16x32_bf16 v[12:15], v[162:165], v[206:209], v[12:15]
	v_mfma_f32_16x16x32_bf16 v[8:11], v[170:173], v[206:209], v[8:11]
	v_mfma_f32_16x16x32_bf16 v[4:7], v[162:165], v[214:217], v[4:7]
	v_mfma_f32_16x16x32_bf16 v[0:3], v[170:173], v[214:217], v[0:3]
	s_setprio 0
	s_barrier
	s_add_i32 s15, s15, 2
	s_add_u32 s6, s6, 0x100
	s_addc_u32 s7, s7, 0
	s_add_u32 s9, s9, 0x100
	s_addc_u32 s14, s14, 0
	s_cmp_gt_u32 s15, 13
	s_cbranch_scc0 .LBB0_562
	s_and_b64 vcc, exec, s[52:53]
	s_cbranch_vccz .LBB0_565
	s_barrier

; #define PG8_STAGE(bufoff, gbase, voff) do { _Pragma("unroll") for (int _i = 0; _i < 2; ++_i) \
;         __builtin_amdgcn_global_load_lds((const unsigned*)((const char*)(gbase) + (voff)[_i]), (PG8_LAS unsigned*)(lds + (bufoff) + ldsw + _i * 8192), 16, 0, 0); } while (0)
; #define PG8_LDA(dst, b, h) do { _Pragma("unroll") for (int m = 0; m < 4; ++m) _Pragma("unroll") for (int k = 0; k < 2; ++k) dst[m][k] = *(const PG8_LAS bf16x8*)(lds + PG8_SA(b, h) + aoff + m * 2048 + k * 1024); } while (0)
; #define PG8_LDB(dst, b, h) do { _Pragma("unroll") for (int n = 0; n < 2; ++n) _Pragma("unroll") for (int k = 0; k < 2; ++k) dst[n][k] = *(const PG8_LAS bf16x8*)(lds + PG8_SB(b, h) + boff + n * 2048 + k * 1024); } while (0)
; #define PG8_MMA(ai, bj, At, Bt) do { __builtin_amdgcn_s_setprio(1); _Pragma("unroll") for (int m = 0; m < 4; ++m) _Pragma("unroll") for (int n = 0; n < 2; ++n) _Pragma("unroll") for (int k = 0; k < 2; ++k) \
;         acc[ai][bj][m][n] = __builtin_amdgcn_mfma_f32_16x16x32_bf16(Bt[n][k], At[m][k], acc[ai][bj][m][n], 0, 0, 0); __builtin_amdgcn_s_setprio(0); } while (0)
; #define PG8_WAIT_V(n) asm volatile("s_waitcnt vmcnt(" #n ")" ::: "memory")
; #define PG8_WAIT_L(n) asm volatile("s_waitcnt lgkmcnt(" #n ")" ::: "memory")
; #define PG8_BAR __builtin_amdgcn_s_barrier()
; #define PG8_SCHED __builtin_amdgcn_sched_barrier(0)
; template <class Epi, class Sched, bool ALIGN_EPI = false, bool SP2 = false>
; __device__ __forceinline__ void gemm_phase(PG8_LAS unsigned char* lds, const Gemm g, const Sched& S, const Epi& E, int wave_s_) {
;     ...
;             PG8_LDB(B0, 0, 0); PG8_LDB(B1, 0, 1); PG8_SCHED; PG8_LDA(At, 0, 0); PG8_STAGE(PG8_SA(1, 1), a1 + hstep, voffA);
;             PG8_WAIT_V(8); PG8_WAIT_L(0); PG8_BAR; PG8_MMA(0, 0, At, B0); PG8_MMA(0, 1, At, B1); PG8_BAR; PG8_SCHED;
;             PG8_LDA(At, 0, 1); PG8_STAGE(PG8_SB(0, 0), b2, voffB); PG8_STAGE(PG8_SB(0, 1), b2 + hstep, voffB); PG8_STAGE(PG8_SA(0, 0), a2, voffA);
;             PG8_WAIT_V(8); PG8_WAIT_L(0); PG8_BAR; PG8_MMA(1, 0, At, B0); PG8_MMA(1, 1, At, B1); PG8_BAR; PG8_SCHED;
.LBB0_1185:
	s_add_u32 s20, s18, 0xfffc0080
	s_addc_u32 s21, s19, -1
	s_add_i32 s46, 0, 0x10000
	s_cmp_eq_u32 s45, 12
	s_cselect_b32 s23, s7, s21
	s_cselect_b32 s22, s6, s20
	s_cselect_b32 s21, s17, s44
	s_cselect_b32 s20, s16, s15
	s_add_i32 s48, 0, 0x14000
	v_add_u32_e32 v148, s46, v134
	v_add_u32_e32 v164, s48, v134
	ds_read_b128 v[136:139], v148
	ds_read_b128 v[140:143], v148 offset:1024
	ds_read_b128 v[144:147], v148 offset:2048
	ds_read_b128 v[148:151], v148 offset:3072
	ds_read_b128 v[152:155], v164
	ds_read_b128 v[156:159], v164 offset:1024
	ds_read_b128 v[160:163], v164 offset:2048
	ds_read_b128 v[164:167], v164 offset:3072
	s_add_i32 m0, s30, 0xc000
	ds_read_b128 v[168:171], v135
	ds_read_b128 v[172:175], v135 offset:1024
	ds_read_b128 v[176:179], v135 offset:2048
	ds_read_b128 v[180:183], v135 offset:3072
	ds_read_b128 v[184:187], v135 offset:4096
	ds_read_b128 v[188:191], v135 offset:5120
	ds_read_b128 v[192:195], v135 offset:6144
	ds_read_b128 v[206:209], v135 offset:7168
	global_load_lds_dwordx4 v130, s[18:19]
	s_add_i32 m0, s30, 0xe000
	s_nop 0
	global_load_lds_dwordx4 v132, s[18:19]
	s_waitcnt vmcnt(8)
	s_waitcnt lgkmcnt(0)
	s_barrier
	s_setprio 1
	s_waitcnt lgkmcnt(0)
	v_mfma_f32_16x16x32_bf16 v[124:127], v[136:139], v[168:171], v[124:127]
	v_mfma_f32_16x16x32_bf16 v[120:123], v[144:147], v[168:171], v[120:123]
	v_mfma_f32_16x16x32_bf16 v[116:119], v[136:139], v[176:179], v[116:119]
	v_mfma_f32_16x16x32_bf16 v[112:115], v[144:147], v[176:179], v[112:115]
	v_mfma_f32_16x16x32_bf16 v[108:111], v[136:139], v[184:187], v[108:111]
	v_mfma_f32_16x16x32_bf16 v[100:103], v[144:147], v[184:187], v[100:103]
	v_mfma_f32_16x16x32_bf16 v[92:95], v[136:139], v[192:195], v[92:95]
	v_mfma_f32_16x16x32_bf16 v[84:87], v[144:147], v[192:195], v[84:87]
	v_mfma_f32_16x16x32_bf16 v[124:127], v[140:143], v[172:175], v[124:127]
	v_mfma_f32_16x16x32_bf16 v[120:123], v[148:151], v[172:175], v[120:123]
	v_mfma_f32_16x16x32_bf16 v[116:119], v[140:143], v[180:183], v[116:119]
	v_mfma_f32_16x16x32_bf16 v[112:115], v[148:151], v[180:183], v[112:115]
	v_mfma_f32_16x16x32_bf16 v[108:111], v[140:143], v[188:191], v[108:111]
	v_mfma_f32_16x16x32_bf16 v[100:103], v[148:151], v[188:191], v[100:103]
	v_mfma_f32_16x16x32_bf16 v[92:95], v[140:143], v[206:209], v[92:95]
	v_mfma_f32_16x16x32_bf16 v[84:87], v[148:151], v[206:209], v[84:87]
	s_setprio 0
	s_setprio 1
	v_mfma_f32_16x16x32_bf16 v[104:107], v[152:155], v[168:171], v[104:107]
	v_mfma_f32_16x16x32_bf16 v[96:99], v[160:163], v[168:171], v[96:99]
	v_mfma_f32_16x16x32_bf16 v[88:91], v[152:155], v[176:179], v[88:91]
	v_mfma_f32_16x16x32_bf16 v[80:83], v[160:163], v[176:179], v[80:83]
	v_mfma_f32_16x16x32_bf16 v[76:79], v[152:155], v[184:187], v[76:79]
	v_mfma_f32_16x16x32_bf16 v[72:75], v[160:163], v[184:187], v[72:75]
	v_mfma_f32_16x16x32_bf16 v[68:71], v[152:155], v[192:195], v[68:71]
	v_mfma_f32_16x16x32_bf16 v[64:67], v[160:163], v[192:195], v[64:67]
	v_mfma_f32_16x16x32_bf16 v[104:107], v[156:159], v[172:175], v[104:107]
	v_mfma_f32_16x16x32_bf16 v[96:99], v[164:167], v[172:175], v[96:99]
	v_mfma_f32_16x16x32_bf16 v[88:91], v[156:159], v[180:183], v[88:91]
	v_mfma_f32_16x16x32_bf16 v[80:83], v[164:167], v[180:183], v[80:83]
	v_mfma_f32_16x16x32_bf16 v[76:79], v[156:159], v[188:191], v[76:79]
	v_mfma_f32_16x16x32_bf16 v[72:75], v[164:167], v[188:191], v[72:75]
	v_mfma_f32_16x16x32_bf16 v[68:71], v[156:159], v[206:209], v[68:71]
	v_mfma_f32_16x16x32_bf16 v[64:67], v[164:167], v[206:209], v[64:67]
	s_setprio 0
	s_barrier
	s_add_i32 s46, s46, s29
	v_lshl_add_u64 v[210:211], s[20:21], 0, v[196:197]
	s_mov_b32 m0, s46
	ds_read_b128 v[168:171], v135 offset:16384
	ds_read_b128 v[172:175], v135 offset:17408
	ds_read_b128 v[176:179], v135 offset:18432
	ds_read_b128 v[180:183], v135 offset:19456
	ds_read_b128 v[184:187], v135 offset:20480
	ds_read_b128 v[188:191], v135 offset:21504
	ds_read_b128 v[192:195], v135 offset:22528
	ds_read_b128 v[206:209], v135 offset:23552
	global_load_lds_dwordx4 v[210:211], off
	s_add_i32 m0, s46, 0x2000
	s_add_u32 s46, s20, 0x40000
	v_lshl_add_u64 v[212:213], s[20:21], 0, v[128:129]
	s_addc_u32 s47, s21, 0
	s_add_i32 s48, s48, s29
	global_load_lds_dwordx4 v[212:213], off
	s_mov_b32 m0, s48
	v_lshl_add_u64 v[216:217], s[22:23], 0, v[128:129]
	global_load_lds_dwordx4 v196, s[46:47]
	s_add_i32 m0, s48, 0x2000
	s_nop 0
	global_load_lds_dwordx4 v128, s[46:47]
	v_lshl_add_u64 v[214:215], s[22:23], 0, v[196:197]
	s_mov_b32 m0, s30
	s_nop 0
	global_load_lds_dwordx4 v[214:215], off
	s_mov_b32 m0, s31
	s_nop 0
	global_load_lds_dwordx4 v[216:217], off
	s_waitcnt vmcnt(8)
	s_waitcnt lgkmcnt(0)
	s_barrier
; #define PG8_STAGE(bufoff, gbase, voff) do { _Pragma("unroll") for (int _i = 0; _i < 2; ++_i) \
;         __builtin_amdgcn_global_load_lds((const unsigned*)((const char*)(gbase) + (voff)[_i]), (PG8_LAS unsigned*)(lds + (bufoff) + ldsw + _i * 8192), 16, 0, 0); } while (0)
; #define PG8_LDA(dst, b, h) do { _Pragma("unroll") for (int m = 0; m < 4; ++m) _Pragma("unroll") for (int k = 0; k < 2; ++k) dst[m][k] = *(const PG8_LAS bf16x8*)(lds + PG8_SA(b, h) + aoff + m * 2048 + k * 1024); } while (0)
; #define PG8_LDB(dst, b, h) do { _Pragma("unroll") for (int n = 0; n < 2; ++n) _Pragma("unroll") for (int k = 0; k < 2; ++k) dst[n][k] = *(const PG8_LAS bf16x8*)(lds + PG8_SB(b, h) + boff + n * 2048 + k * 1024); } while (0)
; #define PG8_MMA(ai, bj, At, Bt) do { __builtin_amdgcn_s_setprio(1); _Pragma("unroll") for (int m = 0; m < 4; ++m) _Pragma("unroll") for (int n = 0; n < 2; ++n) _Pragma("unroll") for (int k = 0; k < 2; ++k) \
;         acc[ai][bj][m][n] = __builtin_amdgcn_mfma_f32_16x16x32_bf16(Bt[n][k], At[m][k], acc[ai][bj][m][n], 0, 0, 0); __builtin_amdgcn_s_setprio(0); } while (0)
; #define PG8_WAIT_V(n) asm volatile("s_waitcnt vmcnt(" #n ")" ::: "memory")
; #define PG8_WAIT_L(n) asm volatile("s_waitcnt lgkmcnt(" #n ")" ::: "memory")
; #define PG8_BAR __builtin_amdgcn_s_barrier()
; #define PG8_SCHED __builtin_amdgcn_sched_barrier(0)
; template <class Epi, class Sched, bool ALIGN_EPI = false, bool SP2 = false>
; __device__ __forceinline__ void gemm_phase(PG8_LAS unsigned char* lds, const Gemm g, const Sched& S, const Epi& E, int wave_s_) {
;     ...
;             PG8_WAIT_V(8); PG8_WAIT_L(0); PG8_BAR; PG8_MMA(1, 0, At, B0); PG8_MMA(1, 1, At, B1); PG8_BAR; PG8_SCHED;
;             PG8_LDB(B0, 1, 0); PG8_LDB(B1, 1, 1); PG8_SCHED; PG8_LDA(At, 1, 0); PG8_STAGE(PG8_SA(0, 1), a2 + hstep, voffA);
;             PG8_WAIT_V(8); PG8_WAIT_L(0); PG8_BAR; PG8_MMA(0, 0, At, B0); PG8_MMA(0, 1, At, B1); PG8_BAR; PG8_SCHED;
	s_setprio 1
	s_waitcnt lgkmcnt(0)
	v_mfma_f32_16x16x32_bf16 v[60:63], v[136:139], v[168:171], v[60:63]
	v_mfma_f32_16x16x32_bf16 v[56:59], v[144:147], v[168:171], v[56:59]
	v_mfma_f32_16x16x32_bf16 v[52:55], v[136:139], v[176:179], v[52:55]
	v_mfma_f32_16x16x32_bf16 v[48:51], v[144:147], v[176:179], v[48:51]
	v_mfma_f32_16x16x32_bf16 v[44:47], v[136:139], v[184:187], v[44:47]
	v_mfma_f32_16x16x32_bf16 v[36:39], v[144:147], v[184:187], v[36:39]
	v_mfma_f32_16x16x32_bf16 v[28:31], v[136:139], v[192:195], v[28:31]
	v_mfma_f32_16x16x32_bf16 v[20:23], v[144:147], v[192:195], v[20:23]
	v_mfma_f32_16x16x32_bf16 v[60:63], v[140:143], v[172:175], v[60:63]
	v_mfma_f32_16x16x32_bf16 v[56:59], v[148:151], v[172:175], v[56:59]
	v_mfma_f32_16x16x32_bf16 v[52:55], v[140:143], v[180:183], v[52:55]
	v_mfma_f32_16x16x32_bf16 v[48:51], v[148:151], v[180:183], v[48:51]
	v_mfma_f32_16x16x32_bf16 v[44:47], v[140:143], v[188:191], v[44:47]
	v_mfma_f32_16x16x32_bf16 v[36:39], v[148:151], v[188:191], v[36:39]
	v_mfma_f32_16x16x32_bf16 v[28:31], v[140:143], v[206:209], v[28:31]
	v_mfma_f32_16x16x32_bf16 v[20:23], v[148:151], v[206:209], v[20:23]
	s_setprio 0
	s_setprio 1
	v_mfma_f32_16x16x32_bf16 v[40:43], v[152:155], v[168:171], v[40:43]
	v_mfma_f32_16x16x32_bf16 v[32:35], v[160:163], v[168:171], v[32:35]
	v_mfma_f32_16x16x32_bf16 v[24:27], v[152:155], v[176:179], v[24:27]
	v_mfma_f32_16x16x32_bf16 v[16:19], v[160:163], v[176:179], v[16:19]
	v_mfma_f32_16x16x32_bf16 v[12:15], v[152:155], v[184:187], v[12:15]
	v_mfma_f32_16x16x32_bf16 v[8:11], v[160:163], v[184:187], v[8:11]
	v_mfma_f32_16x16x32_bf16 v[4:7], v[152:155], v[192:195], v[4:7]
	v_mfma_f32_16x16x32_bf16 v[0:3], v[160:163], v[192:195], v[0:3]
	v_mfma_f32_16x16x32_bf16 v[40:43], v[156:159], v[172:175], v[40:43]
	v_mfma_f32_16x16x32_bf16 v[32:35], v[164:167], v[172:175], v[32:35]
	v_mfma_f32_16x16x32_bf16 v[24:27], v[156:159], v[180:183], v[24:27]
	v_mfma_f32_16x16x32_bf16 v[16:19], v[164:167], v[180:183], v[16:19]
	v_mfma_f32_16x16x32_bf16 v[12:15], v[156:159], v[188:191], v[12:15]
	v_mfma_f32_16x16x32_bf16 v[8:11], v[164:167], v[188:191], v[8:11]
	v_mfma_f32_16x16x32_bf16 v[4:7], v[156:159], v[206:209], v[4:7]
	v_mfma_f32_16x16x32_bf16 v[0:3], v[164:167], v[206:209], v[0:3]
	s_setprio 0
	s_barrier
	s_add_i32 s46, 0, 0x18000
	s_add_i32 s47, 0, 0x1c000
	v_add_u32_e32 v148, s46, v134
	v_add_u32_e32 v164, s47, v134
	ds_read_b128 v[136:139], v148
	ds_read_b128 v[140:143], v148 offset:1024
	ds_read_b128 v[144:147], v148 offset:2048
	ds_read_b128 v[148:151], v148 offset:3072
	ds_read_b128 v[152:155], v164
	ds_read_b128 v[156:159], v164 offset:1024
	ds_read_b128 v[160:163], v164 offset:2048
	ds_read_b128 v[164:167], v164 offset:3072
	s_add_u32 s22, s22, 0x40000
	s_addc_u32 s23, s23, 0
	s_mov_b32 m0, s33
	ds_read_b128 v[168:171], v135 offset:32768
	ds_read_b128 v[172:175], v135 offset:33792
	ds_read_b128 v[176:179], v135 offset:34816
	ds_read_b128 v[180:183], v135 offset:35840
	ds_read_b128 v[184:187], v135 offset:36864
	ds_read_b128 v[188:191], v135 offset:37888
	ds_read_b128 v[192:195], v135 offset:38912
	ds_read_b128 v[206:209], v135 offset:39936
	global_load_lds_dwordx4 v196, s[22:23]
	s_mov_b32 m0, s34
	s_nop 0
	global_load_lds_dwordx4 v128, s[22:23]
	s_waitcnt vmcnt(8)
	s_waitcnt lgkmcnt(0)
	s_barrier
	s_setprio 1
	s_waitcnt lgkmcnt(0)
	v_mfma_f32_16x16x32_bf16 v[124:127], v[136:139], v[168:171], v[124:127]
	v_mfma_f32_16x16x32_bf16 v[120:123], v[144:147], v[168:171], v[120:123]
	v_mfma_f32_16x16x32_bf16 v[116:119], v[136:139], v[176:179], v[116:119]
	v_mfma_f32_16x16x32_bf16 v[112:115], v[144:147], v[176:179], v[112:115]
	v_mfma_f32_16x16x32_bf16 v[108:111], v[136:139], v[184:187], v[108:111]
	v_mfma_f32_16x16x32_bf16 v[100:103], v[144:147], v[184:187], v[100:103]
	v_mfma_f32_16x16x32_bf16 v[92:95], v[136:139], v[192:195], v[92:95]
	v_mfma_f32_16x16x32_bf16 v[84:87], v[144:147], v[192:195], v[84:87]
	v_mfma_f32_16x16x32_bf16 v[124:127], v[140:143], v[172:175], v[124:127]
	v_mfma_f32_16x16x32_bf16 v[120:123], v[148:151], v[172:175], v[120:123]
	v_mfma_f32_16x16x32_bf16 v[116:119], v[140:143], v[180:183], v[116:119]
	v_mfma_f32_16x16x32_bf16 v[112:115], v[148:151], v[180:183], v[112:115]
	v_mfma_f32_16x16x32_bf16 v[108:111], v[140:143], v[188:191], v[108:111]
	v_mfma_f32_16x16x32_bf16 v[100:103], v[148:151], v[188:191], v[100:103]
	v_mfma_f32_16x16x32_bf16 v[92:95], v[140:143], v[206:209], v[92:95]
	v_mfma_f32_16x16x32_bf16 v[84:87], v[148:151], v[206:209], v[84:87]
	s_setprio 0
	s_setprio 1
	v_mfma_f32_16x16x32_bf16 v[104:107], v[152:155], v[168:171], v[104:107]
	v_mfma_f32_16x16x32_bf16 v[96:99], v[160:163], v[168:171], v[96:99]
	v_mfma_f32_16x16x32_bf16 v[88:91], v[152:155], v[176:179], v[88:91]
	v_mfma_f32_16x16x32_bf16 v[80:83], v[160:163], v[176:179], v[80:83]
	v_mfma_f32_16x16x32_bf16 v[76:79], v[152:155], v[184:187], v[76:79]
	v_mfma_f32_16x16x32_bf16 v[72:75], v[160:163], v[184:187], v[72:75]
	v_mfma_f32_16x16x32_bf16 v[68:71], v[152:155], v[192:195], v[68:71]
	v_mfma_f32_16x16x32_bf16 v[64:67], v[160:163], v[192:195], v[64:67]
	v_mfma_f32_16x16x32_bf16 v[104:107], v[156:159], v[172:175], v[104:107]
	v_mfma_f32_16x16x32_bf16 v[96:99], v[164:167], v[172:175], v[96:99]
	v_mfma_f32_16x16x32_bf16 v[88:91], v[156:159], v[180:183], v[88:91]
	v_mfma_f32_16x16x32_bf16 v[80:83], v[164:167], v[180:183], v[80:83]
	v_mfma_f32_16x16x32_bf16 v[76:79], v[156:159], v[188:191], v[76:79]
	v_mfma_f32_16x16x32_bf16 v[72:75], v[164:167], v[188:191], v[72:75]
	v_mfma_f32_16x16x32_bf16 v[68:71], v[156:159], v[206:209], v[68:71]
	v_mfma_f32_16x16x32_bf16 v[64:67], v[164:167], v[206:209], v[64:67]
	s_setprio 0
	s_barrier
; #define PG8_STAGE(bufoff, gbase, voff) do { _Pragma("unroll") for (int _i = 0; _i < 2; ++_i) \
;         __builtin_amdgcn_global_load_lds((const unsigned*)((const char*)(gbase) + (voff)[_i]), (PG8_LAS unsigned*)(lds + (bufoff) + ldsw + _i * 8192), 16, 0, 0); } while (0)
; #define PG8_LDA(dst, b, h) do { _Pragma("unroll") for (int m = 0; m < 4; ++m) _Pragma("unroll") for (int k = 0; k < 2; ++k) dst[m][k] = *(const PG8_LAS bf16x8*)(lds + PG8_SA(b, h) + aoff + m * 2048 + k * 1024); } while (0)
; #define PG8_MMA(ai, bj, At, Bt) do { __builtin_amdgcn_s_setprio(1); _Pragma("unroll") for (int m = 0; m < 4; ++m) _Pragma("unroll") for (int n = 0; n < 2; ++n) _Pragma("unroll") for (int k = 0; k < 2; ++k) \
;         acc[ai][bj][m][n] = __builtin_amdgcn_mfma_f32_16x16x32_bf16(Bt[n][k], At[m][k], acc[ai][bj][m][n], 0, 0, 0); __builtin_amdgcn_s_setprio(0); } while (0)
; #define PG8_WAIT_V(n) asm volatile("s_waitcnt vmcnt(" #n ")" ::: "memory")
; #define PG8_WAIT_L(n) asm volatile("s_waitcnt lgkmcnt(" #n ")" ::: "memory")
; #define PG8_BAR __builtin_amdgcn_s_barrier()
; #define PG8_SCHED __builtin_amdgcn_sched_barrier(0)
; template <class Epi, class Sched, bool ALIGN_EPI = false, bool SP2 = false>
; __device__ __forceinline__ void gemm_phase(PG8_LAS unsigned char* lds, const Gemm g, const Sched& S, const Epi& E, int wave_s_) {
;     ...
;             PG8_WAIT_V(8); PG8_WAIT_L(0); PG8_BAR; PG8_MMA(0, 0, At, B0); PG8_MMA(0, 1, At, B1); PG8_BAR; PG8_SCHED;
;             PG8_LDA(At, 1, 1); PG8_STAGE(PG8_SB(1, 0), b3, voffB); PG8_STAGE(PG8_SB(1, 1), b3 + hstep, voffB); PG8_STAGE(PG8_SA(1, 0), a3, voffA);
;             PG8_WAIT_V(8); PG8_WAIT_L(0); PG8_BAR; PG8_MMA(1, 0, At, B0); PG8_MMA(1, 1, At, B1); PG8_BAR; PG8_SCHED;
	s_add_i32 s22, s46, s29
	v_lshl_add_u64 v[210:211], v[210:211], 0, s[76:77]
	s_mov_b32 m0, s22
	ds_read_b128 v[168:171], v135 offset:49152
	ds_read_b128 v[172:175], v135 offset:50176
	ds_read_b128 v[176:179], v135 offset:51200
	ds_read_b128 v[180:183], v135 offset:52224
	ds_read_b128 v[184:187], v135 offset:53248
	ds_read_b128 v[188:191], v135 offset:54272
	ds_read_b128 v[192:195], v135 offset:55296
	ds_read_b128 v[206:209], v135 offset:56320
	global_load_lds_dwordx4 v[210:211], off
	s_add_i32 m0, s22, 0x2000
	s_add_u32 s20, s20, 0x40080
	v_lshl_add_u64 v[210:211], v[212:213], 0, s[76:77]
	s_addc_u32 s21, s21, 0
	s_add_i32 s22, s47, s29
	global_load_lds_dwordx4 v[210:211], off
	s_mov_b32 m0, s22
	s_nop 0
	global_load_lds_dwordx4 v196, s[20:21]
	s_add_i32 m0, s22, 0x2000
	s_nop 0
	global_load_lds_dwordx4 v128, s[20:21]
	v_lshl_add_u64 v[210:211], v[214:215], 0, s[76:77]
	s_mov_b32 m0, s38
	s_nop 0
	global_load_lds_dwordx4 v[210:211], off
	v_lshl_add_u64 v[210:211], v[216:217], 0, s[76:77]
	s_mov_b32 m0, s39
	s_nop 0
	global_load_lds_dwordx4 v[210:211], off
	s_waitcnt vmcnt(8)
	s_waitcnt lgkmcnt(0)
	s_barrier
	s_setprio 1
	s_waitcnt lgkmcnt(0)
	v_mfma_f32_16x16x32_bf16 v[60:63], v[136:139], v[168:171], v[60:63]
	v_mfma_f32_16x16x32_bf16 v[56:59], v[144:147], v[168:171], v[56:59]
	v_mfma_f32_16x16x32_bf16 v[52:55], v[136:139], v[176:179], v[52:55]
	v_mfma_f32_16x16x32_bf16 v[48:51], v[144:147], v[176:179], v[48:51]
	v_mfma_f32_16x16x32_bf16 v[44:47], v[136:139], v[184:187], v[44:47]
	v_mfma_f32_16x16x32_bf16 v[36:39], v[144:147], v[184:187], v[36:39]
	v_mfma_f32_16x16x32_bf16 v[28:31], v[136:139], v[192:195], v[28:31]
	v_mfma_f32_16x16x32_bf16 v[20:23], v[144:147], v[192:195], v[20:23]
	v_mfma_f32_16x16x32_bf16 v[60:63], v[140:143], v[172:175], v[60:63]
	v_mfma_f32_16x16x32_bf16 v[56:59], v[148:151], v[172:175], v[56:59]
	v_mfma_f32_16x16x32_bf16 v[52:55], v[140:143], v[180:183], v[52:55]
	v_mfma_f32_16x16x32_bf16 v[48:51], v[148:151], v[180:183], v[48:51]
	v_mfma_f32_16x16x32_bf16 v[44:47], v[140:143], v[188:191], v[44:47]
	v_mfma_f32_16x16x32_bf16 v[36:39], v[148:151], v[188:191], v[36:39]
	v_mfma_f32_16x16x32_bf16 v[28:31], v[140:143], v[206:209], v[28:31]
	v_mfma_f32_16x16x32_bf16 v[20:23], v[148:151], v[206:209], v[20:23]
	s_setprio 0
	s_setprio 1
	v_mfma_f32_16x16x32_bf16 v[40:43], v[152:155], v[168:171], v[40:43]
	v_mfma_f32_16x16x32_bf16 v[32:35], v[160:163], v[168:171], v[32:35]
	v_mfma_f32_16x16x32_bf16 v[24:27], v[152:155], v[176:179], v[24:27]
	v_mfma_f32_16x16x32_bf16 v[16:19], v[160:163], v[176:179], v[16:19]
	v_mfma_f32_16x16x32_bf16 v[12:15], v[152:155], v[184:187], v[12:15]
	v_mfma_f32_16x16x32_bf16 v[8:11], v[160:163], v[184:187], v[8:11]
	v_mfma_f32_16x16x32_bf16 v[4:7], v[152:155], v[192:195], v[4:7]
	v_mfma_f32_16x16x32_bf16 v[0:3], v[160:163], v[192:195], v[0:3]
	v_mfma_f32_16x16x32_bf16 v[40:43], v[156:159], v[172:175], v[40:43]
	v_mfma_f32_16x16x32_bf16 v[32:35], v[164:167], v[172:175], v[32:35]
	v_mfma_f32_16x16x32_bf16 v[24:27], v[156:159], v[180:183], v[24:27]
	v_mfma_f32_16x16x32_bf16 v[16:19], v[164:167], v[180:183], v[16:19]
	v_mfma_f32_16x16x32_bf16 v[12:15], v[156:159], v[188:191], v[12:15]
	v_mfma_f32_16x16x32_bf16 v[8:11], v[164:167], v[188:191], v[8:11]
	v_mfma_f32_16x16x32_bf16 v[4:7], v[156:159], v[206:209], v[4:7]
	v_mfma_f32_16x16x32_bf16 v[0:3], v[164:167], v[206:209], v[0:3]
	s_setprio 0
	s_barrier
	s_add_i32 s45, s45, 2
	s_add_u32 s18, s18, 0x100
	s_addc_u32 s19, s19, 0
	s_add_u32 s15, s15, 0x100
	s_addc_u32 s44, s44, 0
	s_cmp_gt_u32 s45, 13
	s_cbranch_scc0 .LBB0_1185
	s_and_b64 vcc, exec, s[12:13]
	s_cbranch_vccz .LBB0_1188
	s_barrier

; #define PG8_STAGE(bufoff, gbase, voff) do { _Pragma("unroll") for (int _i = 0; _i < 2; ++_i) \
;         __builtin_amdgcn_global_load_lds((const unsigned*)((const char*)(gbase) + (voff)[_i]), (PG8_LAS unsigned*)(lds + (bufoff) + ldsw + _i * 8192), 16, 0, 0); } while (0)
; #define PG8_LDA(dst, b, h) do { _Pragma("unroll") for (int m = 0; m < 4; ++m) _Pragma("unroll") for (int k = 0; k < 2; ++k) dst[m][k] = *(const PG8_LAS bf16x8*)(lds + PG8_SA(b, h) + aoff + m * 2048 + k * 1024); } while (0)
; #define PG8_LDB(dst, b, h) do { _Pragma("unroll") for (int n = 0; n < 2; ++n) _Pragma("unroll") for (int k = 0; k < 2; ++k) dst[n][k] = *(const PG8_LAS bf16x8*)(lds + PG8_SB(b, h) + boff + n * 2048 + k * 1024); } while (0)
; #define PG8_MMA(ai, bj, At, Bt) do { __builtin_amdgcn_s_setprio(1); _Pragma("unroll") for (int m = 0; m < 4; ++m) _Pragma("unroll") for (int n = 0; n < 2; ++n) _Pragma("unroll") for (int k = 0; k < 2; ++k) \
;         acc[ai][bj][m][n] = __builtin_amdgcn_mfma_f32_16x16x32_bf16(Bt[n][k], At[m][k], acc[ai][bj][m][n], 0, 0, 0); __builtin_amdgcn_s_setprio(0); } while (0)
; #define PG8_WAIT_V(n) asm volatile("s_waitcnt vmcnt(" #n ")" ::: "memory")
; #define PG8_WAIT_L(n) asm volatile("s_waitcnt lgkmcnt(" #n ")" ::: "memory")
; #define PG8_BAR __builtin_amdgcn_s_barrier()
; #define PG8_SCHED __builtin_amdgcn_sched_barrier(0)
; template <class Epi, class Sched, bool ALIGN_EPI = false, bool SP2 = false>
; __device__ __forceinline__ void gemm_phase(PG8_LAS unsigned char* lds, const Gemm g, const Sched& S, const Epi& E, int wave_s_) {
;     ...
;             PG8_LDB(B0, 0, 0); PG8_LDB(B1, 0, 1); PG8_SCHED; PG8_LDA(At, 0, 0); PG8_STAGE(PG8_SA(1, 1), a1 + hstep, voffA);
;             PG8_WAIT_V(8); PG8_WAIT_L(0); PG8_BAR; PG8_MMA(0, 0, At, B0); PG8_MMA(0, 1, At, B1); PG8_BAR; PG8_SCHED;
;             PG8_LDA(At, 0, 1); PG8_STAGE(PG8_SB(0, 0), b2, voffB); PG8_STAGE(PG8_SB(0, 1), b2 + hstep, voffB); PG8_STAGE(PG8_SA(0, 0), a2, voffA);
;             PG8_WAIT_V(8); PG8_WAIT_L(0); PG8_BAR; PG8_MMA(1, 0, At, B0); PG8_MMA(1, 1, At, B1); PG8_BAR; PG8_SCHED;
.LBB0_1338:
	s_add_u32 s18, s16, 0x100
	s_addc_u32 s19, s17, 0
	s_add_i32 s48, 0, 0x10000
	s_cmp_eq_u32 s47, 2
	s_cselect_b32 s23, s7, s19
	s_cselect_b32 s22, s6, s18
	s_cselect_b32 s21, s15, s46
	s_cselect_b32 s20, s14, s45
	s_add_i32 s49, 0, 0x14000
	v_add_u32_e32 v152, s48, v142
	v_add_u32_e32 v168, s49, v142
	ds_read_b128 v[138:141], v152
	ds_read_b128 v[144:147], v152 offset:1024
	ds_read_b128 v[148:151], v152 offset:2048
	ds_read_b128 v[152:155], v152 offset:3072
	ds_read_b128 v[156:159], v168
	ds_read_b128 v[160:163], v168 offset:1024
	ds_read_b128 v[164:167], v168 offset:2048
	ds_read_b128 v[168:171], v168 offset:3072
	v_lshl_add_u64 v[214:215], s[16:17], 0, v[134:135]
	s_add_i32 m0, s30, 0xc000
	ds_read_b128 v[172:175], v143
	ds_read_b128 v[176:179], v143 offset:1024
	ds_read_b128 v[180:183], v143 offset:2048
	ds_read_b128 v[184:187], v143 offset:3072
	ds_read_b128 v[188:191], v143 offset:4096
	ds_read_b128 v[192:195], v143 offset:5120
	ds_read_b128 v[206:209], v143 offset:6144
	ds_read_b128 v[210:213], v143 offset:7168
	global_load_lds_dwordx4 v[214:215], off
	v_lshl_add_u64 v[214:215], s[16:17], 0, v[136:137]
	s_add_i32 m0, s30, 0xe000
	s_nop 0
	global_load_lds_dwordx4 v[214:215], off
	s_waitcnt vmcnt(8)
	s_waitcnt lgkmcnt(0)
	s_barrier
	s_setprio 1
	s_waitcnt lgkmcnt(0)
	v_mfma_f32_16x16x32_bf16 v[124:127], v[138:141], v[172:175], v[124:127]
	v_mfma_f32_16x16x32_bf16 v[120:123], v[148:151], v[172:175], v[120:123]
	v_mfma_f32_16x16x32_bf16 v[116:119], v[138:141], v[180:183], v[116:119]
	v_mfma_f32_16x16x32_bf16 v[108:111], v[148:151], v[180:183], v[108:111]
	v_mfma_f32_16x16x32_bf16 v[100:103], v[138:141], v[188:191], v[100:103]
	v_mfma_f32_16x16x32_bf16 v[92:95], v[148:151], v[188:191], v[92:95]
	v_mfma_f32_16x16x32_bf16 v[84:87], v[138:141], v[206:209], v[84:87]
	v_mfma_f32_16x16x32_bf16 v[76:79], v[148:151], v[206:209], v[76:79]
	v_mfma_f32_16x16x32_bf16 v[124:127], v[144:147], v[176:179], v[124:127]
	v_mfma_f32_16x16x32_bf16 v[120:123], v[152:155], v[176:179], v[120:123]
	v_mfma_f32_16x16x32_bf16 v[116:119], v[144:147], v[184:187], v[116:119]
	v_mfma_f32_16x16x32_bf16 v[108:111], v[152:155], v[184:187], v[108:111]
	v_mfma_f32_16x16x32_bf16 v[100:103], v[144:147], v[192:195], v[100:103]
	v_mfma_f32_16x16x32_bf16 v[92:95], v[152:155], v[192:195], v[92:95]
	v_mfma_f32_16x16x32_bf16 v[84:87], v[144:147], v[210:213], v[84:87]
	v_mfma_f32_16x16x32_bf16 v[76:79], v[152:155], v[210:213], v[76:79]
	s_setprio 0
	s_setprio 1
	v_mfma_f32_16x16x32_bf16 v[112:115], v[156:159], v[172:175], v[112:115]
	v_mfma_f32_16x16x32_bf16 v[104:107], v[164:167], v[172:175], v[104:107]
	v_mfma_f32_16x16x32_bf16 v[96:99], v[156:159], v[180:183], v[96:99]
	v_mfma_f32_16x16x32_bf16 v[88:91], v[164:167], v[180:183], v[88:91]
	v_mfma_f32_16x16x32_bf16 v[80:83], v[156:159], v[188:191], v[80:83]
	v_mfma_f32_16x16x32_bf16 v[72:75], v[164:167], v[188:191], v[72:75]
	v_mfma_f32_16x16x32_bf16 v[68:71], v[156:159], v[206:209], v[68:71]
	v_mfma_f32_16x16x32_bf16 v[64:67], v[164:167], v[206:209], v[64:67]
	v_mfma_f32_16x16x32_bf16 v[112:115], v[160:163], v[176:179], v[112:115]
	v_mfma_f32_16x16x32_bf16 v[104:107], v[168:171], v[176:179], v[104:107]
	v_mfma_f32_16x16x32_bf16 v[96:99], v[160:163], v[184:187], v[96:99]
	v_mfma_f32_16x16x32_bf16 v[88:91], v[168:171], v[184:187], v[88:91]
	v_mfma_f32_16x16x32_bf16 v[80:83], v[160:163], v[192:195], v[80:83]
	v_mfma_f32_16x16x32_bf16 v[72:75], v[168:171], v[192:195], v[72:75]
	v_mfma_f32_16x16x32_bf16 v[68:71], v[160:163], v[210:213], v[68:71]
	v_mfma_f32_16x16x32_bf16 v[64:67], v[168:171], v[210:213], v[64:67]
	s_setprio 0
	s_barrier
	s_add_i32 s16, s48, s29
	v_lshl_add_u64 v[214:215], s[20:21], 0, v[196:197]
	s_mov_b32 m0, s16
	ds_read_b128 v[172:175], v143 offset:16384
	ds_read_b128 v[176:179], v143 offset:17408
	ds_read_b128 v[180:183], v143 offset:18432
	ds_read_b128 v[184:187], v143 offset:19456
	ds_read_b128 v[188:191], v143 offset:20480
	ds_read_b128 v[192:195], v143 offset:21504
	ds_read_b128 v[206:209], v143 offset:22528
	ds_read_b128 v[210:213], v143 offset:23552
	global_load_lds_dwordx4 v[214:215], off
	s_add_i32 m0, s16, 0x2000
	s_add_u32 s16, s20, 0x18000
	v_lshl_add_u64 v[216:217], s[20:21], 0, v[132:133]
	s_addc_u32 s17, s21, 0
	s_add_i32 s48, s49, s29
	global_load_lds_dwordx4 v[216:217], off
	s_mov_b32 m0, s48
	v_lshl_add_u64 v[220:221], s[22:23], 0, v[130:131]
	global_load_lds_dwordx4 v196, s[16:17]
	s_add_i32 m0, s48, 0x2000
	s_nop 0
	global_load_lds_dwordx4 v132, s[16:17]
	v_lshl_add_u64 v[218:219], s[22:23], 0, v[128:129]
	s_mov_b32 m0, s30
	s_nop 0
	global_load_lds_dwordx4 v[218:219], off
	s_mov_b32 m0, s31
	s_nop 0
	global_load_lds_dwordx4 v[220:221], off
	s_waitcnt vmcnt(8)
	s_waitcnt lgkmcnt(0)
	s_barrier
; #define PG8_STAGE(bufoff, gbase, voff) do { _Pragma("unroll") for (int _i = 0; _i < 2; ++_i) \
;         __builtin_amdgcn_global_load_lds((const unsigned*)((const char*)(gbase) + (voff)[_i]), (PG8_LAS unsigned*)(lds + (bufoff) + ldsw + _i * 8192), 16, 0, 0); } while (0)
; #define PG8_LDA(dst, b, h) do { _Pragma("unroll") for (int m = 0; m < 4; ++m) _Pragma("unroll") for (int k = 0; k < 2; ++k) dst[m][k] = *(const PG8_LAS bf16x8*)(lds + PG8_SA(b, h) + aoff + m * 2048 + k * 1024); } while (0)
; #define PG8_LDB(dst, b, h) do { _Pragma("unroll") for (int n = 0; n < 2; ++n) _Pragma("unroll") for (int k = 0; k < 2; ++k) dst[n][k] = *(const PG8_LAS bf16x8*)(lds + PG8_SB(b, h) + boff + n * 2048 + k * 1024); } while (0)
; #define PG8_MMA(ai, bj, At, Bt) do { __builtin_amdgcn_s_setprio(1); _Pragma("unroll") for (int m = 0; m < 4; ++m) _Pragma("unroll") for (int n = 0; n < 2; ++n) _Pragma("unroll") for (int k = 0; k < 2; ++k) \
;         acc[ai][bj][m][n] = __builtin_amdgcn_mfma_f32_16x16x32_bf16(Bt[n][k], At[m][k], acc[ai][bj][m][n], 0, 0, 0); __builtin_amdgcn_s_setprio(0); } while (0)
; #define PG8_WAIT_V(n) asm volatile("s_waitcnt vmcnt(" #n ")" ::: "memory")
; #define PG8_WAIT_L(n) asm volatile("s_waitcnt lgkmcnt(" #n ")" ::: "memory")
; #define PG8_BAR __builtin_amdgcn_s_barrier()
; #define PG8_SCHED __builtin_amdgcn_sched_barrier(0)
; template <class Epi, class Sched, bool ALIGN_EPI = false, bool SP2 = false>
; __device__ __forceinline__ void gemm_phase(PG8_LAS unsigned char* lds, const Gemm g, const Sched& S, const Epi& E, int wave_s_) {
;     ...
;             PG8_WAIT_V(8); PG8_WAIT_L(0); PG8_BAR; PG8_MMA(1, 0, At, B0); PG8_MMA(1, 1, At, B1); PG8_BAR; PG8_SCHED;
;             PG8_LDB(B0, 1, 0); PG8_LDB(B1, 1, 1); PG8_SCHED; PG8_LDA(At, 1, 0); PG8_STAGE(PG8_SA(0, 1), a2 + hstep, voffA);
;             PG8_WAIT_V(8); PG8_WAIT_L(0); PG8_BAR; PG8_MMA(0, 0, At, B0); PG8_MMA(0, 1, At, B1); PG8_BAR; PG8_SCHED;
	s_setprio 1
	s_waitcnt lgkmcnt(0)
	v_mfma_f32_16x16x32_bf16 v[60:63], v[138:141], v[172:175], v[60:63]
	v_mfma_f32_16x16x32_bf16 v[56:59], v[148:151], v[172:175], v[56:59]
	v_mfma_f32_16x16x32_bf16 v[52:55], v[138:141], v[180:183], v[52:55]
	v_mfma_f32_16x16x32_bf16 v[44:47], v[148:151], v[180:183], v[44:47]
	v_mfma_f32_16x16x32_bf16 v[36:39], v[138:141], v[188:191], v[36:39]
	v_mfma_f32_16x16x32_bf16 v[28:31], v[148:151], v[188:191], v[28:31]
	v_mfma_f32_16x16x32_bf16 v[20:23], v[138:141], v[206:209], v[20:23]
	v_mfma_f32_16x16x32_bf16 v[12:15], v[148:151], v[206:209], v[12:15]
	v_mfma_f32_16x16x32_bf16 v[60:63], v[144:147], v[176:179], v[60:63]
	v_mfma_f32_16x16x32_bf16 v[56:59], v[152:155], v[176:179], v[56:59]
	v_mfma_f32_16x16x32_bf16 v[52:55], v[144:147], v[184:187], v[52:55]
	v_mfma_f32_16x16x32_bf16 v[44:47], v[152:155], v[184:187], v[44:47]
	v_mfma_f32_16x16x32_bf16 v[36:39], v[144:147], v[192:195], v[36:39]
	v_mfma_f32_16x16x32_bf16 v[28:31], v[152:155], v[192:195], v[28:31]
	v_mfma_f32_16x16x32_bf16 v[20:23], v[144:147], v[210:213], v[20:23]
	v_mfma_f32_16x16x32_bf16 v[12:15], v[152:155], v[210:213], v[12:15]
	s_setprio 0
	s_setprio 1
	v_mfma_f32_16x16x32_bf16 v[48:51], v[156:159], v[172:175], v[48:51]
	v_mfma_f32_16x16x32_bf16 v[40:43], v[164:167], v[172:175], v[40:43]
	v_mfma_f32_16x16x32_bf16 v[32:35], v[156:159], v[180:183], v[32:35]
	v_mfma_f32_16x16x32_bf16 v[24:27], v[164:167], v[180:183], v[24:27]
	v_mfma_f32_16x16x32_bf16 v[16:19], v[156:159], v[188:191], v[16:19]
	v_mfma_f32_16x16x32_bf16 v[8:11], v[164:167], v[188:191], v[8:11]
	v_mfma_f32_16x16x32_bf16 v[4:7], v[156:159], v[206:209], v[4:7]
	v_mfma_f32_16x16x32_bf16 v[0:3], v[164:167], v[206:209], v[0:3]
	v_mfma_f32_16x16x32_bf16 v[48:51], v[160:163], v[176:179], v[48:51]
	v_mfma_f32_16x16x32_bf16 v[40:43], v[168:171], v[176:179], v[40:43]
	v_mfma_f32_16x16x32_bf16 v[32:35], v[160:163], v[184:187], v[32:35]
	v_mfma_f32_16x16x32_bf16 v[24:27], v[168:171], v[184:187], v[24:27]
	v_mfma_f32_16x16x32_bf16 v[16:19], v[160:163], v[192:195], v[16:19]
	v_mfma_f32_16x16x32_bf16 v[8:11], v[168:171], v[192:195], v[8:11]
	v_mfma_f32_16x16x32_bf16 v[4:7], v[160:163], v[210:213], v[4:7]
	v_mfma_f32_16x16x32_bf16 v[0:3], v[168:171], v[210:213], v[0:3]
	s_setprio 0
	s_barrier
	s_add_i32 s48, 0, 0x18000
	s_add_i32 s49, 0, 0x1c000
	v_add_u32_e32 v152, s48, v142
	v_add_u32_e32 v168, s49, v142
	ds_read_b128 v[138:141], v152
	ds_read_b128 v[144:147], v152 offset:1024
	ds_read_b128 v[148:151], v152 offset:2048
	ds_read_b128 v[152:155], v152 offset:3072
	ds_read_b128 v[156:159], v168
	ds_read_b128 v[160:163], v168 offset:1024
	ds_read_b128 v[164:167], v168 offset:2048
	ds_read_b128 v[168:171], v168 offset:3072
	s_add_u32 s16, s22, 0x18000
	s_addc_u32 s17, s23, 0
	s_mov_b32 m0, s33
	ds_read_b128 v[172:175], v143 offset:32768
	ds_read_b128 v[176:179], v143 offset:33792
	ds_read_b128 v[180:183], v143 offset:34816
	ds_read_b128 v[184:187], v143 offset:35840
	ds_read_b128 v[188:191], v143 offset:36864
	ds_read_b128 v[192:195], v143 offset:37888
	ds_read_b128 v[206:209], v143 offset:38912
	ds_read_b128 v[210:213], v143 offset:39936
	global_load_lds_dwordx4 v128, s[16:17]
	s_mov_b32 m0, s34
	s_nop 0
	global_load_lds_dwordx4 v130, s[16:17]
	s_waitcnt vmcnt(8)
	s_waitcnt lgkmcnt(0)
	s_barrier
	s_setprio 1
	s_waitcnt lgkmcnt(0)
	v_mfma_f32_16x16x32_bf16 v[124:127], v[138:141], v[172:175], v[124:127]
	v_mfma_f32_16x16x32_bf16 v[120:123], v[148:151], v[172:175], v[120:123]
	v_mfma_f32_16x16x32_bf16 v[116:119], v[138:141], v[180:183], v[116:119]
	v_mfma_f32_16x16x32_bf16 v[108:111], v[148:151], v[180:183], v[108:111]
	v_mfma_f32_16x16x32_bf16 v[100:103], v[138:141], v[188:191], v[100:103]
	v_mfma_f32_16x16x32_bf16 v[92:95], v[148:151], v[188:191], v[92:95]
	v_mfma_f32_16x16x32_bf16 v[84:87], v[138:141], v[206:209], v[84:87]
	v_mfma_f32_16x16x32_bf16 v[76:79], v[148:151], v[206:209], v[76:79]
	v_mfma_f32_16x16x32_bf16 v[124:127], v[144:147], v[176:179], v[124:127]
	v_mfma_f32_16x16x32_bf16 v[120:123], v[152:155], v[176:179], v[120:123]
	v_mfma_f32_16x16x32_bf16 v[116:119], v[144:147], v[184:187], v[116:119]
	v_mfma_f32_16x16x32_bf16 v[108:111], v[152:155], v[184:187], v[108:111]
	v_mfma_f32_16x16x32_bf16 v[100:103], v[144:147], v[192:195], v[100:103]
	v_mfma_f32_16x16x32_bf16 v[92:95], v[152:155], v[192:195], v[92:95]
	v_mfma_f32_16x16x32_bf16 v[84:87], v[144:147], v[210:213], v[84:87]
	v_mfma_f32_16x16x32_bf16 v[76:79], v[152:155], v[210:213], v[76:79]
	s_setprio 0
	s_setprio 1
	v_mfma_f32_16x16x32_bf16 v[112:115], v[156:159], v[172:175], v[112:115]
	v_mfma_f32_16x16x32_bf16 v[104:107], v[164:167], v[172:175], v[104:107]
	v_mfma_f32_16x16x32_bf16 v[96:99], v[156:159], v[180:183], v[96:99]
	v_mfma_f32_16x16x32_bf16 v[88:91], v[164:167], v[180:183], v[88:91]
	v_mfma_f32_16x16x32_bf16 v[80:83], v[156:159], v[188:191], v[80:83]
	v_mfma_f32_16x16x32_bf16 v[72:75], v[164:167], v[188:191], v[72:75]
	v_mfma_f32_16x16x32_bf16 v[68:71], v[156:159], v[206:209], v[68:71]
	v_mfma_f32_16x16x32_bf16 v[64:67], v[164:167], v[206:209], v[64:67]
	v_mfma_f32_16x16x32_bf16 v[112:115], v[160:163], v[176:179], v[112:115]
	v_mfma_f32_16x16x32_bf16 v[104:107], v[168:171], v[176:179], v[104:107]
	v_mfma_f32_16x16x32_bf16 v[96:99], v[160:163], v[184:187], v[96:99]
	v_mfma_f32_16x16x32_bf16 v[88:91], v[168:171], v[184:187], v[88:91]
	v_mfma_f32_16x16x32_bf16 v[80:83], v[160:163], v[192:195], v[80:83]
	v_mfma_f32_16x16x32_bf16 v[72:75], v[168:171], v[192:195], v[72:75]
	v_mfma_f32_16x16x32_bf16 v[68:71], v[160:163], v[210:213], v[68:71]
	v_mfma_f32_16x16x32_bf16 v[64:67], v[168:171], v[210:213], v[64:67]
	s_setprio 0
	s_barrier
; #define PG8_STAGE(bufoff, gbase, voff) do { _Pragma("unroll") for (int _i = 0; _i < 2; ++_i) \
;         __builtin_amdgcn_global_load_lds((const unsigned*)((const char*)(gbase) + (voff)[_i]), (PG8_LAS unsigned*)(lds + (bufoff) + ldsw + _i * 8192), 16, 0, 0); } while (0)
; #define PG8_LDA(dst, b, h) do { _Pragma("unroll") for (int m = 0; m < 4; ++m) _Pragma("unroll") for (int k = 0; k < 2; ++k) dst[m][k] = *(const PG8_LAS bf16x8*)(lds + PG8_SA(b, h) + aoff + m * 2048 + k * 1024); } while (0)
; #define PG8_MMA(ai, bj, At, Bt) do { __builtin_amdgcn_s_setprio(1); _Pragma("unroll") for (int m = 0; m < 4; ++m) _Pragma("unroll") for (int n = 0; n < 2; ++n) _Pragma("unroll") for (int k = 0; k < 2; ++k) \
;         acc[ai][bj][m][n] = __builtin_amdgcn_mfma_f32_16x16x32_bf16(Bt[n][k], At[m][k], acc[ai][bj][m][n], 0, 0, 0); __builtin_amdgcn_s_setprio(0); } while (0)
; #define PG8_WAIT_V(n) asm volatile("s_waitcnt vmcnt(" #n ")" ::: "memory")
; #define PG8_WAIT_L(n) asm volatile("s_waitcnt lgkmcnt(" #n ")" ::: "memory")
; #define PG8_BAR __builtin_amdgcn_s_barrier()
; #define PG8_SCHED __builtin_amdgcn_sched_barrier(0)
; template <class Epi, class Sched, bool ALIGN_EPI = false, bool SP2 = false>
; __device__ __forceinline__ void gemm_phase(PG8_LAS unsigned char* lds, const Gemm g, const Sched& S, const Epi& E, int wave_s_) {
;     ...
;             PG8_WAIT_V(8); PG8_WAIT_L(0); PG8_BAR; PG8_MMA(0, 0, At, B0); PG8_MMA(0, 1, At, B1); PG8_BAR; PG8_SCHED;
;             PG8_LDA(At, 1, 1); PG8_STAGE(PG8_SB(1, 0), b3, voffB); PG8_STAGE(PG8_SB(1, 1), b3 + hstep, voffB); PG8_STAGE(PG8_SA(1, 0), a3, voffA);
;             PG8_WAIT_V(8); PG8_WAIT_L(0); PG8_BAR; PG8_MMA(1, 0, At, B0); PG8_MMA(1, 1, At, B1); PG8_BAR; PG8_SCHED;
	s_add_i32 s16, s48, s29
	v_lshl_add_u64 v[214:215], v[214:215], 0, s[76:77]
	s_mov_b32 m0, s16
	ds_read_b128 v[172:175], v143 offset:49152
	ds_read_b128 v[176:179], v143 offset:50176
	ds_read_b128 v[180:183], v143 offset:51200
	ds_read_b128 v[184:187], v143 offset:52224
	ds_read_b128 v[188:191], v143 offset:53248
	ds_read_b128 v[192:195], v143 offset:54272
	ds_read_b128 v[206:209], v143 offset:55296
	ds_read_b128 v[210:213], v143 offset:56320
	global_load_lds_dwordx4 v[214:215], off
	s_add_i32 m0, s16, 0x2000
	s_add_u32 s16, s20, 0x18080
	v_lshl_add_u64 v[214:215], v[216:217], 0, s[76:77]
	s_addc_u32 s17, s21, 0
	s_add_i32 s20, s49, s29
	global_load_lds_dwordx4 v[214:215], off
	s_mov_b32 m0, s20
	s_nop 0
	global_load_lds_dwordx4 v196, s[16:17]
	s_add_i32 m0, s20, 0x2000
	s_nop 0
	global_load_lds_dwordx4 v132, s[16:17]
	v_lshl_add_u64 v[214:215], v[218:219], 0, s[76:77]
	s_mov_b32 m0, s37
	s_nop 0
	global_load_lds_dwordx4 v[214:215], off
	v_lshl_add_u64 v[214:215], v[220:221], 0, s[76:77]
	s_mov_b32 m0, s38
	s_nop 0
	global_load_lds_dwordx4 v[214:215], off
	s_waitcnt vmcnt(8)
	s_waitcnt lgkmcnt(0)
	s_barrier
	s_setprio 1
	s_waitcnt lgkmcnt(0)
	v_mfma_f32_16x16x32_bf16 v[60:63], v[138:141], v[172:175], v[60:63]
	v_mfma_f32_16x16x32_bf16 v[56:59], v[148:151], v[172:175], v[56:59]
	v_mfma_f32_16x16x32_bf16 v[52:55], v[138:141], v[180:183], v[52:55]
	v_mfma_f32_16x16x32_bf16 v[44:47], v[148:151], v[180:183], v[44:47]
	v_mfma_f32_16x16x32_bf16 v[36:39], v[138:141], v[188:191], v[36:39]
	v_mfma_f32_16x16x32_bf16 v[28:31], v[148:151], v[188:191], v[28:31]
	v_mfma_f32_16x16x32_bf16 v[20:23], v[138:141], v[206:209], v[20:23]
	v_mfma_f32_16x16x32_bf16 v[12:15], v[148:151], v[206:209], v[12:15]
	v_mfma_f32_16x16x32_bf16 v[60:63], v[144:147], v[176:179], v[60:63]
	v_mfma_f32_16x16x32_bf16 v[56:59], v[152:155], v[176:179], v[56:59]
	v_mfma_f32_16x16x32_bf16 v[52:55], v[144:147], v[184:187], v[52:55]
	v_mfma_f32_16x16x32_bf16 v[44:47], v[152:155], v[184:187], v[44:47]
	v_mfma_f32_16x16x32_bf16 v[36:39], v[144:147], v[192:195], v[36:39]
	v_mfma_f32_16x16x32_bf16 v[28:31], v[152:155], v[192:195], v[28:31]
	v_mfma_f32_16x16x32_bf16 v[20:23], v[144:147], v[210:213], v[20:23]
	v_mfma_f32_16x16x32_bf16 v[12:15], v[152:155], v[210:213], v[12:15]
	s_setprio 0
	s_setprio 1
	v_mfma_f32_16x16x32_bf16 v[48:51], v[156:159], v[172:175], v[48:51]
	v_mfma_f32_16x16x32_bf16 v[40:43], v[164:167], v[172:175], v[40:43]
	v_mfma_f32_16x16x32_bf16 v[32:35], v[156:159], v[180:183], v[32:35]
	v_mfma_f32_16x16x32_bf16 v[24:27], v[164:167], v[180:183], v[24:27]
	v_mfma_f32_16x16x32_bf16 v[16:19], v[156:159], v[188:191], v[16:19]
	v_mfma_f32_16x16x32_bf16 v[8:11], v[164:167], v[188:191], v[8:11]
	v_mfma_f32_16x16x32_bf16 v[4:7], v[156:159], v[206:209], v[4:7]
	v_mfma_f32_16x16x32_bf16 v[0:3], v[164:167], v[206:209], v[0:3]
	v_mfma_f32_16x16x32_bf16 v[48:51], v[160:163], v[176:179], v[48:51]
	v_mfma_f32_16x16x32_bf16 v[40:43], v[168:171], v[176:179], v[40:43]
	v_mfma_f32_16x16x32_bf16 v[32:35], v[160:163], v[184:187], v[32:35]
	v_mfma_f32_16x16x32_bf16 v[24:27], v[168:171], v[184:187], v[24:27]
	v_mfma_f32_16x16x32_bf16 v[16:19], v[160:163], v[192:195], v[16:19]
	v_mfma_f32_16x16x32_bf16 v[8:11], v[168:171], v[192:195], v[8:11]
	v_mfma_f32_16x16x32_bf16 v[4:7], v[160:163], v[210:213], v[4:7]
	v_mfma_f32_16x16x32_bf16 v[0:3], v[168:171], v[210:213], v[0:3]
	s_setprio 0
	s_barrier
	s_add_i32 s47, s47, 2
	s_add_u32 s45, s45, 0x100
	s_addc_u32 s46, s46, 0
	s_cmp_gt_u32 s47, 3
	s_mov_b64 s[16:17], s[18:19]
	s_cbranch_scc0 .LBB0_1338
	s_and_b64 vcc, exec, s[12:13]
	s_cbranch_vccz .LBB0_1341
	s_barrier

;     __device__ __forceinline__ int nt_of(const Unit& u) const { return (u.pm >> 12) ? ktper : kt; }
; #define PG8_STAGE(bufoff, gbase, voff) do { _Pragma("unroll") for (int _i = 0; _i < 2; ++_i) \
;         __builtin_amdgcn_global_load_lds((const unsigned*)((const char*)(gbase) + (voff)[_i]), (PG8_LAS unsigned*)(lds + (bufoff) + ldsw + _i * 8192), 16, 0, 0); } while (0)
; #define PG8_LDA(dst, b, h) do { _Pragma("unroll") for (int m = 0; m < 4; ++m) _Pragma("unroll") for (int k = 0; k < 2; ++k) dst[m][k] = *(const PG8_LAS bf16x8*)(lds + PG8_SA(b, h) + aoff + m * 2048 + k * 1024); } while (0)
; #define PG8_LDB(dst, b, h) do { _Pragma("unroll") for (int n = 0; n < 2; ++n) _Pragma("unroll") for (int k = 0; k < 2; ++k) dst[n][k] = *(const PG8_LAS bf16x8*)(lds + PG8_SB(b, h) + boff + n * 2048 + k * 1024); } while (0)
; #define PG8_WAIT_V(n) asm volatile("s_waitcnt vmcnt(" #n ")" ::: "memory")
; #define PG8_WAIT_L(n) asm volatile("s_waitcnt lgkmcnt(" #n ")" ::: "memory")
; #define PG8_BAR __builtin_amdgcn_s_barrier()
; template <class Epi, class Sched, bool ALIGN_EPI = false, bool SP2 = false>
; __device__ __forceinline__ void gemm_phase(PG8_LAS unsigned char* lds, const Gemm g, const Sched& S, const Epi& E, int wave_s_) {
;     ...
;         const char* nA = has_next ? (const char*)g.A + (size_t)(nxt.pm & 4095) * tstep + (size_t)S.k0_of(nxt) * kstep : cA; const char* nB = has_next ? (const char*)g.Bt + (size_t)nxt.pn * tstep + (size_t)S.k0_of(nxt) * kstep : cB;
;         const int nt = S.nt_of(cur);
;         for (int t = 0; t < nt; t += 2) {
;             const bool last = (t == nt - 2);
;             const char* a1 = cA + (size_t)(t + 1) * kstep;
;             const char* a2 = last ? nA : cA + (size_t)(t + 2) * kstep; const char* b2 = last ? nB : cB + (size_t)(t + 2) * kstep;
;             const char* a3 = a2 + kstep; const char* b3 = b2 + kstep;
;             if (last && has_next) S.a_ready(nxt);
;             if constexpr (SP2) {
;             PG8_LDB(B0, 0, 0); PG8_LDB(B1, 0, 1); PG8_SCHED; PG8_LDA(At, 0, 0); PG8_STAGE(PG8_SA(1, 1), a1 + hstep, voffA);
;             PG8_WAIT_V(8); PG8_WAIT_L(0); PG8_BAR; PG8_MMA(0, 0, At, B0); PG8_MMA(0, 1, At, B1); PG8_BAR; PG8_SCHED;
;             PG8_LDA(At, 0, 1); PG8_STAGE(PG8_SB(0, 0), b2, voffB); PG8_STAGE(PG8_SB(0, 1), b2 + hstep, voffB); PG8_STAGE(PG8_SA(0, 0), a2, voffA);
.LBB0_1358:
	s_add_u32 s30, s18, s13
	s_addc_u32 s31, s19, 0
	s_add_u32 s26, s30, 0x100
	s_addc_u32 s27, s31, 0
	s_and_b64 s[24:25], s[22:23], exec
	s_cselect_b32 s27, s7, s27
	s_cselect_b32 s26, s6, s26
	s_add_u32 s13, s16, s13
	s_addc_u32 s24, s17, 0
	s_add_u32 s13, s13, 0x100
	s_addc_u32 s24, s24, 0
	s_add_i32 s62, 0, 0x10000
	s_and_b64 s[22:23], s[22:23], exec
	s_cselect_b32 s29, s15, s24
	s_cselect_b32 s28, s14, s13
	s_add_i32 s23, 0, 0x14000
	s_add_u32 s34, s30, 0x10080
	s_addc_u32 s35, s31, 0
	s_add_i32 s61, s62, s39
	s_add_i32 m0, s41, 0xc000
	s_add_i32 s64, s41, 0xe000
	s_add_i32 s58, s61, 0x2000
	s_add_u32 s30, s28, 0x10000
	v_add_u32_e32 v150, s62, v136
	v_add_u32_e32 v166, s23, v136
	s_addc_u32 s31, s29, 0
	s_add_i32 s60, s23, s39
	ds_read_b128 v[138:141], v150
	ds_read_b128 v[142:145], v150 offset:1024
	ds_read_b128 v[146:149], v150 offset:2048
	ds_read_b128 v[150:153], v150 offset:3072
	ds_read_b128 v[154:157], v166
	ds_read_b128 v[158:161], v166 offset:1024
	ds_read_b128 v[162:165], v166 offset:2048
	ds_read_b128 v[166:169], v166 offset:3072
	s_add_i32 s59, s60, 0x2000
	s_add_i32 s57, 0, 0x18000
	s_add_i32 s56, 0, 0x1c000
	s_add_u32 s24, s26, 0x10000
	s_addc_u32 s25, s27, 0
	s_add_i32 s55, s57, s39
	s_add_i32 s13, s55, 0x2000
	s_add_u32 s22, s28, 0x10080
	s_addc_u32 s23, s29, 0
	s_add_i32 s63, s56, s39
	s_add_i32 s62, s63, 0x2000
	ds_read_b128 v[170:173], v137
	ds_read_b128 v[174:177], v137 offset:1024
	ds_read_b128 v[178:181], v137 offset:2048
	ds_read_b128 v[182:185], v137 offset:3072
	ds_read_b128 v[186:189], v137 offset:4096
	ds_read_b128 v[190:193], v137 offset:5120
	ds_read_b128 v[206:209], v137 offset:6144
	ds_read_b128 v[210:213], v137 offset:7168
	global_load_lds_dwordx4 v134, s[34:35]
	s_mov_b32 m0, s64
	s_nop 0
	global_load_lds_dwordx4 v130, s[34:35]
	s_waitcnt vmcnt(8)
	s_waitcnt lgkmcnt(0)
	s_barrier
	s_setprio 1
	s_waitcnt lgkmcnt(0)
	v_mfma_f32_16x16x32_bf16 v[124:127], v[138:141], v[170:173], v[124:127]
	v_mfma_f32_16x16x32_bf16 v[120:123], v[146:149], v[170:173], v[120:123]
	v_mfma_f32_16x16x32_bf16 v[116:119], v[138:141], v[178:181], v[116:119]
	v_mfma_f32_16x16x32_bf16 v[112:115], v[146:149], v[178:181], v[112:115]
	v_mfma_f32_16x16x32_bf16 v[108:111], v[138:141], v[186:189], v[108:111]
	v_mfma_f32_16x16x32_bf16 v[104:107], v[146:149], v[186:189], v[104:107]
	v_mfma_f32_16x16x32_bf16 v[100:103], v[138:141], v[206:209], v[100:103]
	v_mfma_f32_16x16x32_bf16 v[96:99], v[146:149], v[206:209], v[96:99]
	v_mfma_f32_16x16x32_bf16 v[124:127], v[142:145], v[174:177], v[124:127]
	v_mfma_f32_16x16x32_bf16 v[120:123], v[150:153], v[174:177], v[120:123]
	v_mfma_f32_16x16x32_bf16 v[116:119], v[142:145], v[182:185], v[116:119]
	v_mfma_f32_16x16x32_bf16 v[112:115], v[150:153], v[182:185], v[112:115]
	v_mfma_f32_16x16x32_bf16 v[108:111], v[142:145], v[190:193], v[108:111]
	v_mfma_f32_16x16x32_bf16 v[104:107], v[150:153], v[190:193], v[104:107]
	v_mfma_f32_16x16x32_bf16 v[100:103], v[142:145], v[210:213], v[100:103]
	v_mfma_f32_16x16x32_bf16 v[96:99], v[150:153], v[210:213], v[96:99]
	s_setprio 0
	s_setprio 1
	v_mfma_f32_16x16x32_bf16 v[76:79], v[154:157], v[170:173], v[76:79]
	v_mfma_f32_16x16x32_bf16 v[68:71], v[162:165], v[170:173], v[68:71]
	v_mfma_f32_16x16x32_bf16 v[60:63], v[154:157], v[178:181], v[60:63]
	v_mfma_f32_16x16x32_bf16 v[52:55], v[162:165], v[178:181], v[52:55]
	v_mfma_f32_16x16x32_bf16 v[44:47], v[154:157], v[186:189], v[44:47]
	v_mfma_f32_16x16x32_bf16 v[40:43], v[162:165], v[186:189], v[40:43]
	v_mfma_f32_16x16x32_bf16 v[36:39], v[154:157], v[206:209], v[36:39]
	v_mfma_f32_16x16x32_bf16 v[32:35], v[162:165], v[206:209], v[32:35]
	v_mfma_f32_16x16x32_bf16 v[76:79], v[158:161], v[174:177], v[76:79]
	v_mfma_f32_16x16x32_bf16 v[68:71], v[166:169], v[174:177], v[68:71]
	v_mfma_f32_16x16x32_bf16 v[60:63], v[158:161], v[182:185], v[60:63]
	v_mfma_f32_16x16x32_bf16 v[52:55], v[166:169], v[182:185], v[52:55]
	v_mfma_f32_16x16x32_bf16 v[44:47], v[158:161], v[190:193], v[44:47]
	v_mfma_f32_16x16x32_bf16 v[40:43], v[166:169], v[190:193], v[40:43]
	v_mfma_f32_16x16x32_bf16 v[36:39], v[158:161], v[210:213], v[36:39]
	v_mfma_f32_16x16x32_bf16 v[32:35], v[166:169], v[210:213], v[32:35]
	s_setprio 0
	s_barrier
	s_mov_b32 m0, s61
	v_lshl_add_u64 v[194:195], s[28:29], 0, v[132:133]
	ds_read_b128 v[170:173], v137 offset:16384
	ds_read_b128 v[174:177], v137 offset:17408
	ds_read_b128 v[178:181], v137 offset:18432
	ds_read_b128 v[182:185], v137 offset:19456
	ds_read_b128 v[186:189], v137 offset:20480
	ds_read_b128 v[190:193], v137 offset:21504
	ds_read_b128 v[206:209], v137 offset:22528
	ds_read_b128 v[210:213], v137 offset:23552
	global_load_lds_dwordx4 v[194:195], off
	v_lshl_add_u64 v[214:215], s[28:29], 0, v[128:129]
	s_mov_b32 m0, s58
	s_nop 0
	global_load_lds_dwordx4 v[214:215], off
	s_mov_b32 m0, s60
	v_lshl_add_u64 v[218:219], s[26:27], 0, v[130:131]
	global_load_lds_dwordx4 v132, s[30:31]
	s_mov_b32 m0, s59
	s_nop 0
	global_load_lds_dwordx4 v128, s[30:31]
	v_lshl_add_u64 v[216:217], s[26:27], 0, v[134:135]
	s_mov_b32 m0, s41
	s_nop 0
	global_load_lds_dwordx4 v[216:217], off
	s_mov_b32 m0, s42
	s_nop 0
	global_load_lds_dwordx4 v[218:219], off
	s_waitcnt vmcnt(8)
	s_waitcnt lgkmcnt(0)
	s_barrier
; #define PG8_STAGE(bufoff, gbase, voff) do { _Pragma("unroll") for (int _i = 0; _i < 2; ++_i) \
;         __builtin_amdgcn_global_load_lds((const unsigned*)((const char*)(gbase) + (voff)[_i]), (PG8_LAS unsigned*)(lds + (bufoff) + ldsw + _i * 8192), 16, 0, 0); } while (0)
; #define PG8_LDA(dst, b, h) do { _Pragma("unroll") for (int m = 0; m < 4; ++m) _Pragma("unroll") for (int k = 0; k < 2; ++k) dst[m][k] = *(const PG8_LAS bf16x8*)(lds + PG8_SA(b, h) + aoff + m * 2048 + k * 1024); } while (0)
; #define PG8_LDB(dst, b, h) do { _Pragma("unroll") for (int n = 0; n < 2; ++n) _Pragma("unroll") for (int k = 0; k < 2; ++k) dst[n][k] = *(const PG8_LAS bf16x8*)(lds + PG8_SB(b, h) + boff + n * 2048 + k * 1024); } while (0)
; #define PG8_MMA(ai, bj, At, Bt) do { __builtin_amdgcn_s_setprio(1); _Pragma("unroll") for (int m = 0; m < 4; ++m) _Pragma("unroll") for (int n = 0; n < 2; ++n) _Pragma("unroll") for (int k = 0; k < 2; ++k) \
;         acc[ai][bj][m][n] = __builtin_amdgcn_mfma_f32_16x16x32_bf16(Bt[n][k], At[m][k], acc[ai][bj][m][n], 0, 0, 0); __builtin_amdgcn_s_setprio(0); } while (0)
; #define PG8_WAIT_V(n) asm volatile("s_waitcnt vmcnt(" #n ")" ::: "memory")
; #define PG8_WAIT_L(n) asm volatile("s_waitcnt lgkmcnt(" #n ")" ::: "memory")
; #define PG8_BAR __builtin_amdgcn_s_barrier()
; #define PG8_SCHED __builtin_amdgcn_sched_barrier(0)
; template <class Epi, class Sched, bool ALIGN_EPI = false, bool SP2 = false>
; __device__ __forceinline__ void gemm_phase(PG8_LAS unsigned char* lds, const Gemm g, const Sched& S, const Epi& E, int wave_s_) {
;     ...
;             PG8_WAIT_V(8); PG8_WAIT_L(0); PG8_BAR; PG8_MMA(0, 0, At, B0); PG8_MMA(0, 1, At, B1); PG8_BAR; PG8_SCHED;
;             PG8_LDA(At, 0, 1); PG8_STAGE(PG8_SB(0, 0), b2, voffB); PG8_STAGE(PG8_SB(0, 1), b2 + hstep, voffB); PG8_STAGE(PG8_SA(0, 0), a2, voffA);
;             PG8_WAIT_V(8); PG8_WAIT_L(0); PG8_BAR; PG8_MMA(1, 0, At, B0); PG8_MMA(1, 1, At, B1); PG8_BAR; PG8_SCHED;
;             PG8_LDB(B0, 1, 0); PG8_LDB(B1, 1, 1); PG8_SCHED; PG8_LDA(At, 1, 0); PG8_STAGE(PG8_SA(0, 1), a2 + hstep, voffA);
;             PG8_WAIT_V(8); PG8_WAIT_L(0); PG8_BAR; PG8_MMA(0, 0, At, B0); PG8_MMA(0, 1, At, B1); PG8_BAR; PG8_SCHED;
	s_setprio 1
	s_waitcnt lgkmcnt(0)
	v_mfma_f32_16x16x32_bf16 v[92:95], v[138:141], v[170:173], v[92:95]
	v_mfma_f32_16x16x32_bf16 v[88:91], v[146:149], v[170:173], v[88:91]
	v_mfma_f32_16x16x32_bf16 v[84:87], v[138:141], v[178:181], v[84:87]
	v_mfma_f32_16x16x32_bf16 v[80:83], v[146:149], v[178:181], v[80:83]
	v_mfma_f32_16x16x32_bf16 v[72:75], v[138:141], v[186:189], v[72:75]
	v_mfma_f32_16x16x32_bf16 v[64:67], v[146:149], v[186:189], v[64:67]
	v_mfma_f32_16x16x32_bf16 v[56:59], v[138:141], v[206:209], v[56:59]
	v_mfma_f32_16x16x32_bf16 v[48:51], v[146:149], v[206:209], v[48:51]
	v_mfma_f32_16x16x32_bf16 v[92:95], v[142:145], v[174:177], v[92:95]
	v_mfma_f32_16x16x32_bf16 v[88:91], v[150:153], v[174:177], v[88:91]
	v_mfma_f32_16x16x32_bf16 v[84:87], v[142:145], v[182:185], v[84:87]
	v_mfma_f32_16x16x32_bf16 v[80:83], v[150:153], v[182:185], v[80:83]
	v_mfma_f32_16x16x32_bf16 v[72:75], v[142:145], v[190:193], v[72:75]
	v_mfma_f32_16x16x32_bf16 v[64:67], v[150:153], v[190:193], v[64:67]
	v_mfma_f32_16x16x32_bf16 v[56:59], v[142:145], v[210:213], v[56:59]
	v_mfma_f32_16x16x32_bf16 v[48:51], v[150:153], v[210:213], v[48:51]
	s_setprio 0
	s_setprio 1
	v_mfma_f32_16x16x32_bf16 v[28:31], v[154:157], v[170:173], v[28:31]
	v_mfma_f32_16x16x32_bf16 v[24:27], v[162:165], v[170:173], v[24:27]
	v_mfma_f32_16x16x32_bf16 v[20:23], v[154:157], v[178:181], v[20:23]
	v_mfma_f32_16x16x32_bf16 v[16:19], v[162:165], v[178:181], v[16:19]
	v_mfma_f32_16x16x32_bf16 v[12:15], v[154:157], v[186:189], v[12:15]
	v_mfma_f32_16x16x32_bf16 v[8:11], v[162:165], v[186:189], v[8:11]
	v_mfma_f32_16x16x32_bf16 v[4:7], v[154:157], v[206:209], v[4:7]
	v_mfma_f32_16x16x32_bf16 v[0:3], v[162:165], v[206:209], v[0:3]
	v_mfma_f32_16x16x32_bf16 v[28:31], v[158:161], v[174:177], v[28:31]
	v_mfma_f32_16x16x32_bf16 v[24:27], v[166:169], v[174:177], v[24:27]
	v_mfma_f32_16x16x32_bf16 v[20:23], v[158:161], v[182:185], v[20:23]
	v_mfma_f32_16x16x32_bf16 v[16:19], v[166:169], v[182:185], v[16:19]
	v_mfma_f32_16x16x32_bf16 v[12:15], v[158:161], v[190:193], v[12:15]
	v_mfma_f32_16x16x32_bf16 v[8:11], v[166:169], v[190:193], v[8:11]
	v_mfma_f32_16x16x32_bf16 v[4:7], v[158:161], v[210:213], v[4:7]
	v_mfma_f32_16x16x32_bf16 v[0:3], v[166:169], v[210:213], v[0:3]
	s_setprio 0
	s_barrier
	v_add_u32_e32 v150, s57, v136
	v_add_u32_e32 v166, s56, v136
	ds_read_b128 v[138:141], v150
	ds_read_b128 v[142:145], v150 offset:1024
	ds_read_b128 v[146:149], v150 offset:2048
	ds_read_b128 v[150:153], v150 offset:3072
	ds_read_b128 v[154:157], v166
	ds_read_b128 v[158:161], v166 offset:1024
	ds_read_b128 v[162:165], v166 offset:2048
	ds_read_b128 v[166:169], v166 offset:3072
	s_mov_b32 m0, s43
	ds_read_b128 v[170:173], v137 offset:32768
	ds_read_b128 v[174:177], v137 offset:33792
	ds_read_b128 v[178:181], v137 offset:34816
	ds_read_b128 v[182:185], v137 offset:35840
	ds_read_b128 v[186:189], v137 offset:36864
	ds_read_b128 v[190:193], v137 offset:37888
	ds_read_b128 v[206:209], v137 offset:38912
	ds_read_b128 v[210:213], v137 offset:39936
	global_load_lds_dwordx4 v134, s[24:25]
	s_mov_b32 m0, s44
	s_nop 0
	global_load_lds_dwordx4 v130, s[24:25]
	s_waitcnt vmcnt(8)
	s_waitcnt lgkmcnt(0)
	s_barrier
	s_setprio 1
	s_waitcnt lgkmcnt(0)
	v_mfma_f32_16x16x32_bf16 v[124:127], v[138:141], v[170:173], v[124:127]
	v_mfma_f32_16x16x32_bf16 v[120:123], v[146:149], v[170:173], v[120:123]
	v_mfma_f32_16x16x32_bf16 v[116:119], v[138:141], v[178:181], v[116:119]
	v_mfma_f32_16x16x32_bf16 v[112:115], v[146:149], v[178:181], v[112:115]
	v_mfma_f32_16x16x32_bf16 v[108:111], v[138:141], v[186:189], v[108:111]
	v_mfma_f32_16x16x32_bf16 v[104:107], v[146:149], v[186:189], v[104:107]
	v_mfma_f32_16x16x32_bf16 v[100:103], v[138:141], v[206:209], v[100:103]
	v_mfma_f32_16x16x32_bf16 v[96:99], v[146:149], v[206:209], v[96:99]
	v_mfma_f32_16x16x32_bf16 v[124:127], v[142:145], v[174:177], v[124:127]
	v_mfma_f32_16x16x32_bf16 v[120:123], v[150:153], v[174:177], v[120:123]
	v_mfma_f32_16x16x32_bf16 v[116:119], v[142:145], v[182:185], v[116:119]
	v_mfma_f32_16x16x32_bf16 v[112:115], v[150:153], v[182:185], v[112:115]
	v_mfma_f32_16x16x32_bf16 v[108:111], v[142:145], v[190:193], v[108:111]
	v_mfma_f32_16x16x32_bf16 v[104:107], v[150:153], v[190:193], v[104:107]
	v_mfma_f32_16x16x32_bf16 v[100:103], v[142:145], v[210:213], v[100:103]
	v_mfma_f32_16x16x32_bf16 v[96:99], v[150:153], v[210:213], v[96:99]
	s_setprio 0
	s_setprio 1
	v_mfma_f32_16x16x32_bf16 v[76:79], v[154:157], v[170:173], v[76:79]
	v_mfma_f32_16x16x32_bf16 v[68:71], v[162:165], v[170:173], v[68:71]
	v_mfma_f32_16x16x32_bf16 v[60:63], v[154:157], v[178:181], v[60:63]
	v_mfma_f32_16x16x32_bf16 v[52:55], v[162:165], v[178:181], v[52:55]
	v_mfma_f32_16x16x32_bf16 v[44:47], v[154:157], v[186:189], v[44:47]
	v_mfma_f32_16x16x32_bf16 v[40:43], v[162:165], v[186:189], v[40:43]
	v_mfma_f32_16x16x32_bf16 v[36:39], v[154:157], v[206:209], v[36:39]
	v_mfma_f32_16x16x32_bf16 v[32:35], v[162:165], v[206:209], v[32:35]
	v_mfma_f32_16x16x32_bf16 v[76:79], v[158:161], v[174:177], v[76:79]
	v_mfma_f32_16x16x32_bf16 v[68:71], v[166:169], v[174:177], v[68:71]
	v_mfma_f32_16x16x32_bf16 v[60:63], v[158:161], v[182:185], v[60:63]
	v_mfma_f32_16x16x32_bf16 v[52:55], v[166:169], v[182:185], v[52:55]
	v_mfma_f32_16x16x32_bf16 v[44:47], v[158:161], v[190:193], v[44:47]
	v_mfma_f32_16x16x32_bf16 v[40:43], v[166:169], v[190:193], v[40:43]
	v_mfma_f32_16x16x32_bf16 v[36:39], v[158:161], v[210:213], v[36:39]
	v_mfma_f32_16x16x32_bf16 v[32:35], v[166:169], v[210:213], v[32:35]
	s_setprio 0
	s_barrier
; #define PG8_STAGE(bufoff, gbase, voff) do { _Pragma("unroll") for (int _i = 0; _i < 2; ++_i) \
;         __builtin_amdgcn_global_load_lds((const unsigned*)((const char*)(gbase) + (voff)[_i]), (PG8_LAS unsigned*)(lds + (bufoff) + ldsw + _i * 8192), 16, 0, 0); } while (0)
; #define PG8_LDA(dst, b, h) do { _Pragma("unroll") for (int m = 0; m < 4; ++m) _Pragma("unroll") for (int k = 0; k < 2; ++k) dst[m][k] = *(const PG8_LAS bf16x8*)(lds + PG8_SA(b, h) + aoff + m * 2048 + k * 1024); } while (0)
; #define PG8_MMA(ai, bj, At, Bt) do { __builtin_amdgcn_s_setprio(1); _Pragma("unroll") for (int m = 0; m < 4; ++m) _Pragma("unroll") for (int n = 0; n < 2; ++n) _Pragma("unroll") for (int k = 0; k < 2; ++k) \
;         acc[ai][bj][m][n] = __builtin_amdgcn_mfma_f32_16x16x32_bf16(Bt[n][k], At[m][k], acc[ai][bj][m][n], 0, 0, 0); __builtin_amdgcn_s_setprio(0); } while (0)
; #define PG8_WAIT_V(n) asm volatile("s_waitcnt vmcnt(" #n ")" ::: "memory")
; #define PG8_WAIT_L(n) asm volatile("s_waitcnt lgkmcnt(" #n ")" ::: "memory")
; #define PG8_BAR __builtin_amdgcn_s_barrier()
; #define PG8_SCHED __builtin_amdgcn_sched_barrier(0)
; template <class Epi, class Sched, bool ALIGN_EPI = false, bool SP2 = false>
; __device__ __forceinline__ void gemm_phase(PG8_LAS unsigned char* lds, const Gemm g, const Sched& S, const Epi& E, int wave_s_) {
;     ...
;             PG8_LDA(At, 1, 1); PG8_STAGE(PG8_SB(1, 0), b3, voffB); PG8_STAGE(PG8_SB(1, 1), b3 + hstep, voffB); PG8_STAGE(PG8_SA(1, 0), a3, voffA);
;             PG8_WAIT_V(8); PG8_WAIT_L(0); PG8_BAR; PG8_MMA(1, 0, At, B0); PG8_MMA(1, 1, At, B1); PG8_BAR; PG8_SCHED;
	s_mov_b32 m0, s55
	v_lshl_add_u64 v[194:195], v[194:195], 0, s[76:77]
	ds_read_b128 v[170:173], v137 offset:49152
	ds_read_b128 v[174:177], v137 offset:50176
	ds_read_b128 v[178:181], v137 offset:51200
	ds_read_b128 v[182:185], v137 offset:52224
	ds_read_b128 v[186:189], v137 offset:53248
	ds_read_b128 v[190:193], v137 offset:54272
	ds_read_b128 v[206:209], v137 offset:55296
	ds_read_b128 v[210:213], v137 offset:56320
	global_load_lds_dwordx4 v[194:195], off
	v_lshl_add_u64 v[194:195], v[214:215], 0, s[76:77]
	s_mov_b32 m0, s13
	s_nop 0
	global_load_lds_dwordx4 v[194:195], off
	s_mov_b32 m0, s63
	s_nop 0
	global_load_lds_dwordx4 v132, s[22:23]
	s_mov_b32 m0, s62
	s_nop 0
	global_load_lds_dwordx4 v128, s[22:23]
	v_lshl_add_u64 v[194:195], v[216:217], 0, s[76:77]
	s_mov_b32 m0, s46
	s_nop 0
	global_load_lds_dwordx4 v[194:195], off
	v_lshl_add_u64 v[194:195], v[218:219], 0, s[76:77]
	s_mov_b32 m0, s47
	s_nop 0
	global_load_lds_dwordx4 v[194:195], off
	s_waitcnt vmcnt(8)
	s_waitcnt lgkmcnt(0)
	s_barrier
	s_setprio 1
	s_waitcnt lgkmcnt(0)
	v_mfma_f32_16x16x32_bf16 v[92:95], v[138:141], v[170:173], v[92:95]
	v_mfma_f32_16x16x32_bf16 v[88:91], v[146:149], v[170:173], v[88:91]
	v_mfma_f32_16x16x32_bf16 v[84:87], v[138:141], v[178:181], v[84:87]
	v_mfma_f32_16x16x32_bf16 v[80:83], v[146:149], v[178:181], v[80:83]
	v_mfma_f32_16x16x32_bf16 v[72:75], v[138:141], v[186:189], v[72:75]
	v_mfma_f32_16x16x32_bf16 v[64:67], v[146:149], v[186:189], v[64:67]
	v_mfma_f32_16x16x32_bf16 v[56:59], v[138:141], v[206:209], v[56:59]
	v_mfma_f32_16x16x32_bf16 v[48:51], v[146:149], v[206:209], v[48:51]
	v_mfma_f32_16x16x32_bf16 v[92:95], v[142:145], v[174:177], v[92:95]
	v_mfma_f32_16x16x32_bf16 v[88:91], v[150:153], v[174:177], v[88:91]
	v_mfma_f32_16x16x32_bf16 v[84:87], v[142:145], v[182:185], v[84:87]
	v_mfma_f32_16x16x32_bf16 v[80:83], v[150:153], v[182:185], v[80:83]
	v_mfma_f32_16x16x32_bf16 v[72:75], v[142:145], v[190:193], v[72:75]
	v_mfma_f32_16x16x32_bf16 v[64:67], v[150:153], v[190:193], v[64:67]
	v_mfma_f32_16x16x32_bf16 v[56:59], v[142:145], v[210:213], v[56:59]
	v_mfma_f32_16x16x32_bf16 v[48:51], v[150:153], v[210:213], v[48:51]
	s_setprio 0
	s_setprio 1
	v_mfma_f32_16x16x32_bf16 v[28:31], v[154:157], v[170:173], v[28:31]
	v_mfma_f32_16x16x32_bf16 v[24:27], v[162:165], v[170:173], v[24:27]
	v_mfma_f32_16x16x32_bf16 v[20:23], v[154:157], v[178:181], v[20:23]
	v_mfma_f32_16x16x32_bf16 v[16:19], v[162:165], v[178:181], v[16:19]
	v_mfma_f32_16x16x32_bf16 v[12:15], v[154:157], v[186:189], v[12:15]
	v_mfma_f32_16x16x32_bf16 v[8:11], v[162:165], v[186:189], v[8:11]
	v_mfma_f32_16x16x32_bf16 v[4:7], v[154:157], v[206:209], v[4:7]
	v_mfma_f32_16x16x32_bf16 v[0:3], v[162:165], v[206:209], v[0:3]
	v_mfma_f32_16x16x32_bf16 v[28:31], v[158:161], v[174:177], v[28:31]
	v_mfma_f32_16x16x32_bf16 v[24:27], v[166:169], v[174:177], v[24:27]
	v_mfma_f32_16x16x32_bf16 v[20:23], v[158:161], v[182:185], v[20:23]
	v_mfma_f32_16x16x32_bf16 v[16:19], v[166:169], v[182:185], v[16:19]
	v_mfma_f32_16x16x32_bf16 v[12:15], v[158:161], v[190:193], v[12:15]
	v_mfma_f32_16x16x32_bf16 v[8:11], v[166:169], v[190:193], v[8:11]
	v_mfma_f32_16x16x32_bf16 v[4:7], v[158:161], v[210:213], v[4:7]
	v_mfma_f32_16x16x32_bf16 v[0:3], v[166:169], v[210:213], v[0:3]
	s_setprio 0
	s_barrier
	s_movk_i32 s13, 0x100
	s_andn2_b64 vcc, exec, s[20:21]
	s_mov_b64 s[22:23], -1
	s_mov_b64 s[20:21], 0
	s_cbranch_vccz .LBB0_1358
	s_and_b64 vcc, exec, s[10:11]
	s_cbranch_vccz .LBB0_1361
	s_barrier

; #define PG8_STAGE(bufoff, gbase, voff) do { _Pragma("unroll") for (int _i = 0; _i < 2; ++_i) \
;         __builtin_amdgcn_global_load_lds((const unsigned*)((const char*)(gbase) + (voff)[_i]), (PG8_LAS unsigned*)(lds + (bufoff) + ldsw + _i * 8192), 16, 0, 0); } while (0)
; #define PG8_LDA(dst, b, h) do { _Pragma("unroll") for (int m = 0; m < 4; ++m) _Pragma("unroll") for (int k = 0; k < 2; ++k) dst[m][k] = *(const PG8_LAS bf16x8*)(lds + PG8_SA(b, h) + aoff + m * 2048 + k * 1024); } while (0)
; #define PG8_LDB(dst, b, h) do { _Pragma("unroll") for (int n = 0; n < 2; ++n) _Pragma("unroll") for (int k = 0; k < 2; ++k) dst[n][k] = *(const PG8_LAS bf16x8*)(lds + PG8_SB(b, h) + boff + n * 2048 + k * 1024); } while (0)
; #define PG8_MMA(ai, bj, At, Bt) do { __builtin_amdgcn_s_setprio(1); _Pragma("unroll") for (int m = 0; m < 4; ++m) _Pragma("unroll") for (int n = 0; n < 2; ++n) _Pragma("unroll") for (int k = 0; k < 2; ++k) \
;         acc[ai][bj][m][n] = __builtin_amdgcn_mfma_f32_16x16x32_bf16(Bt[n][k], At[m][k], acc[ai][bj][m][n], 0, 0, 0); __builtin_amdgcn_s_setprio(0); } while (0)
; #define PG8_WAIT_V(n) asm volatile("s_waitcnt vmcnt(" #n ")" ::: "memory")
; #define PG8_WAIT_L(n) asm volatile("s_waitcnt lgkmcnt(" #n ")" ::: "memory")
; #define PG8_BAR __builtin_amdgcn_s_barrier()
; #define PG8_SCHED __builtin_amdgcn_sched_barrier(0)
; template <class Epi, class Sched, bool ALIGN_EPI = false, bool SP2 = false>
; __device__ __forceinline__ void gemm_phase(PG8_LAS unsigned char* lds, const Gemm g, const Sched& S, const Epi& E, int wave_s_) {
;     ...
;             PG8_LDB(B0, 0, 0); PG8_LDB(B1, 0, 1); PG8_SCHED; PG8_LDA(At, 0, 0); PG8_STAGE(PG8_SA(1, 1), a1 + hstep, voffA);
;             PG8_WAIT_V(8); PG8_WAIT_L(0); PG8_BAR; PG8_MMA(0, 0, At, B0); PG8_MMA(0, 1, At, B1); PG8_BAR; PG8_SCHED;
;             PG8_LDA(At, 0, 1); PG8_STAGE(PG8_SB(0, 0), b2, voffB); PG8_STAGE(PG8_SB(0, 1), b2 + hstep, voffB); PG8_STAGE(PG8_SA(0, 0), a2, voffA);
.LBB0_1581:
	s_add_i32 s57, s30, 2
	s_add_u32 s28, s10, 0x100
	s_addc_u32 s29, s11, 0
	s_add_i32 s58, 0, 0x10000
	s_cmp_eq_u32 s21, s30
	s_cselect_b32 s35, s23, s29
	s_cselect_b32 s34, s22, s28
	s_cselect_b32 s31, s25, s56
	s_cselect_b32 s30, s24, s55
	s_add_i32 s59, 0, 0x14000
	v_add_u32_e32 v100, s58, v224
	v_add_u32_e32 v120, s59, v224
	ds_read_b128 v[88:91], v100
	ds_read_b128 v[92:95], v100 offset:1024
	ds_read_b128 v[96:99], v100 offset:2048
	ds_read_b128 v[100:103], v100 offset:3072
	ds_read_b128 v[108:111], v120
	ds_read_b128 v[112:115], v120 offset:1024
	ds_read_b128 v[116:119], v120 offset:2048
	ds_read_b128 v[120:123], v120 offset:3072
	v_lshl_add_u64 v[198:199], s[10:11], 0, v[206:207]
	s_add_i32 m0, s40, 0xc000
	ds_read_b128 v[160:163], v225
	ds_read_b128 v[164:167], v225 offset:1024
	ds_read_b128 v[168:171], v225 offset:2048
	ds_read_b128 v[172:175], v225 offset:3072
	ds_read_b128 v[176:179], v225 offset:4096
	ds_read_b128 v[180:183], v225 offset:5120
	ds_read_b128 v[184:187], v225 offset:6144
	ds_read_b128 v[188:191], v225 offset:7168
	global_load_lds_dwordx4 v[198:199], off
	v_lshl_add_u64 v[198:199], s[10:11], 0, v[194:195]
	s_add_i32 m0, s40, 0xe000
	s_nop 0
	global_load_lds_dwordx4 v[198:199], off
	s_waitcnt vmcnt(8)
	s_waitcnt lgkmcnt(0)
	s_barrier
	s_setprio 1
	s_waitcnt lgkmcnt(0)
	v_mfma_f32_16x16x32_bf16 v[156:159], v[88:91], v[160:163], v[156:159]
	v_mfma_f32_16x16x32_bf16 v[152:155], v[96:99], v[160:163], v[152:155]
	v_mfma_f32_16x16x32_bf16 v[144:147], v[88:91], v[168:171], v[144:147]
	v_mfma_f32_16x16x32_bf16 v[136:139], v[96:99], v[168:171], v[136:139]
	v_mfma_f32_16x16x32_bf16 v[124:127], v[88:91], v[176:179], v[124:127]
	v_mfma_f32_16x16x32_bf16 v[104:107], v[96:99], v[176:179], v[104:107]
	v_mfma_f32_16x16x32_bf16 v[80:83], v[88:91], v[184:187], v[80:83]
	v_mfma_f32_16x16x32_bf16 v[72:75], v[96:99], v[184:187], v[72:75]
	v_mfma_f32_16x16x32_bf16 v[156:159], v[92:95], v[164:167], v[156:159]
	v_mfma_f32_16x16x32_bf16 v[152:155], v[100:103], v[164:167], v[152:155]
	v_mfma_f32_16x16x32_bf16 v[144:147], v[92:95], v[172:175], v[144:147]
	v_mfma_f32_16x16x32_bf16 v[136:139], v[100:103], v[172:175], v[136:139]
	v_mfma_f32_16x16x32_bf16 v[124:127], v[92:95], v[180:183], v[124:127]
	v_mfma_f32_16x16x32_bf16 v[104:107], v[100:103], v[180:183], v[104:107]
	v_mfma_f32_16x16x32_bf16 v[80:83], v[92:95], v[188:191], v[80:83]
	v_mfma_f32_16x16x32_bf16 v[72:75], v[100:103], v[188:191], v[72:75]
	s_setprio 0
	s_setprio 1
	v_mfma_f32_16x16x32_bf16 v[148:151], v[108:111], v[160:163], v[148:151]
	v_mfma_f32_16x16x32_bf16 v[140:143], v[116:119], v[160:163], v[140:143]
	v_mfma_f32_16x16x32_bf16 v[132:135], v[108:111], v[168:171], v[132:135]
	v_mfma_f32_16x16x32_bf16 v[128:131], v[116:119], v[168:171], v[128:131]
	v_mfma_f32_16x16x32_bf16 v[84:87], v[108:111], v[176:179], v[84:87]
	v_mfma_f32_16x16x32_bf16 v[76:79], v[116:119], v[176:179], v[76:79]
	v_mfma_f32_16x16x32_bf16 v[68:71], v[108:111], v[184:187], v[68:71]
	v_mfma_f32_16x16x32_bf16 v[64:67], v[116:119], v[184:187], v[64:67]
	v_mfma_f32_16x16x32_bf16 v[148:151], v[112:115], v[164:167], v[148:151]
	v_mfma_f32_16x16x32_bf16 v[140:143], v[120:123], v[164:167], v[140:143]
	v_mfma_f32_16x16x32_bf16 v[132:135], v[112:115], v[172:175], v[132:135]
	v_mfma_f32_16x16x32_bf16 v[128:131], v[120:123], v[172:175], v[128:131]
	v_mfma_f32_16x16x32_bf16 v[84:87], v[112:115], v[180:183], v[84:87]
	v_mfma_f32_16x16x32_bf16 v[76:79], v[120:123], v[180:183], v[76:79]
	v_mfma_f32_16x16x32_bf16 v[68:71], v[112:115], v[188:191], v[68:71]
	v_mfma_f32_16x16x32_bf16 v[64:67], v[120:123], v[188:191], v[64:67]
	s_setprio 0
	s_barrier
	s_add_i32 s10, s58, s39
	v_lshl_add_u64 v[198:199], s[30:31], 0, v[196:197]
	s_mov_b32 m0, s10
	ds_read_b128 v[160:163], v225 offset:16384
	ds_read_b128 v[164:167], v225 offset:17408
	ds_read_b128 v[168:171], v225 offset:18432
	ds_read_b128 v[172:175], v225 offset:19456
	ds_read_b128 v[176:179], v225 offset:20480
	ds_read_b128 v[180:183], v225 offset:21504
	ds_read_b128 v[184:187], v225 offset:22528
	ds_read_b128 v[188:191], v225 offset:23552
	global_load_lds_dwordx4 v[198:199], off
	s_add_i32 m0, s10, 0x2000
	s_add_u32 s10, s30, 0x40000
	v_lshl_add_u64 v[204:205], s[30:31], 0, v[192:193]
	s_addc_u32 s11, s31, 0
	s_add_i32 s58, s59, s39
	global_load_lds_dwordx4 v[204:205], off
	s_mov_b32 m0, s58
	v_lshl_add_u64 v[210:211], s[34:35], 0, v[192:193]
	global_load_lds_dwordx4 v196, s[10:11]
	s_add_i32 m0, s58, 0x2000
	s_nop 0
	global_load_lds_dwordx4 v192, s[10:11]
	v_lshl_add_u64 v[208:209], s[34:35], 0, v[196:197]
	s_mov_b32 m0, s40
	s_nop 0
	global_load_lds_dwordx4 v[208:209], off
	s_mov_b32 m0, s41
	s_nop 0
	global_load_lds_dwordx4 v[210:211], off
	s_waitcnt vmcnt(8)
	s_waitcnt lgkmcnt(0)
	s_barrier
; #define PG8_STAGE(bufoff, gbase, voff) do { _Pragma("unroll") for (int _i = 0; _i < 2; ++_i) \
;         __builtin_amdgcn_global_load_lds((const unsigned*)((const char*)(gbase) + (voff)[_i]), (PG8_LAS unsigned*)(lds + (bufoff) + ldsw + _i * 8192), 16, 0, 0); } while (0)
; #define PG8_LDA(dst, b, h) do { _Pragma("unroll") for (int m = 0; m < 4; ++m) _Pragma("unroll") for (int k = 0; k < 2; ++k) dst[m][k] = *(const PG8_LAS bf16x8*)(lds + PG8_SA(b, h) + aoff + m * 2048 + k * 1024); } while (0)
; #define PG8_LDB(dst, b, h) do { _Pragma("unroll") for (int n = 0; n < 2; ++n) _Pragma("unroll") for (int k = 0; k < 2; ++k) dst[n][k] = *(const PG8_LAS bf16x8*)(lds + PG8_SB(b, h) + boff + n * 2048 + k * 1024); } while (0)
; #define PG8_MMA(ai, bj, At, Bt) do { __builtin_amdgcn_s_setprio(1); _Pragma("unroll") for (int m = 0; m < 4; ++m) _Pragma("unroll") for (int n = 0; n < 2; ++n) _Pragma("unroll") for (int k = 0; k < 2; ++k) \
;         acc[ai][bj][m][n] = __builtin_amdgcn_mfma_f32_16x16x32_bf16(Bt[n][k], At[m][k], acc[ai][bj][m][n], 0, 0, 0); __builtin_amdgcn_s_setprio(0); } while (0)
; #define PG8_WAIT_V(n) asm volatile("s_waitcnt vmcnt(" #n ")" ::: "memory")
; #define PG8_WAIT_L(n) asm volatile("s_waitcnt lgkmcnt(" #n ")" ::: "memory")
; #define PG8_BAR __builtin_amdgcn_s_barrier()
; #define PG8_SCHED __builtin_amdgcn_sched_barrier(0)
; template <class Epi, class Sched, bool ALIGN_EPI = false, bool SP2 = false>
; __device__ __forceinline__ void gemm_phase(PG8_LAS unsigned char* lds, const Gemm g, const Sched& S, const Epi& E, int wave_s_) {
;     ...
;             PG8_WAIT_V(8); PG8_WAIT_L(0); PG8_BAR; PG8_MMA(1, 0, At, B0); PG8_MMA(1, 1, At, B1); PG8_BAR; PG8_SCHED;
;             PG8_LDB(B0, 1, 0); PG8_LDB(B1, 1, 1); PG8_SCHED; PG8_LDA(At, 1, 0); PG8_STAGE(PG8_SA(0, 1), a2 + hstep, voffA);
;             PG8_WAIT_V(8); PG8_WAIT_L(0); PG8_BAR; PG8_MMA(0, 0, At, B0); PG8_MMA(0, 1, At, B1); PG8_BAR; PG8_SCHED;
	s_setprio 1
	s_waitcnt lgkmcnt(0)
	v_mfma_f32_16x16x32_bf16 v[60:63], v[88:91], v[160:163], v[60:63]
	v_mfma_f32_16x16x32_bf16 v[56:59], v[96:99], v[160:163], v[56:59]
	v_mfma_f32_16x16x32_bf16 v[48:51], v[88:91], v[168:171], v[48:51]
	v_mfma_f32_16x16x32_bf16 v[40:43], v[96:99], v[168:171], v[40:43]
	v_mfma_f32_16x16x32_bf16 v[28:31], v[88:91], v[176:179], v[28:31]
	v_mfma_f32_16x16x32_bf16 v[24:27], v[96:99], v[176:179], v[24:27]
	v_mfma_f32_16x16x32_bf16 v[16:19], v[88:91], v[184:187], v[16:19]
	v_mfma_f32_16x16x32_bf16 v[8:11], v[96:99], v[184:187], v[8:11]
	v_mfma_f32_16x16x32_bf16 v[60:63], v[92:95], v[164:167], v[60:63]
	v_mfma_f32_16x16x32_bf16 v[56:59], v[100:103], v[164:167], v[56:59]
	v_mfma_f32_16x16x32_bf16 v[48:51], v[92:95], v[172:175], v[48:51]
	v_mfma_f32_16x16x32_bf16 v[40:43], v[100:103], v[172:175], v[40:43]
	v_mfma_f32_16x16x32_bf16 v[28:31], v[92:95], v[180:183], v[28:31]
	v_mfma_f32_16x16x32_bf16 v[24:27], v[100:103], v[180:183], v[24:27]
	v_mfma_f32_16x16x32_bf16 v[16:19], v[92:95], v[188:191], v[16:19]
	v_mfma_f32_16x16x32_bf16 v[8:11], v[100:103], v[188:191], v[8:11]
	s_setprio 0
	s_setprio 1
	v_mfma_f32_16x16x32_bf16 v[52:55], v[108:111], v[160:163], v[52:55]
	v_mfma_f32_16x16x32_bf16 v[44:47], v[116:119], v[160:163], v[44:47]
	v_mfma_f32_16x16x32_bf16 v[36:39], v[108:111], v[168:171], v[36:39]
	v_mfma_f32_16x16x32_bf16 v[32:35], v[116:119], v[168:171], v[32:35]
	v_mfma_f32_16x16x32_bf16 v[20:23], v[108:111], v[176:179], v[20:23]
	v_mfma_f32_16x16x32_bf16 v[12:15], v[116:119], v[176:179], v[12:15]
	v_mfma_f32_16x16x32_bf16 v[4:7], v[108:111], v[184:187], v[4:7]
	v_mfma_f32_16x16x32_bf16 v[0:3], v[116:119], v[184:187], v[0:3]
	v_mfma_f32_16x16x32_bf16 v[52:55], v[112:115], v[164:167], v[52:55]
	v_mfma_f32_16x16x32_bf16 v[44:47], v[120:123], v[164:167], v[44:47]
	v_mfma_f32_16x16x32_bf16 v[36:39], v[112:115], v[172:175], v[36:39]
	v_mfma_f32_16x16x32_bf16 v[32:35], v[120:123], v[172:175], v[32:35]
	v_mfma_f32_16x16x32_bf16 v[20:23], v[112:115], v[180:183], v[20:23]
	v_mfma_f32_16x16x32_bf16 v[12:15], v[120:123], v[180:183], v[12:15]
	v_mfma_f32_16x16x32_bf16 v[4:7], v[112:115], v[188:191], v[4:7]
	v_mfma_f32_16x16x32_bf16 v[0:3], v[120:123], v[188:191], v[0:3]
	s_setprio 0
	s_barrier
	s_add_i32 s58, 0, 0x18000
	s_add_i32 s59, 0, 0x1c000
	v_add_u32_e32 v100, s58, v224
	v_add_u32_e32 v120, s59, v224
	ds_read_b128 v[88:91], v100
	ds_read_b128 v[92:95], v100 offset:1024
	ds_read_b128 v[96:99], v100 offset:2048
	ds_read_b128 v[100:103], v100 offset:3072
	ds_read_b128 v[108:111], v120
	ds_read_b128 v[112:115], v120 offset:1024
	ds_read_b128 v[116:119], v120 offset:2048
	ds_read_b128 v[120:123], v120 offset:3072
	s_add_u32 s10, s34, 0x40000
	s_addc_u32 s11, s35, 0
	s_mov_b32 m0, s42
	ds_read_b128 v[160:163], v225 offset:32768
	ds_read_b128 v[164:167], v225 offset:33792
	ds_read_b128 v[168:171], v225 offset:34816
	ds_read_b128 v[172:175], v225 offset:35840
	ds_read_b128 v[176:179], v225 offset:36864
	ds_read_b128 v[180:183], v225 offset:37888
	ds_read_b128 v[184:187], v225 offset:38912
	ds_read_b128 v[188:191], v225 offset:39936
	global_load_lds_dwordx4 v196, s[10:11]
	s_mov_b32 m0, s43
	s_nop 0
	global_load_lds_dwordx4 v192, s[10:11]
	s_waitcnt vmcnt(8)
	s_waitcnt lgkmcnt(0)
	s_barrier
	s_setprio 1
	s_waitcnt lgkmcnt(0)
	v_mfma_f32_16x16x32_bf16 v[156:159], v[88:91], v[160:163], v[156:159]
	v_mfma_f32_16x16x32_bf16 v[152:155], v[96:99], v[160:163], v[152:155]
	v_mfma_f32_16x16x32_bf16 v[144:147], v[88:91], v[168:171], v[144:147]
	v_mfma_f32_16x16x32_bf16 v[136:139], v[96:99], v[168:171], v[136:139]
	v_mfma_f32_16x16x32_bf16 v[124:127], v[88:91], v[176:179], v[124:127]
	v_mfma_f32_16x16x32_bf16 v[104:107], v[96:99], v[176:179], v[104:107]
	v_mfma_f32_16x16x32_bf16 v[80:83], v[88:91], v[184:187], v[80:83]
	v_mfma_f32_16x16x32_bf16 v[72:75], v[96:99], v[184:187], v[72:75]
	v_mfma_f32_16x16x32_bf16 v[156:159], v[92:95], v[164:167], v[156:159]
	v_mfma_f32_16x16x32_bf16 v[152:155], v[100:103], v[164:167], v[152:155]
	v_mfma_f32_16x16x32_bf16 v[144:147], v[92:95], v[172:175], v[144:147]
	v_mfma_f32_16x16x32_bf16 v[136:139], v[100:103], v[172:175], v[136:139]
	v_mfma_f32_16x16x32_bf16 v[124:127], v[92:95], v[180:183], v[124:127]
	v_mfma_f32_16x16x32_bf16 v[104:107], v[100:103], v[180:183], v[104:107]
	v_mfma_f32_16x16x32_bf16 v[80:83], v[92:95], v[188:191], v[80:83]
	v_mfma_f32_16x16x32_bf16 v[72:75], v[100:103], v[188:191], v[72:75]
	s_setprio 0
	s_setprio 1
	v_mfma_f32_16x16x32_bf16 v[148:151], v[108:111], v[160:163], v[148:151]
	v_mfma_f32_16x16x32_bf16 v[140:143], v[116:119], v[160:163], v[140:143]
	v_mfma_f32_16x16x32_bf16 v[132:135], v[108:111], v[168:171], v[132:135]
	v_mfma_f32_16x16x32_bf16 v[128:131], v[116:119], v[168:171], v[128:131]
	v_mfma_f32_16x16x32_bf16 v[84:87], v[108:111], v[176:179], v[84:87]
	v_mfma_f32_16x16x32_bf16 v[76:79], v[116:119], v[176:179], v[76:79]
	v_mfma_f32_16x16x32_bf16 v[68:71], v[108:111], v[184:187], v[68:71]
	v_mfma_f32_16x16x32_bf16 v[64:67], v[116:119], v[184:187], v[64:67]
	v_mfma_f32_16x16x32_bf16 v[148:151], v[112:115], v[164:167], v[148:151]
	v_mfma_f32_16x16x32_bf16 v[140:143], v[120:123], v[164:167], v[140:143]
	v_mfma_f32_16x16x32_bf16 v[132:135], v[112:115], v[172:175], v[132:135]
	v_mfma_f32_16x16x32_bf16 v[128:131], v[120:123], v[172:175], v[128:131]
	v_mfma_f32_16x16x32_bf16 v[84:87], v[112:115], v[180:183], v[84:87]
	v_mfma_f32_16x16x32_bf16 v[76:79], v[120:123], v[180:183], v[76:79]
	v_mfma_f32_16x16x32_bf16 v[68:71], v[112:115], v[188:191], v[68:71]
	v_mfma_f32_16x16x32_bf16 v[64:67], v[120:123], v[188:191], v[64:67]
	s_setprio 0
	s_barrier
; #define PG8_STAGE(bufoff, gbase, voff) do { _Pragma("unroll") for (int _i = 0; _i < 2; ++_i) \
;         __builtin_amdgcn_global_load_lds((const unsigned*)((const char*)(gbase) + (voff)[_i]), (PG8_LAS unsigned*)(lds + (bufoff) + ldsw + _i * 8192), 16, 0, 0); } while (0)
; #define PG8_LDA(dst, b, h) do { _Pragma("unroll") for (int m = 0; m < 4; ++m) _Pragma("unroll") for (int k = 0; k < 2; ++k) dst[m][k] = *(const PG8_LAS bf16x8*)(lds + PG8_SA(b, h) + aoff + m * 2048 + k * 1024); } while (0)
; #define PG8_MMA(ai, bj, At, Bt) do { __builtin_amdgcn_s_setprio(1); _Pragma("unroll") for (int m = 0; m < 4; ++m) _Pragma("unroll") for (int n = 0; n < 2; ++n) _Pragma("unroll") for (int k = 0; k < 2; ++k) \
;         acc[ai][bj][m][n] = __builtin_amdgcn_mfma_f32_16x16x32_bf16(Bt[n][k], At[m][k], acc[ai][bj][m][n], 0, 0, 0); __builtin_amdgcn_s_setprio(0); } while (0)
; #define PG8_WAIT_V(n) asm volatile("s_waitcnt vmcnt(" #n ")" ::: "memory")
; #define PG8_WAIT_L(n) asm volatile("s_waitcnt lgkmcnt(" #n ")" ::: "memory")
; #define PG8_BAR __builtin_amdgcn_s_barrier()
; #define PG8_SCHED __builtin_amdgcn_sched_barrier(0)
; template <class Epi, class Sched, bool ALIGN_EPI = false, bool SP2 = false>
; __device__ __forceinline__ void gemm_phase(PG8_LAS unsigned char* lds, const Gemm g, const Sched& S, const Epi& E, int wave_s_) {
;     ...
;             PG8_LDA(At, 1, 1); PG8_STAGE(PG8_SB(1, 0), b3, voffB); PG8_STAGE(PG8_SB(1, 1), b3 + hstep, voffB); PG8_STAGE(PG8_SA(1, 0), a3, voffA);
;             PG8_WAIT_V(8); PG8_WAIT_L(0); PG8_BAR; PG8_MMA(1, 0, At, B0); PG8_MMA(1, 1, At, B1); PG8_BAR; PG8_SCHED;
	s_add_i32 s10, s58, s39
	v_lshl_add_u64 v[198:199], v[198:199], 0, s[76:77]
	s_mov_b32 m0, s10
	ds_read_b128 v[160:163], v225 offset:49152
	ds_read_b128 v[164:167], v225 offset:50176
	ds_read_b128 v[168:171], v225 offset:51200
	ds_read_b128 v[172:175], v225 offset:52224
	ds_read_b128 v[176:179], v225 offset:53248
	ds_read_b128 v[180:183], v225 offset:54272
	ds_read_b128 v[184:187], v225 offset:55296
	ds_read_b128 v[188:191], v225 offset:56320
	global_load_lds_dwordx4 v[198:199], off
	s_add_i32 m0, s10, 0x2000
	s_add_u32 s10, s30, 0x40080
	v_lshl_add_u64 v[198:199], v[204:205], 0, s[76:77]
	s_addc_u32 s11, s31, 0
	s_add_i32 s30, s59, s39
	global_load_lds_dwordx4 v[198:199], off
	s_mov_b32 m0, s30
	s_nop 0
	global_load_lds_dwordx4 v196, s[10:11]
	s_add_i32 m0, s30, 0x2000
	s_nop 0
	global_load_lds_dwordx4 v192, s[10:11]
	v_lshl_add_u64 v[198:199], v[208:209], 0, s[76:77]
	s_mov_b32 m0, s46
	s_nop 0
	global_load_lds_dwordx4 v[198:199], off
	v_lshl_add_u64 v[198:199], v[210:211], 0, s[76:77]
	s_mov_b32 m0, s47
	s_nop 0
	global_load_lds_dwordx4 v[198:199], off
	s_waitcnt vmcnt(8)
	s_waitcnt lgkmcnt(0)
	s_barrier
	s_setprio 1
	s_waitcnt lgkmcnt(0)
	v_mfma_f32_16x16x32_bf16 v[60:63], v[88:91], v[160:163], v[60:63]
	v_mfma_f32_16x16x32_bf16 v[56:59], v[96:99], v[160:163], v[56:59]
	v_mfma_f32_16x16x32_bf16 v[48:51], v[88:91], v[168:171], v[48:51]
	v_mfma_f32_16x16x32_bf16 v[40:43], v[96:99], v[168:171], v[40:43]
	v_mfma_f32_16x16x32_bf16 v[28:31], v[88:91], v[176:179], v[28:31]
	v_mfma_f32_16x16x32_bf16 v[24:27], v[96:99], v[176:179], v[24:27]
	v_mfma_f32_16x16x32_bf16 v[16:19], v[88:91], v[184:187], v[16:19]
	v_mfma_f32_16x16x32_bf16 v[8:11], v[96:99], v[184:187], v[8:11]
	v_mfma_f32_16x16x32_bf16 v[60:63], v[92:95], v[164:167], v[60:63]
	v_mfma_f32_16x16x32_bf16 v[56:59], v[100:103], v[164:167], v[56:59]
	v_mfma_f32_16x16x32_bf16 v[48:51], v[92:95], v[172:175], v[48:51]
	v_mfma_f32_16x16x32_bf16 v[40:43], v[100:103], v[172:175], v[40:43]
	v_mfma_f32_16x16x32_bf16 v[28:31], v[92:95], v[180:183], v[28:31]
	v_mfma_f32_16x16x32_bf16 v[24:27], v[100:103], v[180:183], v[24:27]
	v_mfma_f32_16x16x32_bf16 v[16:19], v[92:95], v[188:191], v[16:19]
	v_mfma_f32_16x16x32_bf16 v[8:11], v[100:103], v[188:191], v[8:11]
	s_setprio 0
	s_setprio 1
	v_mfma_f32_16x16x32_bf16 v[52:55], v[108:111], v[160:163], v[52:55]
	v_mfma_f32_16x16x32_bf16 v[44:47], v[116:119], v[160:163], v[44:47]
	v_mfma_f32_16x16x32_bf16 v[36:39], v[108:111], v[168:171], v[36:39]
	v_mfma_f32_16x16x32_bf16 v[32:35], v[116:119], v[168:171], v[32:35]
	v_mfma_f32_16x16x32_bf16 v[20:23], v[108:111], v[176:179], v[20:23]
	v_mfma_f32_16x16x32_bf16 v[12:15], v[116:119], v[176:179], v[12:15]
	v_mfma_f32_16x16x32_bf16 v[4:7], v[108:111], v[184:187], v[4:7]
	v_mfma_f32_16x16x32_bf16 v[0:3], v[116:119], v[184:187], v[0:3]
	v_mfma_f32_16x16x32_bf16 v[52:55], v[112:115], v[164:167], v[52:55]
	v_mfma_f32_16x16x32_bf16 v[44:47], v[120:123], v[164:167], v[44:47]
	v_mfma_f32_16x16x32_bf16 v[36:39], v[112:115], v[172:175], v[36:39]
	v_mfma_f32_16x16x32_bf16 v[32:35], v[120:123], v[172:175], v[32:35]
	v_mfma_f32_16x16x32_bf16 v[20:23], v[112:115], v[180:183], v[20:23]
	v_mfma_f32_16x16x32_bf16 v[12:15], v[120:123], v[180:183], v[12:15]
	v_mfma_f32_16x16x32_bf16 v[4:7], v[112:115], v[188:191], v[4:7]
	v_mfma_f32_16x16x32_bf16 v[0:3], v[120:123], v[188:191], v[0:3]
	s_setprio 0
	s_barrier
	s_add_u32 s55, s55, 0x100
	s_addc_u32 s56, s56, 0
	s_cmp_ge_u32 s57, s9
	s_mov_b64 s[10:11], s[28:29]
	s_mov_b32 s30, s57
	s_cbranch_scc0 .LBB0_1581
	s_and_b64 vcc, exec, s[18:19]
	s_cbranch_vccz .LBB0_1584
	s_barrier

; #define PG8_STAGE(bufoff, gbase, voff) do { _Pragma("unroll") for (int _i = 0; _i < 2; ++_i) \
;         __builtin_amdgcn_global_load_lds((const unsigned*)((const char*)(gbase) + (voff)[_i]), (PG8_LAS unsigned*)(lds + (bufoff) + ldsw + _i * 8192), 16, 0, 0); } while (0)
; #define PG8_LDA(dst, b, h) do { _Pragma("unroll") for (int m = 0; m < 4; ++m) _Pragma("unroll") for (int k = 0; k < 2; ++k) dst[m][k] = *(const PG8_LAS bf16x8*)(lds + PG8_SA(b, h) + aoff + m * 2048 + k * 1024); } while (0)
; #define PG8_LDB(dst, b, h) do { _Pragma("unroll") for (int n = 0; n < 2; ++n) _Pragma("unroll") for (int k = 0; k < 2; ++k) dst[n][k] = *(const PG8_LAS bf16x8*)(lds + PG8_SB(b, h) + boff + n * 2048 + k * 1024); } while (0)
; #define PG8_MMA(ai, bj, At, Bt) do { __builtin_amdgcn_s_setprio(1); _Pragma("unroll") for (int m = 0; m < 4; ++m) _Pragma("unroll") for (int n = 0; n < 2; ++n) _Pragma("unroll") for (int k = 0; k < 2; ++k) \
;         acc[ai][bj][m][n] = __builtin_amdgcn_mfma_f32_16x16x32_bf16(Bt[n][k], At[m][k], acc[ai][bj][m][n], 0, 0, 0); __builtin_amdgcn_s_setprio(0); } while (0)
; #define PG8_WAIT_V(n) asm volatile("s_waitcnt vmcnt(" #n ")" ::: "memory")
; #define PG8_WAIT_L(n) asm volatile("s_waitcnt lgkmcnt(" #n ")" ::: "memory")
; #define PG8_BAR __builtin_amdgcn_s_barrier()
; #define PG8_SCHED __builtin_amdgcn_sched_barrier(0)
; template <class Epi, class Sched, bool ALIGN_EPI = false, bool SP2 = false>
; __device__ __forceinline__ void gemm_phase(PG8_LAS unsigned char* lds, const Gemm g, const Sched& S, const Epi& E, int wave_s_) {
;     ...
;             PG8_LDB(B0, 0, 0); PG8_LDB(B1, 0, 1); PG8_SCHED; PG8_LDA(At, 0, 0); PG8_STAGE(PG8_SA(1, 1), a1 + hstep, voffA);
;             PG8_WAIT_V(8); PG8_WAIT_L(0); PG8_BAR; PG8_MMA(0, 0, At, B0); PG8_MMA(0, 1, At, B1); PG8_BAR; PG8_SCHED;
;             PG8_LDA(At, 0, 1); PG8_STAGE(PG8_SB(0, 0), b2, voffB); PG8_STAGE(PG8_SB(0, 1), b2 + hstep, voffB); PG8_STAGE(PG8_SA(0, 0), a2, voffA);
.LBB0_1820:
	s_add_u32 s20, s18, 0xfffc0080
	s_addc_u32 s21, s19, -1
	s_add_i32 s47, 0, 0x10000
	s_cmp_eq_u32 s46, 12
	s_cselect_b32 s23, s7, s21
	s_cselect_b32 s22, s6, s20
	s_cselect_b32 s21, s17, s45
	s_cselect_b32 s20, s16, s15
	s_add_i32 s50, 0, 0x14000
	v_add_u32_e32 v152, s47, v138
	v_add_u32_e32 v168, s50, v138
	ds_read_b128 v[140:143], v152
	ds_read_b128 v[144:147], v152 offset:1024
	ds_read_b128 v[148:151], v152 offset:2048
	ds_read_b128 v[152:155], v152 offset:3072
	ds_read_b128 v[156:159], v168
	ds_read_b128 v[160:163], v168 offset:1024
	ds_read_b128 v[164:167], v168 offset:2048
	ds_read_b128 v[168:171], v168 offset:3072
	s_add_i32 m0, s31, 0xc000
	ds_read_b128 v[172:175], v139
	ds_read_b128 v[176:179], v139 offset:1024
	ds_read_b128 v[180:183], v139 offset:2048
	ds_read_b128 v[184:187], v139 offset:3072
	ds_read_b128 v[188:191], v139 offset:4096
	ds_read_b128 v[192:195], v139 offset:5120
	ds_read_b128 v[206:209], v139 offset:6144
	ds_read_b128 v[210:213], v139 offset:7168
	global_load_lds_dwordx4 v136, s[18:19]
	s_add_i32 m0, s31, 0xe000
	s_nop 0
	global_load_lds_dwordx4 v134, s[18:19]
	s_waitcnt vmcnt(8)
	s_waitcnt lgkmcnt(0)
	s_barrier
	s_setprio 1
	s_waitcnt lgkmcnt(0)
	v_mfma_f32_16x16x32_bf16 v[124:127], v[140:143], v[172:175], v[124:127]
	v_mfma_f32_16x16x32_bf16 v[116:119], v[148:151], v[172:175], v[116:119]
	v_mfma_f32_16x16x32_bf16 v[108:111], v[140:143], v[180:183], v[108:111]
	v_mfma_f32_16x16x32_bf16 v[100:103], v[148:151], v[180:183], v[100:103]
	v_mfma_f32_16x16x32_bf16 v[92:95], v[140:143], v[188:191], v[92:95]
	v_mfma_f32_16x16x32_bf16 v[84:87], v[148:151], v[188:191], v[84:87]
	v_mfma_f32_16x16x32_bf16 v[76:79], v[140:143], v[206:209], v[76:79]
	v_mfma_f32_16x16x32_bf16 v[68:71], v[148:151], v[206:209], v[68:71]
	v_mfma_f32_16x16x32_bf16 v[124:127], v[144:147], v[176:179], v[124:127]
	v_mfma_f32_16x16x32_bf16 v[116:119], v[152:155], v[176:179], v[116:119]
	v_mfma_f32_16x16x32_bf16 v[108:111], v[144:147], v[184:187], v[108:111]
	v_mfma_f32_16x16x32_bf16 v[100:103], v[152:155], v[184:187], v[100:103]
	v_mfma_f32_16x16x32_bf16 v[92:95], v[144:147], v[192:195], v[92:95]
	v_mfma_f32_16x16x32_bf16 v[84:87], v[152:155], v[192:195], v[84:87]
	v_mfma_f32_16x16x32_bf16 v[76:79], v[144:147], v[210:213], v[76:79]
	v_mfma_f32_16x16x32_bf16 v[68:71], v[152:155], v[210:213], v[68:71]
	s_setprio 0
	s_setprio 1
	v_mfma_f32_16x16x32_bf16 v[120:123], v[156:159], v[172:175], v[120:123]
	v_mfma_f32_16x16x32_bf16 v[112:115], v[164:167], v[172:175], v[112:115]
	v_mfma_f32_16x16x32_bf16 v[104:107], v[156:159], v[180:183], v[104:107]
	v_mfma_f32_16x16x32_bf16 v[96:99], v[164:167], v[180:183], v[96:99]
	v_mfma_f32_16x16x32_bf16 v[88:91], v[156:159], v[188:191], v[88:91]
	v_mfma_f32_16x16x32_bf16 v[80:83], v[164:167], v[188:191], v[80:83]
	v_mfma_f32_16x16x32_bf16 v[72:75], v[156:159], v[206:209], v[72:75]
	v_mfma_f32_16x16x32_bf16 v[64:67], v[164:167], v[206:209], v[64:67]
	v_mfma_f32_16x16x32_bf16 v[120:123], v[160:163], v[176:179], v[120:123]
	v_mfma_f32_16x16x32_bf16 v[112:115], v[168:171], v[176:179], v[112:115]
	v_mfma_f32_16x16x32_bf16 v[104:107], v[160:163], v[184:187], v[104:107]
	v_mfma_f32_16x16x32_bf16 v[96:99], v[168:171], v[184:187], v[96:99]
	v_mfma_f32_16x16x32_bf16 v[88:91], v[160:163], v[192:195], v[88:91]
	v_mfma_f32_16x16x32_bf16 v[80:83], v[168:171], v[192:195], v[80:83]
	v_mfma_f32_16x16x32_bf16 v[72:75], v[160:163], v[210:213], v[72:75]
	v_mfma_f32_16x16x32_bf16 v[64:67], v[168:171], v[210:213], v[64:67]
	s_setprio 0
	s_barrier
	s_add_i32 s47, s47, s30
	v_lshl_add_u64 v[198:199], s[20:21], 0, v[196:197]
	s_mov_b32 m0, s47
	ds_read_b128 v[172:175], v139 offset:16384
	ds_read_b128 v[176:179], v139 offset:17408
	ds_read_b128 v[180:183], v139 offset:18432
	ds_read_b128 v[184:187], v139 offset:19456
	ds_read_b128 v[188:191], v139 offset:20480
	ds_read_b128 v[192:195], v139 offset:21504
	ds_read_b128 v[206:209], v139 offset:22528
	ds_read_b128 v[210:213], v139 offset:23552
	global_load_lds_dwordx4 v[198:199], off
	s_add_i32 m0, s47, 0x2000
	s_add_u32 s48, s20, 0x40000
	v_lshl_add_u64 v[204:205], s[20:21], 0, v[132:133]
	s_addc_u32 s49, s21, 0
	s_add_i32 s47, s50, s30
	global_load_lds_dwordx4 v[204:205], off
	s_mov_b32 m0, s47
	v_lshl_add_u64 v[216:217], s[22:23], 0, v[130:131]
	global_load_lds_dwordx4 v196, s[48:49]
	s_add_i32 m0, s47, 0x2000
	s_nop 0
	global_load_lds_dwordx4 v132, s[48:49]
	v_lshl_add_u64 v[214:215], s[22:23], 0, v[128:129]
	s_mov_b32 m0, s31
	s_nop 0
	global_load_lds_dwordx4 v[214:215], off
	s_mov_b32 m0, s33
	s_nop 0
	global_load_lds_dwordx4 v[216:217], off
	s_waitcnt vmcnt(8)
	s_waitcnt lgkmcnt(0)
	s_barrier
; #define PG8_STAGE(bufoff, gbase, voff) do { _Pragma("unroll") for (int _i = 0; _i < 2; ++_i) \
;         __builtin_amdgcn_global_load_lds((const unsigned*)((const char*)(gbase) + (voff)[_i]), (PG8_LAS unsigned*)(lds + (bufoff) + ldsw + _i * 8192), 16, 0, 0); } while (0)
; #define PG8_LDA(dst, b, h) do { _Pragma("unroll") for (int m = 0; m < 4; ++m) _Pragma("unroll") for (int k = 0; k < 2; ++k) dst[m][k] = *(const PG8_LAS bf16x8*)(lds + PG8_SA(b, h) + aoff + m * 2048 + k * 1024); } while (0)
; #define PG8_LDB(dst, b, h) do { _Pragma("unroll") for (int n = 0; n < 2; ++n) _Pragma("unroll") for (int k = 0; k < 2; ++k) dst[n][k] = *(const PG8_LAS bf16x8*)(lds + PG8_SB(b, h) + boff + n * 2048 + k * 1024); } while (0)
; #define PG8_MMA(ai, bj, At, Bt) do { __builtin_amdgcn_s_setprio(1); _Pragma("unroll") for (int m = 0; m < 4; ++m) _Pragma("unroll") for (int n = 0; n < 2; ++n) _Pragma("unroll") for (int k = 0; k < 2; ++k) \
;         acc[ai][bj][m][n] = __builtin_amdgcn_mfma_f32_16x16x32_bf16(Bt[n][k], At[m][k], acc[ai][bj][m][n], 0, 0, 0); __builtin_amdgcn_s_setprio(0); } while (0)
; #define PG8_WAIT_V(n) asm volatile("s_waitcnt vmcnt(" #n ")" ::: "memory")
; #define PG8_WAIT_L(n) asm volatile("s_waitcnt lgkmcnt(" #n ")" ::: "memory")
; #define PG8_BAR __builtin_amdgcn_s_barrier()
; #define PG8_SCHED __builtin_amdgcn_sched_barrier(0)
; template <class Epi, class Sched, bool ALIGN_EPI = false, bool SP2 = false>
; __device__ __forceinline__ void gemm_phase(PG8_LAS unsigned char* lds, const Gemm g, const Sched& S, const Epi& E, int wave_s_) {
;     ...
;             PG8_WAIT_V(8); PG8_WAIT_L(0); PG8_BAR; PG8_MMA(1, 0, At, B0); PG8_MMA(1, 1, At, B1); PG8_BAR; PG8_SCHED;
;             PG8_LDB(B0, 1, 0); PG8_LDB(B1, 1, 1); PG8_SCHED; PG8_LDA(At, 1, 0); PG8_STAGE(PG8_SA(0, 1), a2 + hstep, voffA);
;             PG8_WAIT_V(8); PG8_WAIT_L(0); PG8_BAR; PG8_MMA(0, 0, At, B0); PG8_MMA(0, 1, At, B1); PG8_BAR; PG8_SCHED;
	s_setprio 1
	s_waitcnt lgkmcnt(0)
	v_mfma_f32_16x16x32_bf16 v[60:63], v[140:143], v[172:175], v[60:63]
	v_mfma_f32_16x16x32_bf16 v[52:55], v[148:151], v[172:175], v[52:55]
	v_mfma_f32_16x16x32_bf16 v[44:47], v[140:143], v[180:183], v[44:47]
	v_mfma_f32_16x16x32_bf16 v[36:39], v[148:151], v[180:183], v[36:39]
	v_mfma_f32_16x16x32_bf16 v[28:31], v[140:143], v[188:191], v[28:31]
	v_mfma_f32_16x16x32_bf16 v[20:23], v[148:151], v[188:191], v[20:23]
	v_mfma_f32_16x16x32_bf16 v[12:15], v[140:143], v[206:209], v[12:15]
	v_mfma_f32_16x16x32_bf16 v[4:7], v[148:151], v[206:209], v[4:7]
	v_mfma_f32_16x16x32_bf16 v[60:63], v[144:147], v[176:179], v[60:63]
	v_mfma_f32_16x16x32_bf16 v[52:55], v[152:155], v[176:179], v[52:55]
	v_mfma_f32_16x16x32_bf16 v[44:47], v[144:147], v[184:187], v[44:47]
	v_mfma_f32_16x16x32_bf16 v[36:39], v[152:155], v[184:187], v[36:39]
	v_mfma_f32_16x16x32_bf16 v[28:31], v[144:147], v[192:195], v[28:31]
	v_mfma_f32_16x16x32_bf16 v[20:23], v[152:155], v[192:195], v[20:23]
	v_mfma_f32_16x16x32_bf16 v[12:15], v[144:147], v[210:213], v[12:15]
	v_mfma_f32_16x16x32_bf16 v[4:7], v[152:155], v[210:213], v[4:7]
	s_setprio 0
	s_setprio 1
	v_mfma_f32_16x16x32_bf16 v[56:59], v[156:159], v[172:175], v[56:59]
	v_mfma_f32_16x16x32_bf16 v[48:51], v[164:167], v[172:175], v[48:51]
	v_mfma_f32_16x16x32_bf16 v[40:43], v[156:159], v[180:183], v[40:43]
	v_mfma_f32_16x16x32_bf16 v[32:35], v[164:167], v[180:183], v[32:35]
	v_mfma_f32_16x16x32_bf16 v[24:27], v[156:159], v[188:191], v[24:27]
	v_mfma_f32_16x16x32_bf16 v[16:19], v[164:167], v[188:191], v[16:19]
	v_mfma_f32_16x16x32_bf16 v[8:11], v[156:159], v[206:209], v[8:11]
	v_mfma_f32_16x16x32_bf16 v[0:3], v[164:167], v[206:209], v[0:3]
	v_mfma_f32_16x16x32_bf16 v[56:59], v[160:163], v[176:179], v[56:59]
	v_mfma_f32_16x16x32_bf16 v[48:51], v[168:171], v[176:179], v[48:51]
	v_mfma_f32_16x16x32_bf16 v[40:43], v[160:163], v[184:187], v[40:43]
	v_mfma_f32_16x16x32_bf16 v[32:35], v[168:171], v[184:187], v[32:35]
	v_mfma_f32_16x16x32_bf16 v[24:27], v[160:163], v[192:195], v[24:27]
	v_mfma_f32_16x16x32_bf16 v[16:19], v[168:171], v[192:195], v[16:19]
	v_mfma_f32_16x16x32_bf16 v[8:11], v[160:163], v[210:213], v[8:11]
	v_mfma_f32_16x16x32_bf16 v[0:3], v[168:171], v[210:213], v[0:3]
	s_setprio 0
	s_barrier
	s_add_i32 s47, 0, 0x18000
	s_add_i32 s48, 0, 0x1c000
	v_add_u32_e32 v152, s47, v138
	v_add_u32_e32 v168, s48, v138
	ds_read_b128 v[140:143], v152
	ds_read_b128 v[144:147], v152 offset:1024
	ds_read_b128 v[148:151], v152 offset:2048
	ds_read_b128 v[152:155], v152 offset:3072
	ds_read_b128 v[156:159], v168
	ds_read_b128 v[160:163], v168 offset:1024
	ds_read_b128 v[164:167], v168 offset:2048
	ds_read_b128 v[168:171], v168 offset:3072
	s_add_u32 s22, s22, 0x40000
	s_addc_u32 s23, s23, 0
	s_mov_b32 m0, s34
	ds_read_b128 v[172:175], v139 offset:32768
	ds_read_b128 v[176:179], v139 offset:33792
	ds_read_b128 v[180:183], v139 offset:34816
	ds_read_b128 v[184:187], v139 offset:35840
	ds_read_b128 v[188:191], v139 offset:36864
	ds_read_b128 v[192:195], v139 offset:37888
	ds_read_b128 v[206:209], v139 offset:38912
	ds_read_b128 v[210:213], v139 offset:39936
	global_load_lds_dwordx4 v128, s[22:23]
	s_mov_b32 m0, s35
	s_nop 0
	global_load_lds_dwordx4 v130, s[22:23]
	s_waitcnt vmcnt(8)
	s_waitcnt lgkmcnt(0)
	s_barrier
	s_setprio 1
	s_waitcnt lgkmcnt(0)
	v_mfma_f32_16x16x32_bf16 v[124:127], v[140:143], v[172:175], v[124:127]
	v_mfma_f32_16x16x32_bf16 v[116:119], v[148:151], v[172:175], v[116:119]
	v_mfma_f32_16x16x32_bf16 v[108:111], v[140:143], v[180:183], v[108:111]
	v_mfma_f32_16x16x32_bf16 v[100:103], v[148:151], v[180:183], v[100:103]
	v_mfma_f32_16x16x32_bf16 v[92:95], v[140:143], v[188:191], v[92:95]
	v_mfma_f32_16x16x32_bf16 v[84:87], v[148:151], v[188:191], v[84:87]
	v_mfma_f32_16x16x32_bf16 v[76:79], v[140:143], v[206:209], v[76:79]
	v_mfma_f32_16x16x32_bf16 v[68:71], v[148:151], v[206:209], v[68:71]
	v_mfma_f32_16x16x32_bf16 v[124:127], v[144:147], v[176:179], v[124:127]
	v_mfma_f32_16x16x32_bf16 v[116:119], v[152:155], v[176:179], v[116:119]
	v_mfma_f32_16x16x32_bf16 v[108:111], v[144:147], v[184:187], v[108:111]
	v_mfma_f32_16x16x32_bf16 v[100:103], v[152:155], v[184:187], v[100:103]
	v_mfma_f32_16x16x32_bf16 v[92:95], v[144:147], v[192:195], v[92:95]
	v_mfma_f32_16x16x32_bf16 v[84:87], v[152:155], v[192:195], v[84:87]
	v_mfma_f32_16x16x32_bf16 v[76:79], v[144:147], v[210:213], v[76:79]
	v_mfma_f32_16x16x32_bf16 v[68:71], v[152:155], v[210:213], v[68:71]
	s_setprio 0
	s_setprio 1
	v_mfma_f32_16x16x32_bf16 v[120:123], v[156:159], v[172:175], v[120:123]
	v_mfma_f32_16x16x32_bf16 v[112:115], v[164:167], v[172:175], v[112:115]
	v_mfma_f32_16x16x32_bf16 v[104:107], v[156:159], v[180:183], v[104:107]
	v_mfma_f32_16x16x32_bf16 v[96:99], v[164:167], v[180:183], v[96:99]
	v_mfma_f32_16x16x32_bf16 v[88:91], v[156:159], v[188:191], v[88:91]
	v_mfma_f32_16x16x32_bf16 v[80:83], v[164:167], v[188:191], v[80:83]
	v_mfma_f32_16x16x32_bf16 v[72:75], v[156:159], v[206:209], v[72:75]
	v_mfma_f32_16x16x32_bf16 v[64:67], v[164:167], v[206:209], v[64:67]
	v_mfma_f32_16x16x32_bf16 v[120:123], v[160:163], v[176:179], v[120:123]
	v_mfma_f32_16x16x32_bf16 v[112:115], v[168:171], v[176:179], v[112:115]
	v_mfma_f32_16x16x32_bf16 v[104:107], v[160:163], v[184:187], v[104:107]
	v_mfma_f32_16x16x32_bf16 v[96:99], v[168:171], v[184:187], v[96:99]
	v_mfma_f32_16x16x32_bf16 v[88:91], v[160:163], v[192:195], v[88:91]
	v_mfma_f32_16x16x32_bf16 v[80:83], v[168:171], v[192:195], v[80:83]
	v_mfma_f32_16x16x32_bf16 v[72:75], v[160:163], v[210:213], v[72:75]
	v_mfma_f32_16x16x32_bf16 v[64:67], v[168:171], v[210:213], v[64:67]
	s_setprio 0
	s_barrier
; #define PG8_STAGE(bufoff, gbase, voff) do { _Pragma("unroll") for (int _i = 0; _i < 2; ++_i) \
;         __builtin_amdgcn_global_load_lds((const unsigned*)((const char*)(gbase) + (voff)[_i]), (PG8_LAS unsigned*)(lds + (bufoff) + ldsw + _i * 8192), 16, 0, 0); } while (0)
; #define PG8_LDA(dst, b, h) do { _Pragma("unroll") for (int m = 0; m < 4; ++m) _Pragma("unroll") for (int k = 0; k < 2; ++k) dst[m][k] = *(const PG8_LAS bf16x8*)(lds + PG8_SA(b, h) + aoff + m * 2048 + k * 1024); } while (0)
; #define PG8_MMA(ai, bj, At, Bt) do { __builtin_amdgcn_s_setprio(1); _Pragma("unroll") for (int m = 0; m < 4; ++m) _Pragma("unroll") for (int n = 0; n < 2; ++n) _Pragma("unroll") for (int k = 0; k < 2; ++k) \
;         acc[ai][bj][m][n] = __builtin_amdgcn_mfma_f32_16x16x32_bf16(Bt[n][k], At[m][k], acc[ai][bj][m][n], 0, 0, 0); __builtin_amdgcn_s_setprio(0); } while (0)
; #define PG8_WAIT_V(n) asm volatile("s_waitcnt vmcnt(" #n ")" ::: "memory")
; #define PG8_WAIT_L(n) asm volatile("s_waitcnt lgkmcnt(" #n ")" ::: "memory")
; #define PG8_BAR __builtin_amdgcn_s_barrier()
; #define PG8_SCHED __builtin_amdgcn_sched_barrier(0)
; template <class Epi, class Sched, bool ALIGN_EPI = false, bool SP2 = false>
; __device__ __forceinline__ void gemm_phase(PG8_LAS unsigned char* lds, const Gemm g, const Sched& S, const Epi& E, int wave_s_) {
;     ...
;             PG8_LDA(At, 1, 1); PG8_STAGE(PG8_SB(1, 0), b3, voffB); PG8_STAGE(PG8_SB(1, 1), b3 + hstep, voffB); PG8_STAGE(PG8_SA(1, 0), a3, voffA);
;             PG8_WAIT_V(8); PG8_WAIT_L(0); PG8_BAR; PG8_MMA(1, 0, At, B0); PG8_MMA(1, 1, At, B1); PG8_BAR; PG8_SCHED;
	s_add_i32 s22, s47, s30
	v_lshl_add_u64 v[198:199], v[198:199], 0, s[76:77]
	s_mov_b32 m0, s22
	ds_read_b128 v[172:175], v139 offset:49152
	ds_read_b128 v[176:179], v139 offset:50176
	ds_read_b128 v[180:183], v139 offset:51200
	ds_read_b128 v[184:187], v139 offset:52224
	ds_read_b128 v[188:191], v139 offset:53248
	ds_read_b128 v[192:195], v139 offset:54272
	ds_read_b128 v[206:209], v139 offset:55296
	ds_read_b128 v[210:213], v139 offset:56320
	global_load_lds_dwordx4 v[198:199], off
	s_add_i32 m0, s22, 0x2000
	s_add_u32 s20, s20, 0x40080
	v_lshl_add_u64 v[198:199], v[204:205], 0, s[76:77]
	s_addc_u32 s21, s21, 0
	s_add_i32 s22, s48, s30
	global_load_lds_dwordx4 v[198:199], off
	s_mov_b32 m0, s22
	s_nop 0
	global_load_lds_dwordx4 v196, s[20:21]
	s_add_i32 m0, s22, 0x2000
	s_nop 0
	global_load_lds_dwordx4 v132, s[20:21]
	v_lshl_add_u64 v[198:199], v[214:215], 0, s[76:77]
	s_mov_b32 m0, s38
	s_nop 0
	global_load_lds_dwordx4 v[198:199], off
	v_lshl_add_u64 v[198:199], v[216:217], 0, s[76:77]
	s_mov_b32 m0, s39
	s_nop 0
	global_load_lds_dwordx4 v[198:199], off
	s_waitcnt vmcnt(8)
	s_waitcnt lgkmcnt(0)
	s_barrier
	s_setprio 1
	s_waitcnt lgkmcnt(0)
	v_mfma_f32_16x16x32_bf16 v[60:63], v[140:143], v[172:175], v[60:63]
	v_mfma_f32_16x16x32_bf16 v[52:55], v[148:151], v[172:175], v[52:55]
	v_mfma_f32_16x16x32_bf16 v[44:47], v[140:143], v[180:183], v[44:47]
	v_mfma_f32_16x16x32_bf16 v[36:39], v[148:151], v[180:183], v[36:39]
	v_mfma_f32_16x16x32_bf16 v[28:31], v[140:143], v[188:191], v[28:31]
	v_mfma_f32_16x16x32_bf16 v[20:23], v[148:151], v[188:191], v[20:23]
	v_mfma_f32_16x16x32_bf16 v[12:15], v[140:143], v[206:209], v[12:15]
	v_mfma_f32_16x16x32_bf16 v[4:7], v[148:151], v[206:209], v[4:7]
	v_mfma_f32_16x16x32_bf16 v[60:63], v[144:147], v[176:179], v[60:63]
	v_mfma_f32_16x16x32_bf16 v[52:55], v[152:155], v[176:179], v[52:55]
	v_mfma_f32_16x16x32_bf16 v[44:47], v[144:147], v[184:187], v[44:47]
	v_mfma_f32_16x16x32_bf16 v[36:39], v[152:155], v[184:187], v[36:39]
	v_mfma_f32_16x16x32_bf16 v[28:31], v[144:147], v[192:195], v[28:31]
	v_mfma_f32_16x16x32_bf16 v[20:23], v[152:155], v[192:195], v[20:23]
	v_mfma_f32_16x16x32_bf16 v[12:15], v[144:147], v[210:213], v[12:15]
	v_mfma_f32_16x16x32_bf16 v[4:7], v[152:155], v[210:213], v[4:7]
	s_setprio 0
	s_setprio 1
	v_mfma_f32_16x16x32_bf16 v[56:59], v[156:159], v[172:175], v[56:59]
	v_mfma_f32_16x16x32_bf16 v[48:51], v[164:167], v[172:175], v[48:51]
	v_mfma_f32_16x16x32_bf16 v[40:43], v[156:159], v[180:183], v[40:43]
	v_mfma_f32_16x16x32_bf16 v[32:35], v[164:167], v[180:183], v[32:35]
	v_mfma_f32_16x16x32_bf16 v[24:27], v[156:159], v[188:191], v[24:27]
	v_mfma_f32_16x16x32_bf16 v[16:19], v[164:167], v[188:191], v[16:19]
	v_mfma_f32_16x16x32_bf16 v[8:11], v[156:159], v[206:209], v[8:11]
	v_mfma_f32_16x16x32_bf16 v[0:3], v[164:167], v[206:209], v[0:3]
	v_mfma_f32_16x16x32_bf16 v[56:59], v[160:163], v[176:179], v[56:59]
	v_mfma_f32_16x16x32_bf16 v[48:51], v[168:171], v[176:179], v[48:51]
	v_mfma_f32_16x16x32_bf16 v[40:43], v[160:163], v[184:187], v[40:43]
	v_mfma_f32_16x16x32_bf16 v[32:35], v[168:171], v[184:187], v[32:35]
	v_mfma_f32_16x16x32_bf16 v[24:27], v[160:163], v[192:195], v[24:27]
	v_mfma_f32_16x16x32_bf16 v[16:19], v[168:171], v[192:195], v[16:19]
	v_mfma_f32_16x16x32_bf16 v[8:11], v[160:163], v[210:213], v[8:11]
	v_mfma_f32_16x16x32_bf16 v[0:3], v[168:171], v[210:213], v[0:3]
	s_setprio 0
	s_barrier
	s_add_i32 s46, s46, 2
	s_add_u32 s15, s15, 0x100
	s_addc_u32 s45, s45, 0
	s_add_u32 s18, s18, 0x100
	s_addc_u32 s19, s19, 0
	s_cmp_gt_u32 s46, 13
	s_cbranch_scc0 .LBB0_1820
	s_and_b64 vcc, exec, s[12:13]
	s_cbranch_vccz .LBB0_1823
	s_barrier

; #define PG8_STAGE(bufoff, gbase, voff) do { _Pragma("unroll") for (int _i = 0; _i < 2; ++_i) \
;         __builtin_amdgcn_global_load_lds((const unsigned*)((const char*)(gbase) + (voff)[_i]), (PG8_LAS unsigned*)(lds + (bufoff) + ldsw + _i * 8192), 16, 0, 0); } while (0)
; #define PG8_LDA(dst, b, h) do { _Pragma("unroll") for (int m = 0; m < 4; ++m) _Pragma("unroll") for (int k = 0; k < 2; ++k) dst[m][k] = *(const PG8_LAS bf16x8*)(lds + PG8_SA(b, h) + aoff + m * 2048 + k * 1024); } while (0)
; #define PG8_LDB(dst, b, h) do { _Pragma("unroll") for (int n = 0; n < 2; ++n) _Pragma("unroll") for (int k = 0; k < 2; ++k) dst[n][k] = *(const PG8_LAS bf16x8*)(lds + PG8_SB(b, h) + boff + n * 2048 + k * 1024); } while (0)
; #define PG8_MMA(ai, bj, At, Bt) do { __builtin_amdgcn_s_setprio(1); _Pragma("unroll") for (int m = 0; m < 4; ++m) _Pragma("unroll") for (int n = 0; n < 2; ++n) _Pragma("unroll") for (int k = 0; k < 2; ++k) \
;         acc[ai][bj][m][n] = __builtin_amdgcn_mfma_f32_16x16x32_bf16(Bt[n][k], At[m][k], acc[ai][bj][m][n], 0, 0, 0); __builtin_amdgcn_s_setprio(0); } while (0)
; #define PG8_WAIT_V(n) asm volatile("s_waitcnt vmcnt(" #n ")" ::: "memory")
; #define PG8_WAIT_L(n) asm volatile("s_waitcnt lgkmcnt(" #n ")" ::: "memory")
; #define PG8_BAR __builtin_amdgcn_s_barrier()
; #define PG8_SCHED __builtin_amdgcn_sched_barrier(0)
; template <class Epi, class Sched, bool ALIGN_EPI = false, bool SP2 = false>
; __device__ __forceinline__ void gemm_phase(PG8_LAS unsigned char* lds, const Gemm g, const Sched& S, const Epi& E, int wave_s_) {
;     ...
;             PG8_LDB(B0, 0, 0); PG8_LDB(B1, 0, 1); PG8_SCHED; PG8_LDA(At, 0, 0); PG8_STAGE(PG8_SA(1, 1), a1 + hstep, voffA);
;             PG8_WAIT_V(8); PG8_WAIT_L(0); PG8_BAR; PG8_MMA(0, 0, At, B0); PG8_MMA(0, 1, At, B1); PG8_BAR; PG8_SCHED;
;             PG8_LDA(At, 0, 1); PG8_STAGE(PG8_SB(0, 0), b2, voffB); PG8_STAGE(PG8_SB(0, 1), b2 + hstep, voffB); PG8_STAGE(PG8_SA(0, 0), a2, voffA);
.LBB0_1908:
	s_add_i32 s57, s26, 2
	s_add_u32 s10, s8, 0x100
	s_addc_u32 s11, s9, 0
	s_add_i32 s58, 0, 0x10000
	s_cmp_eq_u32 s54, s26
	s_cselect_b32 s29, s21, s11
	s_cselect_b32 s28, s20, s10
	s_cselect_b32 s27, s23, s56
	s_cselect_b32 s26, s22, s55
	s_add_i32 s59, 0, 0x14000
	v_add_u32_e32 v100, s58, v224
	v_add_u32_e32 v120, s59, v224
	ds_read_b128 v[76:79], v100
	ds_read_b128 v[84:87], v100 offset:1024
	ds_read_b128 v[92:95], v100 offset:2048
	ds_read_b128 v[100:103], v100 offset:3072
	ds_read_b128 v[104:107], v120
	ds_read_b128 v[108:111], v120 offset:1024
	ds_read_b128 v[112:115], v120 offset:2048
	ds_read_b128 v[120:123], v120 offset:3072
	v_lshl_add_u64 v[198:199], s[8:9], 0, v[206:207]
	s_add_i32 m0, s36, 0xc000
	ds_read_b128 v[160:163], v225
	ds_read_b128 v[164:167], v225 offset:1024
	ds_read_b128 v[168:171], v225 offset:2048
	ds_read_b128 v[172:175], v225 offset:3072
	ds_read_b128 v[176:179], v225 offset:4096
	ds_read_b128 v[180:183], v225 offset:5120
	ds_read_b128 v[184:187], v225 offset:6144
	ds_read_b128 v[188:191], v225 offset:7168
	global_load_lds_dwordx4 v[198:199], off
	v_lshl_add_u64 v[198:199], s[8:9], 0, v[194:195]
	s_add_i32 m0, s36, 0xe000
	s_nop 0
	global_load_lds_dwordx4 v[198:199], off
	s_waitcnt vmcnt(8)
	s_waitcnt lgkmcnt(0)
	s_barrier
	s_setprio 1
	s_waitcnt lgkmcnt(0)
	v_mfma_f32_16x16x32_bf16 v[156:159], v[76:79], v[160:163], v[156:159]
	v_mfma_f32_16x16x32_bf16 v[152:155], v[92:95], v[160:163], v[152:155]
	v_mfma_f32_16x16x32_bf16 v[144:147], v[76:79], v[168:171], v[144:147]
	v_mfma_f32_16x16x32_bf16 v[136:139], v[92:95], v[168:171], v[136:139]
	v_mfma_f32_16x16x32_bf16 v[124:127], v[76:79], v[176:179], v[124:127]
	v_mfma_f32_16x16x32_bf16 v[116:119], v[92:95], v[176:179], v[116:119]
	v_mfma_f32_16x16x32_bf16 v[88:91], v[76:79], v[184:187], v[88:91]
	v_mfma_f32_16x16x32_bf16 v[72:75], v[92:95], v[184:187], v[72:75]
	v_mfma_f32_16x16x32_bf16 v[156:159], v[84:87], v[164:167], v[156:159]
	v_mfma_f32_16x16x32_bf16 v[152:155], v[100:103], v[164:167], v[152:155]
	v_mfma_f32_16x16x32_bf16 v[144:147], v[84:87], v[172:175], v[144:147]
	v_mfma_f32_16x16x32_bf16 v[136:139], v[100:103], v[172:175], v[136:139]
	v_mfma_f32_16x16x32_bf16 v[124:127], v[84:87], v[180:183], v[124:127]
	v_mfma_f32_16x16x32_bf16 v[116:119], v[100:103], v[180:183], v[116:119]
	v_mfma_f32_16x16x32_bf16 v[88:91], v[84:87], v[188:191], v[88:91]
	v_mfma_f32_16x16x32_bf16 v[72:75], v[100:103], v[188:191], v[72:75]
	s_setprio 0
	s_setprio 1
	v_mfma_f32_16x16x32_bf16 v[148:151], v[104:107], v[160:163], v[148:151]
	v_mfma_f32_16x16x32_bf16 v[140:143], v[112:115], v[160:163], v[140:143]
	v_mfma_f32_16x16x32_bf16 v[132:135], v[104:107], v[168:171], v[132:135]
	v_mfma_f32_16x16x32_bf16 v[128:131], v[112:115], v[168:171], v[128:131]
	v_mfma_f32_16x16x32_bf16 v[96:99], v[104:107], v[176:179], v[96:99]
	v_mfma_f32_16x16x32_bf16 v[80:83], v[112:115], v[176:179], v[80:83]
	v_mfma_f32_16x16x32_bf16 v[68:71], v[104:107], v[184:187], v[68:71]
	v_mfma_f32_16x16x32_bf16 v[64:67], v[112:115], v[184:187], v[64:67]
	v_mfma_f32_16x16x32_bf16 v[148:151], v[108:111], v[164:167], v[148:151]
	v_mfma_f32_16x16x32_bf16 v[140:143], v[120:123], v[164:167], v[140:143]
	v_mfma_f32_16x16x32_bf16 v[132:135], v[108:111], v[172:175], v[132:135]
	v_mfma_f32_16x16x32_bf16 v[128:131], v[120:123], v[172:175], v[128:131]
	v_mfma_f32_16x16x32_bf16 v[96:99], v[108:111], v[180:183], v[96:99]
	v_mfma_f32_16x16x32_bf16 v[80:83], v[120:123], v[180:183], v[80:83]
	v_mfma_f32_16x16x32_bf16 v[68:71], v[108:111], v[188:191], v[68:71]
	v_mfma_f32_16x16x32_bf16 v[64:67], v[120:123], v[188:191], v[64:67]
	s_setprio 0
	s_barrier
	s_add_i32 s8, s58, s35
	v_lshl_add_u64 v[198:199], s[26:27], 0, v[196:197]
	s_mov_b32 m0, s8
	ds_read_b128 v[160:163], v225 offset:16384
	ds_read_b128 v[164:167], v225 offset:17408
	ds_read_b128 v[168:171], v225 offset:18432
	ds_read_b128 v[172:175], v225 offset:19456
	ds_read_b128 v[176:179], v225 offset:20480
	ds_read_b128 v[180:183], v225 offset:21504
	ds_read_b128 v[184:187], v225 offset:22528
	ds_read_b128 v[188:191], v225 offset:23552
	global_load_lds_dwordx4 v[198:199], off
	s_add_i32 m0, s8, 0x2000
	s_add_u32 s8, s26, 0xb0000
	v_lshl_add_u64 v[204:205], s[26:27], 0, v[192:193]
	s_addc_u32 s9, s27, 0
	s_add_i32 s58, s59, s35
	global_load_lds_dwordx4 v[204:205], off
	s_mov_b32 m0, s58
	v_lshl_add_u64 v[210:211], s[28:29], 0, v[192:193]
	global_load_lds_dwordx4 v196, s[8:9]
	s_add_i32 m0, s58, 0x2000
	s_nop 0
	global_load_lds_dwordx4 v192, s[8:9]
	v_lshl_add_u64 v[208:209], s[28:29], 0, v[196:197]
	s_mov_b32 m0, s36
	s_nop 0
	global_load_lds_dwordx4 v[208:209], off
	s_mov_b32 m0, s37
	s_nop 0
	global_load_lds_dwordx4 v[210:211], off
	s_waitcnt vmcnt(8)
	s_waitcnt lgkmcnt(0)
	s_barrier
; #define PG8_STAGE(bufoff, gbase, voff) do { _Pragma("unroll") for (int _i = 0; _i < 2; ++_i) \
;         __builtin_amdgcn_global_load_lds((const unsigned*)((const char*)(gbase) + (voff)[_i]), (PG8_LAS unsigned*)(lds + (bufoff) + ldsw + _i * 8192), 16, 0, 0); } while (0)
; #define PG8_LDA(dst, b, h) do { _Pragma("unroll") for (int m = 0; m < 4; ++m) _Pragma("unroll") for (int k = 0; k < 2; ++k) dst[m][k] = *(const PG8_LAS bf16x8*)(lds + PG8_SA(b, h) + aoff + m * 2048 + k * 1024); } while (0)
; #define PG8_LDB(dst, b, h) do { _Pragma("unroll") for (int n = 0; n < 2; ++n) _Pragma("unroll") for (int k = 0; k < 2; ++k) dst[n][k] = *(const PG8_LAS bf16x8*)(lds + PG8_SB(b, h) + boff + n * 2048 + k * 1024); } while (0)
; #define PG8_MMA(ai, bj, At, Bt) do { __builtin_amdgcn_s_setprio(1); _Pragma("unroll") for (int m = 0; m < 4; ++m) _Pragma("unroll") for (int n = 0; n < 2; ++n) _Pragma("unroll") for (int k = 0; k < 2; ++k) \
;         acc[ai][bj][m][n] = __builtin_amdgcn_mfma_f32_16x16x32_bf16(Bt[n][k], At[m][k], acc[ai][bj][m][n], 0, 0, 0); __builtin_amdgcn_s_setprio(0); } while (0)
; #define PG8_WAIT_V(n) asm volatile("s_waitcnt vmcnt(" #n ")" ::: "memory")
; #define PG8_WAIT_L(n) asm volatile("s_waitcnt lgkmcnt(" #n ")" ::: "memory")
; #define PG8_BAR __builtin_amdgcn_s_barrier()
; #define PG8_SCHED __builtin_amdgcn_sched_barrier(0)
; template <class Epi, class Sched, bool ALIGN_EPI = false, bool SP2 = false>
; __device__ __forceinline__ void gemm_phase(PG8_LAS unsigned char* lds, const Gemm g, const Sched& S, const Epi& E, int wave_s_) {
;     ...
;             PG8_WAIT_V(8); PG8_WAIT_L(0); PG8_BAR; PG8_MMA(1, 0, At, B0); PG8_MMA(1, 1, At, B1); PG8_BAR; PG8_SCHED;
;             PG8_LDB(B0, 1, 0); PG8_LDB(B1, 1, 1); PG8_SCHED; PG8_LDA(At, 1, 0); PG8_STAGE(PG8_SA(0, 1), a2 + hstep, voffA);
;             PG8_WAIT_V(8); PG8_WAIT_L(0); PG8_BAR; PG8_MMA(0, 0, At, B0); PG8_MMA(0, 1, At, B1); PG8_BAR; PG8_SCHED;
	s_setprio 1
	s_waitcnt lgkmcnt(0)
	v_mfma_f32_16x16x32_bf16 v[60:63], v[76:79], v[160:163], v[60:63]
	v_mfma_f32_16x16x32_bf16 v[56:59], v[92:95], v[160:163], v[56:59]
	v_mfma_f32_16x16x32_bf16 v[48:51], v[76:79], v[168:171], v[48:51]
	v_mfma_f32_16x16x32_bf16 v[40:43], v[92:95], v[168:171], v[40:43]
	v_mfma_f32_16x16x32_bf16 v[28:31], v[76:79], v[176:179], v[28:31]
	v_mfma_f32_16x16x32_bf16 v[24:27], v[92:95], v[176:179], v[24:27]
	v_mfma_f32_16x16x32_bf16 v[16:19], v[76:79], v[184:187], v[16:19]
	v_mfma_f32_16x16x32_bf16 v[8:11], v[92:95], v[184:187], v[8:11]
	v_mfma_f32_16x16x32_bf16 v[60:63], v[84:87], v[164:167], v[60:63]
	v_mfma_f32_16x16x32_bf16 v[56:59], v[100:103], v[164:167], v[56:59]
	v_mfma_f32_16x16x32_bf16 v[48:51], v[84:87], v[172:175], v[48:51]
	v_mfma_f32_16x16x32_bf16 v[40:43], v[100:103], v[172:175], v[40:43]
	v_mfma_f32_16x16x32_bf16 v[28:31], v[84:87], v[180:183], v[28:31]
	v_mfma_f32_16x16x32_bf16 v[24:27], v[100:103], v[180:183], v[24:27]
	v_mfma_f32_16x16x32_bf16 v[16:19], v[84:87], v[188:191], v[16:19]
	v_mfma_f32_16x16x32_bf16 v[8:11], v[100:103], v[188:191], v[8:11]
	s_setprio 0
	s_setprio 1
	v_mfma_f32_16x16x32_bf16 v[52:55], v[104:107], v[160:163], v[52:55]
	v_mfma_f32_16x16x32_bf16 v[44:47], v[112:115], v[160:163], v[44:47]
	v_mfma_f32_16x16x32_bf16 v[36:39], v[104:107], v[168:171], v[36:39]
	v_mfma_f32_16x16x32_bf16 v[32:35], v[112:115], v[168:171], v[32:35]
	v_mfma_f32_16x16x32_bf16 v[20:23], v[104:107], v[176:179], v[20:23]
	v_mfma_f32_16x16x32_bf16 v[12:15], v[112:115], v[176:179], v[12:15]
	v_mfma_f32_16x16x32_bf16 v[4:7], v[104:107], v[184:187], v[4:7]
	v_mfma_f32_16x16x32_bf16 v[0:3], v[112:115], v[184:187], v[0:3]
	v_mfma_f32_16x16x32_bf16 v[52:55], v[108:111], v[164:167], v[52:55]
	v_mfma_f32_16x16x32_bf16 v[44:47], v[120:123], v[164:167], v[44:47]
	v_mfma_f32_16x16x32_bf16 v[36:39], v[108:111], v[172:175], v[36:39]
	v_mfma_f32_16x16x32_bf16 v[32:35], v[120:123], v[172:175], v[32:35]
	v_mfma_f32_16x16x32_bf16 v[20:23], v[108:111], v[180:183], v[20:23]
	v_mfma_f32_16x16x32_bf16 v[12:15], v[120:123], v[180:183], v[12:15]
	v_mfma_f32_16x16x32_bf16 v[4:7], v[108:111], v[188:191], v[4:7]
	v_mfma_f32_16x16x32_bf16 v[0:3], v[120:123], v[188:191], v[0:3]
	s_setprio 0
	s_barrier
	s_add_i32 s58, 0, 0x18000
	s_add_i32 s59, 0, 0x1c000
	v_add_u32_e32 v100, s58, v224
	v_add_u32_e32 v120, s59, v224
	ds_read_b128 v[76:79], v100
	ds_read_b128 v[84:87], v100 offset:1024
	ds_read_b128 v[92:95], v100 offset:2048
	ds_read_b128 v[100:103], v100 offset:3072
	ds_read_b128 v[104:107], v120
	ds_read_b128 v[108:111], v120 offset:1024
	ds_read_b128 v[112:115], v120 offset:2048
	ds_read_b128 v[120:123], v120 offset:3072
	s_add_u32 s8, s28, 0xb0000
	s_addc_u32 s9, s29, 0
	s_mov_b32 m0, s38
	ds_read_b128 v[160:163], v225 offset:32768
	ds_read_b128 v[164:167], v225 offset:33792
	ds_read_b128 v[168:171], v225 offset:34816
	ds_read_b128 v[172:175], v225 offset:35840
	ds_read_b128 v[176:179], v225 offset:36864
	ds_read_b128 v[180:183], v225 offset:37888
	ds_read_b128 v[184:187], v225 offset:38912
	ds_read_b128 v[188:191], v225 offset:39936
	global_load_lds_dwordx4 v196, s[8:9]
	s_mov_b32 m0, s39
	s_nop 0
	global_load_lds_dwordx4 v192, s[8:9]
	s_waitcnt vmcnt(8)
	s_waitcnt lgkmcnt(0)
	s_barrier
	s_setprio 1
	s_waitcnt lgkmcnt(0)
	v_mfma_f32_16x16x32_bf16 v[156:159], v[76:79], v[160:163], v[156:159]
	v_mfma_f32_16x16x32_bf16 v[152:155], v[92:95], v[160:163], v[152:155]
	v_mfma_f32_16x16x32_bf16 v[144:147], v[76:79], v[168:171], v[144:147]
	v_mfma_f32_16x16x32_bf16 v[136:139], v[92:95], v[168:171], v[136:139]
	v_mfma_f32_16x16x32_bf16 v[124:127], v[76:79], v[176:179], v[124:127]
	v_mfma_f32_16x16x32_bf16 v[116:119], v[92:95], v[176:179], v[116:119]
	v_mfma_f32_16x16x32_bf16 v[88:91], v[76:79], v[184:187], v[88:91]
	v_mfma_f32_16x16x32_bf16 v[72:75], v[92:95], v[184:187], v[72:75]
	v_mfma_f32_16x16x32_bf16 v[156:159], v[84:87], v[164:167], v[156:159]
	v_mfma_f32_16x16x32_bf16 v[152:155], v[100:103], v[164:167], v[152:155]
	v_mfma_f32_16x16x32_bf16 v[144:147], v[84:87], v[172:175], v[144:147]
	v_mfma_f32_16x16x32_bf16 v[136:139], v[100:103], v[172:175], v[136:139]
	v_mfma_f32_16x16x32_bf16 v[124:127], v[84:87], v[180:183], v[124:127]
	v_mfma_f32_16x16x32_bf16 v[116:119], v[100:103], v[180:183], v[116:119]
	v_mfma_f32_16x16x32_bf16 v[88:91], v[84:87], v[188:191], v[88:91]
	v_mfma_f32_16x16x32_bf16 v[72:75], v[100:103], v[188:191], v[72:75]
	s_setprio 0
	s_setprio 1
	v_mfma_f32_16x16x32_bf16 v[148:151], v[104:107], v[160:163], v[148:151]
	v_mfma_f32_16x16x32_bf16 v[140:143], v[112:115], v[160:163], v[140:143]
	v_mfma_f32_16x16x32_bf16 v[132:135], v[104:107], v[168:171], v[132:135]
	v_mfma_f32_16x16x32_bf16 v[128:131], v[112:115], v[168:171], v[128:131]
	v_mfma_f32_16x16x32_bf16 v[96:99], v[104:107], v[176:179], v[96:99]
	v_mfma_f32_16x16x32_bf16 v[80:83], v[112:115], v[176:179], v[80:83]
	v_mfma_f32_16x16x32_bf16 v[68:71], v[104:107], v[184:187], v[68:71]
	v_mfma_f32_16x16x32_bf16 v[64:67], v[112:115], v[184:187], v[64:67]
	v_mfma_f32_16x16x32_bf16 v[148:151], v[108:111], v[164:167], v[148:151]
	v_mfma_f32_16x16x32_bf16 v[140:143], v[120:123], v[164:167], v[140:143]
	v_mfma_f32_16x16x32_bf16 v[132:135], v[108:111], v[172:175], v[132:135]
	v_mfma_f32_16x16x32_bf16 v[128:131], v[120:123], v[172:175], v[128:131]
	v_mfma_f32_16x16x32_bf16 v[96:99], v[108:111], v[180:183], v[96:99]
	v_mfma_f32_16x16x32_bf16 v[80:83], v[120:123], v[180:183], v[80:83]
	v_mfma_f32_16x16x32_bf16 v[68:71], v[108:111], v[188:191], v[68:71]
	v_mfma_f32_16x16x32_bf16 v[64:67], v[120:123], v[188:191], v[64:67]
	s_setprio 0
	s_barrier
; #define PG8_STAGE(bufoff, gbase, voff) do { _Pragma("unroll") for (int _i = 0; _i < 2; ++_i) \
;         __builtin_amdgcn_global_load_lds((const unsigned*)((const char*)(gbase) + (voff)[_i]), (PG8_LAS unsigned*)(lds + (bufoff) + ldsw + _i * 8192), 16, 0, 0); } while (0)
; #define PG8_LDA(dst, b, h) do { _Pragma("unroll") for (int m = 0; m < 4; ++m) _Pragma("unroll") for (int k = 0; k < 2; ++k) dst[m][k] = *(const PG8_LAS bf16x8*)(lds + PG8_SA(b, h) + aoff + m * 2048 + k * 1024); } while (0)
; #define PG8_MMA(ai, bj, At, Bt) do { __builtin_amdgcn_s_setprio(1); _Pragma("unroll") for (int m = 0; m < 4; ++m) _Pragma("unroll") for (int n = 0; n < 2; ++n) _Pragma("unroll") for (int k = 0; k < 2; ++k) \
;         acc[ai][bj][m][n] = __builtin_amdgcn_mfma_f32_16x16x32_bf16(Bt[n][k], At[m][k], acc[ai][bj][m][n], 0, 0, 0); __builtin_amdgcn_s_setprio(0); } while (0)
; #define PG8_WAIT_V(n) asm volatile("s_waitcnt vmcnt(" #n ")" ::: "memory")
; #define PG8_WAIT_L(n) asm volatile("s_waitcnt lgkmcnt(" #n ")" ::: "memory")
; #define PG8_BAR __builtin_amdgcn_s_barrier()
; #define PG8_SCHED __builtin_amdgcn_sched_barrier(0)
; template <class Epi, class Sched, bool ALIGN_EPI = false, bool SP2 = false>
; __device__ __forceinline__ void gemm_phase(PG8_LAS unsigned char* lds, const Gemm g, const Sched& S, const Epi& E, int wave_s_) {
;     ...
;             PG8_LDA(At, 1, 1); PG8_STAGE(PG8_SB(1, 0), b3, voffB); PG8_STAGE(PG8_SB(1, 1), b3 + hstep, voffB); PG8_STAGE(PG8_SA(1, 0), a3, voffA);
;             PG8_WAIT_V(8); PG8_WAIT_L(0); PG8_BAR; PG8_MMA(1, 0, At, B0); PG8_MMA(1, 1, At, B1); PG8_BAR; PG8_SCHED;
	s_add_i32 s8, s58, s35
	v_lshl_add_u64 v[198:199], v[198:199], 0, s[76:77]
	s_mov_b32 m0, s8
	ds_read_b128 v[160:163], v225 offset:49152
	ds_read_b128 v[164:167], v225 offset:50176
	ds_read_b128 v[168:171], v225 offset:51200
	ds_read_b128 v[172:175], v225 offset:52224
	ds_read_b128 v[176:179], v225 offset:53248
	ds_read_b128 v[180:183], v225 offset:54272
	ds_read_b128 v[184:187], v225 offset:55296
	ds_read_b128 v[188:191], v225 offset:56320
	global_load_lds_dwordx4 v[198:199], off
	s_add_i32 m0, s8, 0x2000
	s_add_u32 s8, s26, 0xb0080
	v_lshl_add_u64 v[198:199], v[204:205], 0, s[76:77]
	s_addc_u32 s9, s27, 0
	s_add_i32 s26, s59, s35
	global_load_lds_dwordx4 v[198:199], off
	s_mov_b32 m0, s26
	s_nop 0
	global_load_lds_dwordx4 v196, s[8:9]
	s_add_i32 m0, s26, 0x2000
	s_nop 0
	global_load_lds_dwordx4 v192, s[8:9]
	v_lshl_add_u64 v[198:199], v[208:209], 0, s[76:77]
	s_mov_b32 m0, s42
	s_nop 0
	global_load_lds_dwordx4 v[198:199], off
	v_lshl_add_u64 v[198:199], v[210:211], 0, s[76:77]
	s_mov_b32 m0, s43
	s_nop 0
	global_load_lds_dwordx4 v[198:199], off
	s_waitcnt vmcnt(8)
	s_waitcnt lgkmcnt(0)
	s_barrier
	s_setprio 1
	s_waitcnt lgkmcnt(0)
	v_mfma_f32_16x16x32_bf16 v[60:63], v[76:79], v[160:163], v[60:63]
	v_mfma_f32_16x16x32_bf16 v[56:59], v[92:95], v[160:163], v[56:59]
	v_mfma_f32_16x16x32_bf16 v[48:51], v[76:79], v[168:171], v[48:51]
	v_mfma_f32_16x16x32_bf16 v[40:43], v[92:95], v[168:171], v[40:43]
	v_mfma_f32_16x16x32_bf16 v[28:31], v[76:79], v[176:179], v[28:31]
	v_mfma_f32_16x16x32_bf16 v[24:27], v[92:95], v[176:179], v[24:27]
	v_mfma_f32_16x16x32_bf16 v[16:19], v[76:79], v[184:187], v[16:19]
	v_mfma_f32_16x16x32_bf16 v[8:11], v[92:95], v[184:187], v[8:11]
	v_mfma_f32_16x16x32_bf16 v[60:63], v[84:87], v[164:167], v[60:63]
	v_mfma_f32_16x16x32_bf16 v[56:59], v[100:103], v[164:167], v[56:59]
	v_mfma_f32_16x16x32_bf16 v[48:51], v[84:87], v[172:175], v[48:51]
	v_mfma_f32_16x16x32_bf16 v[40:43], v[100:103], v[172:175], v[40:43]
	v_mfma_f32_16x16x32_bf16 v[28:31], v[84:87], v[180:183], v[28:31]
	v_mfma_f32_16x16x32_bf16 v[24:27], v[100:103], v[180:183], v[24:27]
	v_mfma_f32_16x16x32_bf16 v[16:19], v[84:87], v[188:191], v[16:19]
	v_mfma_f32_16x16x32_bf16 v[8:11], v[100:103], v[188:191], v[8:11]
	s_setprio 0
	s_setprio 1
	v_mfma_f32_16x16x32_bf16 v[52:55], v[104:107], v[160:163], v[52:55]
	v_mfma_f32_16x16x32_bf16 v[44:47], v[112:115], v[160:163], v[44:47]
	v_mfma_f32_16x16x32_bf16 v[36:39], v[104:107], v[168:171], v[36:39]
	v_mfma_f32_16x16x32_bf16 v[32:35], v[112:115], v[168:171], v[32:35]
	v_mfma_f32_16x16x32_bf16 v[20:23], v[104:107], v[176:179], v[20:23]
	v_mfma_f32_16x16x32_bf16 v[12:15], v[112:115], v[176:179], v[12:15]
	v_mfma_f32_16x16x32_bf16 v[4:7], v[104:107], v[184:187], v[4:7]
	v_mfma_f32_16x16x32_bf16 v[0:3], v[112:115], v[184:187], v[0:3]
	v_mfma_f32_16x16x32_bf16 v[52:55], v[108:111], v[164:167], v[52:55]
	v_mfma_f32_16x16x32_bf16 v[44:47], v[120:123], v[164:167], v[44:47]
	v_mfma_f32_16x16x32_bf16 v[36:39], v[108:111], v[172:175], v[36:39]
	v_mfma_f32_16x16x32_bf16 v[32:35], v[120:123], v[172:175], v[32:35]
	v_mfma_f32_16x16x32_bf16 v[20:23], v[108:111], v[180:183], v[20:23]
	v_mfma_f32_16x16x32_bf16 v[12:15], v[120:123], v[180:183], v[12:15]
	v_mfma_f32_16x16x32_bf16 v[4:7], v[108:111], v[188:191], v[4:7]
	v_mfma_f32_16x16x32_bf16 v[0:3], v[120:123], v[188:191], v[0:3]
	s_setprio 0
	s_barrier
	s_add_u32 s55, s55, 0x100
	s_addc_u32 s56, s56, 0
	s_cmp_ge_u32 s57, s53
	s_mov_b64 s[8:9], s[10:11]
	s_mov_b32 s26, s57
	s_cbranch_scc0 .LBB0_1908
	s_and_b64 vcc, exec, s[18:19]
	s_cbranch_vccz .LBB0_1911
	s_barrier
